# v-table sweep ring deepened to 5 batches in flight (fifth buffer in the registers the u sweep uses for partial sums)
# baseline (speedup 1.0000x reference)
; #define IT_ADVANCE() do { it_j += 4; while (it_j >= it_end) { if (it_done) break; ++it_tk; if (it_tk == 4) { it_tk = 0; ++it_p; if (it_p == 16) { it_done = true; it_p = 15; it_j = 0; it_end = 1; break; } } \
;             it_j = __builtin_amdgcn_readfirstlane(OFFS[(tb + it_tk) * 17 + it_p]); it_end = __builtin_amdgcn_readfirstlane(OFFS[(tb + it_tk) * 17 + it_p + 1]); } } while (0)
; __device__ __forceinline__ void peer_tile(const Args& A, LAS unsigned char* lds, int tile) {
;     ...
; #pragma unroll
;             for (int q = 0; q < 8; ++q) oacc[tk][q] = (f32x2){0.f, 0.f}; }
;         int it_p = 0, it_tk = -1, it_j = 0, it_end = 0; bool it_done = false;
;     ...
;         u32x4 uA[4], vA[4], uB[4], vB[4]; float cgA = 0.f, suA = 0.f, svA = 0.f, cgB = 0.f, suB = 0.f, svB = 0.f;
; #pragma unroll
;         for (int k = 0; k < 4; ++k) { uA[k] = (u32x4){0u, 0u, 0u, 0u}; vA[k] = uA[k]; uB[k] = uA[k]; vB[k] = uA[k]; }
;         IT_ADVANCE();
;         LOAD_SET(uA, vA, cgA, suA, svA);
.LU_done:
	s_waitcnt vmcnt(0) lgkmcnt(0)
	v_mov_b64_e32 v[0:1], 0
	v_mov_b64_e32 v[2:3], 0
	v_mov_b64_e32 v[4:5], 0
	v_mov_b64_e32 v[6:7], 0
	v_mov_b64_e32 v[8:9], 0
	v_mov_b64_e32 v[10:11], 0
	v_mov_b64_e32 v[12:13], 0
	v_mov_b64_e32 v[14:15], 0
	v_mov_b64_e32 v[16:17], 0
	v_mov_b64_e32 v[18:19], 0
	v_mov_b64_e32 v[20:21], 0
	v_mov_b64_e32 v[22:23], 0
	v_mov_b64_e32 v[24:25], 0
	v_mov_b64_e32 v[26:27], 0
	v_mov_b64_e32 v[28:29], 0
	v_mov_b64_e32 v[30:31], 0
	v_mov_b64_e32 v[32:33], 0
	v_mov_b64_e32 v[34:35], 0
	v_mov_b64_e32 v[36:37], 0
	v_mov_b64_e32 v[38:39], 0
	v_mov_b64_e32 v[40:41], 0
	v_mov_b64_e32 v[42:43], 0
	v_mov_b64_e32 v[44:45], 0
	v_mov_b64_e32 v[46:47], 0
	v_mov_b64_e32 v[48:49], 0
	v_mov_b64_e32 v[50:51], 0
	v_mov_b64_e32 v[52:53], 0
	v_mov_b64_e32 v[54:55], 0
	v_mov_b64_e32 v[56:57], 0
	v_mov_b64_e32 v[58:59], 0
	v_mov_b64_e32 v[60:61], 0
	v_mov_b64_e32 v[62:63], 0
	v_mov_b64_e32 v[64:65], 0
	v_mov_b64_e32 v[66:67], 0
	v_mov_b64_e32 v[68:69], 0
	v_mov_b64_e32 v[70:71], 0
	v_mov_b64_e32 v[72:73], 0
	v_mov_b64_e32 v[74:75], 0
	v_mov_b64_e32 v[76:77], 0
	v_mov_b64_e32 v[78:79], 0
	v_mov_b64_e32 v[80:81], 0
	v_mov_b64_e32 v[82:83], 0
	v_mov_b64_e32 v[84:85], 0
	v_mov_b64_e32 v[86:87], 0
	v_mov_b64_e32 v[88:89], 0
	v_mov_b64_e32 v[90:91], 0
	v_mov_b64_e32 v[92:93], 0
	v_mov_b64_e32 v[94:95], 0
	v_mov_b64_e32 v[96:97], 0
	v_mov_b64_e32 v[98:99], 0
	v_mov_b64_e32 v[100:101], 0
	v_mov_b64_e32 v[102:103], 0
	v_mov_b64_e32 v[104:105], 0
	v_mov_b64_e32 v[106:107], 0
	v_mov_b64_e32 v[108:109], 0
	v_mov_b64_e32 v[110:111], 0
	v_mov_b64_e32 v[112:113], 0
	v_mov_b64_e32 v[114:115], 0
	v_mov_b64_e32 v[116:117], 0
	v_mov_b64_e32 v[118:119], 0
	v_mov_b64_e32 v[120:121], 0
	v_mov_b64_e32 v[122:123], 0
	v_mov_b64_e32 v[124:125], 0
	v_mov_b64_e32 v[126:127], 0
	s_add_i32 s20, s91, 3
	s_and_b32 s20, s20, -4
	s_waitcnt vmcnt(0) lgkmcnt(0)
	v_mov_b32_e32 v213, s22
	v_mov_b32_e32 v233, v240
	v_mov_b32_e32 v235, v240
	v_mov_b32_e32 v237, v240
	v_mov_b32_e32 v239, v240
	ds_read_b32 v232, v213 offset:0
	ds_read_b32 v234, v213 offset:4
	ds_read_b32 v236, v213 offset:8
	ds_read_b32 v238, v213 offset:12
	s_waitcnt lgkmcnt(0)
	buffer_load_dwordx4 v[128:131], v[232:233], s[60:63], 0 idxen offen
	buffer_load_dwordx4 v[132:135], v[234:235], s[60:63], 0 idxen offen
	buffer_load_dwordx4 v[136:139], v[236:237], s[60:63], 0 idxen offen
	buffer_load_dwordx4 v[140:143], v[238:239], s[60:63], 0 idxen offen
	ds_read_b32 v232, v213 offset:16
	ds_read_b32 v234, v213 offset:20
	ds_read_b32 v236, v213 offset:24
	ds_read_b32 v238, v213 offset:28
	s_waitcnt lgkmcnt(0)
	buffer_load_dwordx4 v[144:147], v[232:233], s[60:63], 0 idxen offen
	buffer_load_dwordx4 v[148:151], v[234:235], s[60:63], 0 idxen offen
	buffer_load_dwordx4 v[152:155], v[236:237], s[60:63], 0 idxen offen
	buffer_load_dwordx4 v[156:159], v[238:239], s[60:63], 0 idxen offen
	ds_read_b32 v232, v213 offset:32
	ds_read_b32 v234, v213 offset:36
	ds_read_b32 v236, v213 offset:40
	ds_read_b32 v238, v213 offset:44
	s_waitcnt lgkmcnt(0)
	buffer_load_dwordx4 v[160:163], v[232:233], s[60:63], 0 idxen offen
	buffer_load_dwordx4 v[164:167], v[234:235], s[60:63], 0 idxen offen
	buffer_load_dwordx4 v[168:171], v[236:237], s[60:63], 0 idxen offen
	buffer_load_dwordx4 v[172:175], v[238:239], s[60:63], 0 idxen offen
	ds_read_b32 v232, v213 offset:48
	ds_read_b32 v234, v213 offset:52
	ds_read_b32 v236, v213 offset:56
	ds_read_b32 v238, v213 offset:60
	s_waitcnt lgkmcnt(0)
	buffer_load_dwordx4 v[176:179], v[232:233], s[60:63], 0 idxen offen
	buffer_load_dwordx4 v[180:183], v[234:235], s[60:63], 0 idxen offen
	buffer_load_dwordx4 v[184:187], v[236:237], s[60:63], 0 idxen offen
	buffer_load_dwordx4 v[188:191], v[238:239], s[60:63], 0 idxen offen
	ds_read_b128 v[248:251], v213 offset:4992
	ds_read_b32 v232, v213 offset:64
	ds_read_b32 v234, v213 offset:68
	ds_read_b32 v236, v213 offset:72
	ds_read_b32 v238, v213 offset:76
	s_mov_b32 s21, 0
	s_mov_b32 s89, -1
	s_mov_b32 s86, 0
	s_mov_b32 s20, 260
	s_branch .LV_sw0
.LV_t0_s0:
	s_cmp_ge_u32 s21, s20
	s_cbranch_scc1 .LV_done
	s_waitcnt lgkmcnt(0)
	buffer_load_dwordx4 v[192:195], v[232:233], s[60:63], 0 idxen offen
	buffer_load_dwordx4 v[196:199], v[234:235], s[60:63], 0 idxen offen
	buffer_load_dwordx4 v[200:203], v[236:237], s[60:63], 0 idxen offen
	buffer_load_dwordx4 v[204:207], v[238:239], s[60:63], 0 idxen offen
	ds_read_b32 v232, v213 offset:80
	ds_read_b32 v234, v213 offset:84
	ds_read_b32 v236, v213 offset:88
	ds_read_b32 v238, v213 offset:92
	ds_read_b128 v[252:255], v213 offset:5008
	s_waitcnt vmcnt(16)
	v_cvt_pk_f32_fp8_e32 v[224:225], v128
	v_cvt_pk_f32_fp8_sdwa v[226:227], v128 src0_sel:WORD_1
	v_cvt_pk_f32_fp8_e32 v[228:229], v129
	v_cvt_pk_f32_fp8_sdwa v[230:231], v129 src0_sel:WORD_1
	v_pk_fma_f32 v[0:1], v[224:225], v[248:249], v[0:1] op_sel_hi:[1,0,1]
	v_pk_fma_f32 v[2:3], v[226:227], v[248:249], v[2:3] op_sel_hi:[1,0,1]
	v_pk_fma_f32 v[4:5], v[228:229], v[248:249], v[4:5] op_sel_hi:[1,0,1]
	v_pk_fma_f32 v[6:7], v[230:231], v[248:249], v[6:7] op_sel_hi:[1,0,1]
	v_cvt_pk_f32_fp8_e32 v[224:225], v130
	v_cvt_pk_f32_fp8_sdwa v[226:227], v130 src0_sel:WORD_1
	v_cvt_pk_f32_fp8_e32 v[228:229], v131
	v_cvt_pk_f32_fp8_sdwa v[230:231], v131 src0_sel:WORD_1
	v_pk_fma_f32 v[8:9], v[224:225], v[248:249], v[8:9] op_sel_hi:[1,0,1]
	v_pk_fma_f32 v[10:11], v[226:227], v[248:249], v[10:11] op_sel_hi:[1,0,1]
	v_pk_fma_f32 v[12:13], v[228:229], v[248:249], v[12:13] op_sel_hi:[1,0,1]
	v_pk_fma_f32 v[14:15], v[230:231], v[248:249], v[14:15] op_sel_hi:[1,0,1]
	v_cvt_pk_f32_fp8_e32 v[224:225], v132
	v_cvt_pk_f32_fp8_sdwa v[226:227], v132 src0_sel:WORD_1
	v_cvt_pk_f32_fp8_e32 v[228:229], v133
	v_cvt_pk_f32_fp8_sdwa v[230:231], v133 src0_sel:WORD_1
	v_pk_fma_f32 v[0:1], v[224:225], v[248:249], v[0:1] op_sel:[0,1,0] op_sel_hi:[1,1,1]
	v_pk_fma_f32 v[2:3], v[226:227], v[248:249], v[2:3] op_sel:[0,1,0] op_sel_hi:[1,1,1]
	v_pk_fma_f32 v[4:5], v[228:229], v[248:249], v[4:5] op_sel:[0,1,0] op_sel_hi:[1,1,1]
	v_pk_fma_f32 v[6:7], v[230:231], v[248:249], v[6:7] op_sel:[0,1,0] op_sel_hi:[1,1,1]
	v_cvt_pk_f32_fp8_e32 v[224:225], v134
	v_cvt_pk_f32_fp8_sdwa v[226:227], v134 src0_sel:WORD_1
	v_cvt_pk_f32_fp8_e32 v[228:229], v135
	v_cvt_pk_f32_fp8_sdwa v[230:231], v135 src0_sel:WORD_1
	v_pk_fma_f32 v[8:9], v[224:225], v[248:249], v[8:9] op_sel:[0,1,0] op_sel_hi:[1,1,1]
	v_pk_fma_f32 v[10:11], v[226:227], v[248:249], v[10:11] op_sel:[0,1,0] op_sel_hi:[1,1,1]
	v_pk_fma_f32 v[12:13], v[228:229], v[248:249], v[12:13] op_sel:[0,1,0] op_sel_hi:[1,1,1]
	v_pk_fma_f32 v[14:15], v[230:231], v[248:249], v[14:15] op_sel:[0,1,0] op_sel_hi:[1,1,1]
	v_cvt_pk_f32_fp8_e32 v[224:225], v136
	v_cvt_pk_f32_fp8_sdwa v[226:227], v136 src0_sel:WORD_1
	v_cvt_pk_f32_fp8_e32 v[228:229], v137
	v_cvt_pk_f32_fp8_sdwa v[230:231], v137 src0_sel:WORD_1
	v_pk_fma_f32 v[0:1], v[224:225], v[250:251], v[0:1] op_sel_hi:[1,0,1]
	v_pk_fma_f32 v[2:3], v[226:227], v[250:251], v[2:3] op_sel_hi:[1,0,1]
	v_pk_fma_f32 v[4:5], v[228:229], v[250:251], v[4:5] op_sel_hi:[1,0,1]
	v_pk_fma_f32 v[6:7], v[230:231], v[250:251], v[6:7] op_sel_hi:[1,0,1]
	v_cvt_pk_f32_fp8_e32 v[224:225], v138
	v_cvt_pk_f32_fp8_sdwa v[226:227], v138 src0_sel:WORD_1
	v_cvt_pk_f32_fp8_e32 v[228:229], v139
	v_cvt_pk_f32_fp8_sdwa v[230:231], v139 src0_sel:WORD_1
	v_pk_fma_f32 v[8:9], v[224:225], v[250:251], v[8:9] op_sel_hi:[1,0,1]
	v_pk_fma_f32 v[10:11], v[226:227], v[250:251], v[10:11] op_sel_hi:[1,0,1]
	v_pk_fma_f32 v[12:13], v[228:229], v[250:251], v[12:13] op_sel_hi:[1,0,1]
	v_pk_fma_f32 v[14:15], v[230:231], v[250:251], v[14:15] op_sel_hi:[1,0,1]
	v_cvt_pk_f32_fp8_e32 v[224:225], v140
	v_cvt_pk_f32_fp8_sdwa v[226:227], v140 src0_sel:WORD_1
	v_cvt_pk_f32_fp8_e32 v[228:229], v141
	v_cvt_pk_f32_fp8_sdwa v[230:231], v141 src0_sel:WORD_1
	v_pk_fma_f32 v[0:1], v[224:225], v[250:251], v[0:1] op_sel:[0,1,0] op_sel_hi:[1,1,1]
	v_pk_fma_f32 v[2:3], v[226:227], v[250:251], v[2:3] op_sel:[0,1,0] op_sel_hi:[1,1,1]
	v_pk_fma_f32 v[4:5], v[228:229], v[250:251], v[4:5] op_sel:[0,1,0] op_sel_hi:[1,1,1]
	v_pk_fma_f32 v[6:7], v[230:231], v[250:251], v[6:7] op_sel:[0,1,0] op_sel_hi:[1,1,1]
	v_cvt_pk_f32_fp8_e32 v[224:225], v142
	v_cvt_pk_f32_fp8_sdwa v[226:227], v142 src0_sel:WORD_1
	v_cvt_pk_f32_fp8_e32 v[228:229], v143
	v_cvt_pk_f32_fp8_sdwa v[230:231], v143 src0_sel:WORD_1
	v_pk_fma_f32 v[8:9], v[224:225], v[250:251], v[8:9] op_sel:[0,1,0] op_sel_hi:[1,1,1]
	v_pk_fma_f32 v[10:11], v[226:227], v[250:251], v[10:11] op_sel:[0,1,0] op_sel_hi:[1,1,1]
	v_pk_fma_f32 v[12:13], v[228:229], v[250:251], v[12:13] op_sel:[0,1,0] op_sel_hi:[1,1,1]
	v_pk_fma_f32 v[14:15], v[230:231], v[250:251], v[14:15] op_sel:[0,1,0] op_sel_hi:[1,1,1]
	s_sub_i32 s90, s90, 1
	s_cmp_eq_u32 s90, 0
	s_cbranch_scc1 .LV_sw1
.LV_t0_s1:
	s_waitcnt lgkmcnt(0)
	buffer_load_dwordx4 v[128:131], v[232:233], s[60:63], 0 idxen offen
	buffer_load_dwordx4 v[132:135], v[234:235], s[60:63], 0 idxen offen
	buffer_load_dwordx4 v[136:139], v[236:237], s[60:63], 0 idxen offen
	buffer_load_dwordx4 v[140:143], v[238:239], s[60:63], 0 idxen offen
	ds_read_b32 v232, v213 offset:96
	ds_read_b32 v234, v213 offset:100
	ds_read_b32 v236, v213 offset:104
	ds_read_b32 v238, v213 offset:108
	ds_read_b128 v[248:251], v213 offset:5024
	s_waitcnt vmcnt(16)
	v_cvt_pk_f32_fp8_e32 v[224:225], v144
	v_cvt_pk_f32_fp8_sdwa v[226:227], v144 src0_sel:WORD_1
	v_cvt_pk_f32_fp8_e32 v[228:229], v145
	v_cvt_pk_f32_fp8_sdwa v[230:231], v145 src0_sel:WORD_1
	v_pk_fma_f32 v[0:1], v[224:225], v[252:253], v[0:1] op_sel_hi:[1,0,1]
	v_pk_fma_f32 v[2:3], v[226:227], v[252:253], v[2:3] op_sel_hi:[1,0,1]
	v_pk_fma_f32 v[4:5], v[228:229], v[252:253], v[4:5] op_sel_hi:[1,0,1]
	v_pk_fma_f32 v[6:7], v[230:231], v[252:253], v[6:7] op_sel_hi:[1,0,1]
	v_cvt_pk_f32_fp8_e32 v[224:225], v146
	v_cvt_pk_f32_fp8_sdwa v[226:227], v146 src0_sel:WORD_1
	v_cvt_pk_f32_fp8_e32 v[228:229], v147
	v_cvt_pk_f32_fp8_sdwa v[230:231], v147 src0_sel:WORD_1
	v_pk_fma_f32 v[8:9], v[224:225], v[252:253], v[8:9] op_sel_hi:[1,0,1]
	v_pk_fma_f32 v[10:11], v[226:227], v[252:253], v[10:11] op_sel_hi:[1,0,1]
	v_pk_fma_f32 v[12:13], v[228:229], v[252:253], v[12:13] op_sel_hi:[1,0,1]
	v_pk_fma_f32 v[14:15], v[230:231], v[252:253], v[14:15] op_sel_hi:[1,0,1]
	v_cvt_pk_f32_fp8_e32 v[224:225], v148
	v_cvt_pk_f32_fp8_sdwa v[226:227], v148 src0_sel:WORD_1
	v_cvt_pk_f32_fp8_e32 v[228:229], v149
	v_cvt_pk_f32_fp8_sdwa v[230:231], v149 src0_sel:WORD_1
	v_pk_fma_f32 v[0:1], v[224:225], v[252:253], v[0:1] op_sel:[0,1,0] op_sel_hi:[1,1,1]
	v_pk_fma_f32 v[2:3], v[226:227], v[252:253], v[2:3] op_sel:[0,1,0] op_sel_hi:[1,1,1]
	v_pk_fma_f32 v[4:5], v[228:229], v[252:253], v[4:5] op_sel:[0,1,0] op_sel_hi:[1,1,1]
	v_pk_fma_f32 v[6:7], v[230:231], v[252:253], v[6:7] op_sel:[0,1,0] op_sel_hi:[1,1,1]
	v_cvt_pk_f32_fp8_e32 v[224:225], v150
	v_cvt_pk_f32_fp8_sdwa v[226:227], v150 src0_sel:WORD_1
	v_cvt_pk_f32_fp8_e32 v[228:229], v151
	v_cvt_pk_f32_fp8_sdwa v[230:231], v151 src0_sel:WORD_1
	v_pk_fma_f32 v[8:9], v[224:225], v[252:253], v[8:9] op_sel:[0,1,0] op_sel_hi:[1,1,1]
	v_pk_fma_f32 v[10:11], v[226:227], v[252:253], v[10:11] op_sel:[0,1,0] op_sel_hi:[1,1,1]
	v_pk_fma_f32 v[12:13], v[228:229], v[252:253], v[12:13] op_sel:[0,1,0] op_sel_hi:[1,1,1]
	v_pk_fma_f32 v[14:15], v[230:231], v[252:253], v[14:15] op_sel:[0,1,0] op_sel_hi:[1,1,1]
	v_cvt_pk_f32_fp8_e32 v[224:225], v152
	v_cvt_pk_f32_fp8_sdwa v[226:227], v152 src0_sel:WORD_1
	v_cvt_pk_f32_fp8_e32 v[228:229], v153
	v_cvt_pk_f32_fp8_sdwa v[230:231], v153 src0_sel:WORD_1
	v_pk_fma_f32 v[0:1], v[224:225], v[254:255], v[0:1] op_sel_hi:[1,0,1]
	v_pk_fma_f32 v[2:3], v[226:227], v[254:255], v[2:3] op_sel_hi:[1,0,1]
	v_pk_fma_f32 v[4:5], v[228:229], v[254:255], v[4:5] op_sel_hi:[1,0,1]
	v_pk_fma_f32 v[6:7], v[230:231], v[254:255], v[6:7] op_sel_hi:[1,0,1]
	v_cvt_pk_f32_fp8_e32 v[224:225], v154
	v_cvt_pk_f32_fp8_sdwa v[226:227], v154 src0_sel:WORD_1
	v_cvt_pk_f32_fp8_e32 v[228:229], v155
	v_cvt_pk_f32_fp8_sdwa v[230:231], v155 src0_sel:WORD_1
	v_pk_fma_f32 v[8:9], v[224:225], v[254:255], v[8:9] op_sel_hi:[1,0,1]
	v_pk_fma_f32 v[10:11], v[226:227], v[254:255], v[10:11] op_sel_hi:[1,0,1]
	v_pk_fma_f32 v[12:13], v[228:229], v[254:255], v[12:13] op_sel_hi:[1,0,1]
	v_pk_fma_f32 v[14:15], v[230:231], v[254:255], v[14:15] op_sel_hi:[1,0,1]
	v_cvt_pk_f32_fp8_e32 v[224:225], v156
	v_cvt_pk_f32_fp8_sdwa v[226:227], v156 src0_sel:WORD_1
	v_cvt_pk_f32_fp8_e32 v[228:229], v157
	v_cvt_pk_f32_fp8_sdwa v[230:231], v157 src0_sel:WORD_1
	v_pk_fma_f32 v[0:1], v[224:225], v[254:255], v[0:1] op_sel:[0,1,0] op_sel_hi:[1,1,1]
	v_pk_fma_f32 v[2:3], v[226:227], v[254:255], v[2:3] op_sel:[0,1,0] op_sel_hi:[1,1,1]
	v_pk_fma_f32 v[4:5], v[228:229], v[254:255], v[4:5] op_sel:[0,1,0] op_sel_hi:[1,1,1]
	v_pk_fma_f32 v[6:7], v[230:231], v[254:255], v[6:7] op_sel:[0,1,0] op_sel_hi:[1,1,1]
	v_cvt_pk_f32_fp8_e32 v[224:225], v158
	v_cvt_pk_f32_fp8_sdwa v[226:227], v158 src0_sel:WORD_1
	v_cvt_pk_f32_fp8_e32 v[228:229], v159
	v_cvt_pk_f32_fp8_sdwa v[230:231], v159 src0_sel:WORD_1
	v_pk_fma_f32 v[8:9], v[224:225], v[254:255], v[8:9] op_sel:[0,1,0] op_sel_hi:[1,1,1]
	v_pk_fma_f32 v[10:11], v[226:227], v[254:255], v[10:11] op_sel:[0,1,0] op_sel_hi:[1,1,1]
	v_pk_fma_f32 v[12:13], v[228:229], v[254:255], v[12:13] op_sel:[0,1,0] op_sel_hi:[1,1,1]
	v_pk_fma_f32 v[14:15], v[230:231], v[254:255], v[14:15] op_sel:[0,1,0] op_sel_hi:[1,1,1]
	s_sub_i32 s90, s90, 1
	s_cmp_eq_u32 s90, 0
	s_cbranch_scc1 .LV_sw2
.LV_t0_s2:
	s_waitcnt lgkmcnt(0)
	buffer_load_dwordx4 v[144:147], v[232:233], s[60:63], 0 idxen offen
	buffer_load_dwordx4 v[148:151], v[234:235], s[60:63], 0 idxen offen
	buffer_load_dwordx4 v[152:155], v[236:237], s[60:63], 0 idxen offen
	buffer_load_dwordx4 v[156:159], v[238:239], s[60:63], 0 idxen offen
	ds_read_b32 v232, v213 offset:112
	ds_read_b32 v234, v213 offset:116
	ds_read_b32 v236, v213 offset:120
	ds_read_b32 v238, v213 offset:124
	ds_read_b128 v[252:255], v213 offset:5040
	s_waitcnt vmcnt(16)
	v_cvt_pk_f32_fp8_e32 v[224:225], v160
	v_cvt_pk_f32_fp8_sdwa v[226:227], v160 src0_sel:WORD_1
	v_cvt_pk_f32_fp8_e32 v[228:229], v161
	v_cvt_pk_f32_fp8_sdwa v[230:231], v161 src0_sel:WORD_1
	v_pk_fma_f32 v[0:1], v[224:225], v[248:249], v[0:1] op_sel_hi:[1,0,1]
	v_pk_fma_f32 v[2:3], v[226:227], v[248:249], v[2:3] op_sel_hi:[1,0,1]
	v_pk_fma_f32 v[4:5], v[228:229], v[248:249], v[4:5] op_sel_hi:[1,0,1]
	v_pk_fma_f32 v[6:7], v[230:231], v[248:249], v[6:7] op_sel_hi:[1,0,1]
	v_cvt_pk_f32_fp8_e32 v[224:225], v162
	v_cvt_pk_f32_fp8_sdwa v[226:227], v162 src0_sel:WORD_1
	v_cvt_pk_f32_fp8_e32 v[228:229], v163
	v_cvt_pk_f32_fp8_sdwa v[230:231], v163 src0_sel:WORD_1
	v_pk_fma_f32 v[8:9], v[224:225], v[248:249], v[8:9] op_sel_hi:[1,0,1]
	v_pk_fma_f32 v[10:11], v[226:227], v[248:249], v[10:11] op_sel_hi:[1,0,1]
	v_pk_fma_f32 v[12:13], v[228:229], v[248:249], v[12:13] op_sel_hi:[1,0,1]
	v_pk_fma_f32 v[14:15], v[230:231], v[248:249], v[14:15] op_sel_hi:[1,0,1]
	v_cvt_pk_f32_fp8_e32 v[224:225], v164
	v_cvt_pk_f32_fp8_sdwa v[226:227], v164 src0_sel:WORD_1
	v_cvt_pk_f32_fp8_e32 v[228:229], v165
	v_cvt_pk_f32_fp8_sdwa v[230:231], v165 src0_sel:WORD_1
	v_pk_fma_f32 v[0:1], v[224:225], v[248:249], v[0:1] op_sel:[0,1,0] op_sel_hi:[1,1,1]
	v_pk_fma_f32 v[2:3], v[226:227], v[248:249], v[2:3] op_sel:[0,1,0] op_sel_hi:[1,1,1]
	v_pk_fma_f32 v[4:5], v[228:229], v[248:249], v[4:5] op_sel:[0,1,0] op_sel_hi:[1,1,1]
	v_pk_fma_f32 v[6:7], v[230:231], v[248:249], v[6:7] op_sel:[0,1,0] op_sel_hi:[1,1,1]
	v_cvt_pk_f32_fp8_e32 v[224:225], v166
	v_cvt_pk_f32_fp8_sdwa v[226:227], v166 src0_sel:WORD_1
	v_cvt_pk_f32_fp8_e32 v[228:229], v167
	v_cvt_pk_f32_fp8_sdwa v[230:231], v167 src0_sel:WORD_1
	v_pk_fma_f32 v[8:9], v[224:225], v[248:249], v[8:9] op_sel:[0,1,0] op_sel_hi:[1,1,1]
	v_pk_fma_f32 v[10:11], v[226:227], v[248:249], v[10:11] op_sel:[0,1,0] op_sel_hi:[1,1,1]
	v_pk_fma_f32 v[12:13], v[228:229], v[248:249], v[12:13] op_sel:[0,1,0] op_sel_hi:[1,1,1]
	v_pk_fma_f32 v[14:15], v[230:231], v[248:249], v[14:15] op_sel:[0,1,0] op_sel_hi:[1,1,1]
	v_cvt_pk_f32_fp8_e32 v[224:225], v168
	v_cvt_pk_f32_fp8_sdwa v[226:227], v168 src0_sel:WORD_1
	v_cvt_pk_f32_fp8_e32 v[228:229], v169
	v_cvt_pk_f32_fp8_sdwa v[230:231], v169 src0_sel:WORD_1
	v_pk_fma_f32 v[0:1], v[224:225], v[250:251], v[0:1] op_sel_hi:[1,0,1]
	v_pk_fma_f32 v[2:3], v[226:227], v[250:251], v[2:3] op_sel_hi:[1,0,1]
	v_pk_fma_f32 v[4:5], v[228:229], v[250:251], v[4:5] op_sel_hi:[1,0,1]
	v_pk_fma_f32 v[6:7], v[230:231], v[250:251], v[6:7] op_sel_hi:[1,0,1]
	v_cvt_pk_f32_fp8_e32 v[224:225], v170
	v_cvt_pk_f32_fp8_sdwa v[226:227], v170 src0_sel:WORD_1
	v_cvt_pk_f32_fp8_e32 v[228:229], v171
	v_cvt_pk_f32_fp8_sdwa v[230:231], v171 src0_sel:WORD_1
	v_pk_fma_f32 v[8:9], v[224:225], v[250:251], v[8:9] op_sel_hi:[1,0,1]
	v_pk_fma_f32 v[10:11], v[226:227], v[250:251], v[10:11] op_sel_hi:[1,0,1]
	v_pk_fma_f32 v[12:13], v[228:229], v[250:251], v[12:13] op_sel_hi:[1,0,1]
	v_pk_fma_f32 v[14:15], v[230:231], v[250:251], v[14:15] op_sel_hi:[1,0,1]
	v_cvt_pk_f32_fp8_e32 v[224:225], v172
	v_cvt_pk_f32_fp8_sdwa v[226:227], v172 src0_sel:WORD_1
	v_cvt_pk_f32_fp8_e32 v[228:229], v173
	v_cvt_pk_f32_fp8_sdwa v[230:231], v173 src0_sel:WORD_1
	v_pk_fma_f32 v[0:1], v[224:225], v[250:251], v[0:1] op_sel:[0,1,0] op_sel_hi:[1,1,1]
	v_pk_fma_f32 v[2:3], v[226:227], v[250:251], v[2:3] op_sel:[0,1,0] op_sel_hi:[1,1,1]
	v_pk_fma_f32 v[4:5], v[228:229], v[250:251], v[4:5] op_sel:[0,1,0] op_sel_hi:[1,1,1]
	v_pk_fma_f32 v[6:7], v[230:231], v[250:251], v[6:7] op_sel:[0,1,0] op_sel_hi:[1,1,1]
	v_cvt_pk_f32_fp8_e32 v[224:225], v174
	v_cvt_pk_f32_fp8_sdwa v[226:227], v174 src0_sel:WORD_1
	v_cvt_pk_f32_fp8_e32 v[228:229], v175
	v_cvt_pk_f32_fp8_sdwa v[230:231], v175 src0_sel:WORD_1
	v_pk_fma_f32 v[8:9], v[224:225], v[250:251], v[8:9] op_sel:[0,1,0] op_sel_hi:[1,1,1]
	v_pk_fma_f32 v[10:11], v[226:227], v[250:251], v[10:11] op_sel:[0,1,0] op_sel_hi:[1,1,1]
	v_pk_fma_f32 v[12:13], v[228:229], v[250:251], v[12:13] op_sel:[0,1,0] op_sel_hi:[1,1,1]
	v_pk_fma_f32 v[14:15], v[230:231], v[250:251], v[14:15] op_sel:[0,1,0] op_sel_hi:[1,1,1]
	s_sub_i32 s90, s90, 1
	s_cmp_eq_u32 s90, 0
	s_cbranch_scc1 .LV_sw3
.LV_t0_s3:
	s_waitcnt lgkmcnt(0)
	buffer_load_dwordx4 v[160:163], v[232:233], s[60:63], 0 idxen offen
	buffer_load_dwordx4 v[164:167], v[234:235], s[60:63], 0 idxen offen
	buffer_load_dwordx4 v[168:171], v[236:237], s[60:63], 0 idxen offen
	buffer_load_dwordx4 v[172:175], v[238:239], s[60:63], 0 idxen offen
	ds_read_b32 v232, v213 offset:128
	ds_read_b32 v234, v213 offset:132
	ds_read_b32 v236, v213 offset:136
	ds_read_b32 v238, v213 offset:140
	ds_read_b128 v[208:211], v213 offset:5056
	s_waitcnt vmcnt(16)
	v_cvt_pk_f32_fp8_e32 v[224:225], v176
	v_cvt_pk_f32_fp8_sdwa v[226:227], v176 src0_sel:WORD_1
	v_cvt_pk_f32_fp8_e32 v[228:229], v177
	v_cvt_pk_f32_fp8_sdwa v[230:231], v177 src0_sel:WORD_1
	v_pk_fma_f32 v[0:1], v[224:225], v[252:253], v[0:1] op_sel_hi:[1,0,1]
	v_pk_fma_f32 v[2:3], v[226:227], v[252:253], v[2:3] op_sel_hi:[1,0,1]
	v_pk_fma_f32 v[4:5], v[228:229], v[252:253], v[4:5] op_sel_hi:[1,0,1]
	v_pk_fma_f32 v[6:7], v[230:231], v[252:253], v[6:7] op_sel_hi:[1,0,1]
	v_cvt_pk_f32_fp8_e32 v[224:225], v178
	v_cvt_pk_f32_fp8_sdwa v[226:227], v178 src0_sel:WORD_1
	v_cvt_pk_f32_fp8_e32 v[228:229], v179
	v_cvt_pk_f32_fp8_sdwa v[230:231], v179 src0_sel:WORD_1
	v_pk_fma_f32 v[8:9], v[224:225], v[252:253], v[8:9] op_sel_hi:[1,0,1]
	v_pk_fma_f32 v[10:11], v[226:227], v[252:253], v[10:11] op_sel_hi:[1,0,1]
	v_pk_fma_f32 v[12:13], v[228:229], v[252:253], v[12:13] op_sel_hi:[1,0,1]
	v_pk_fma_f32 v[14:15], v[230:231], v[252:253], v[14:15] op_sel_hi:[1,0,1]
	v_cvt_pk_f32_fp8_e32 v[224:225], v180
	v_cvt_pk_f32_fp8_sdwa v[226:227], v180 src0_sel:WORD_1
	v_cvt_pk_f32_fp8_e32 v[228:229], v181
	v_cvt_pk_f32_fp8_sdwa v[230:231], v181 src0_sel:WORD_1
	v_pk_fma_f32 v[0:1], v[224:225], v[252:253], v[0:1] op_sel:[0,1,0] op_sel_hi:[1,1,1]
	v_pk_fma_f32 v[2:3], v[226:227], v[252:253], v[2:3] op_sel:[0,1,0] op_sel_hi:[1,1,1]
	v_pk_fma_f32 v[4:5], v[228:229], v[252:253], v[4:5] op_sel:[0,1,0] op_sel_hi:[1,1,1]
	v_pk_fma_f32 v[6:7], v[230:231], v[252:253], v[6:7] op_sel:[0,1,0] op_sel_hi:[1,1,1]
	v_cvt_pk_f32_fp8_e32 v[224:225], v182
	v_cvt_pk_f32_fp8_sdwa v[226:227], v182 src0_sel:WORD_1
	v_cvt_pk_f32_fp8_e32 v[228:229], v183
	v_cvt_pk_f32_fp8_sdwa v[230:231], v183 src0_sel:WORD_1
	v_pk_fma_f32 v[8:9], v[224:225], v[252:253], v[8:9] op_sel:[0,1,0] op_sel_hi:[1,1,1]
	v_pk_fma_f32 v[10:11], v[226:227], v[252:253], v[10:11] op_sel:[0,1,0] op_sel_hi:[1,1,1]
	v_pk_fma_f32 v[12:13], v[228:229], v[252:253], v[12:13] op_sel:[0,1,0] op_sel_hi:[1,1,1]
	v_pk_fma_f32 v[14:15], v[230:231], v[252:253], v[14:15] op_sel:[0,1,0] op_sel_hi:[1,1,1]
	v_cvt_pk_f32_fp8_e32 v[224:225], v184
	v_cvt_pk_f32_fp8_sdwa v[226:227], v184 src0_sel:WORD_1
	v_cvt_pk_f32_fp8_e32 v[228:229], v185
	v_cvt_pk_f32_fp8_sdwa v[230:231], v185 src0_sel:WORD_1
	v_pk_fma_f32 v[0:1], v[224:225], v[254:255], v[0:1] op_sel_hi:[1,0,1]
	v_pk_fma_f32 v[2:3], v[226:227], v[254:255], v[2:3] op_sel_hi:[1,0,1]
	v_pk_fma_f32 v[4:5], v[228:229], v[254:255], v[4:5] op_sel_hi:[1,0,1]
	v_pk_fma_f32 v[6:7], v[230:231], v[254:255], v[6:7] op_sel_hi:[1,0,1]
	v_cvt_pk_f32_fp8_e32 v[224:225], v186
	v_cvt_pk_f32_fp8_sdwa v[226:227], v186 src0_sel:WORD_1
	v_cvt_pk_f32_fp8_e32 v[228:229], v187
	v_cvt_pk_f32_fp8_sdwa v[230:231], v187 src0_sel:WORD_1
	v_pk_fma_f32 v[8:9], v[224:225], v[254:255], v[8:9] op_sel_hi:[1,0,1]
	v_pk_fma_f32 v[10:11], v[226:227], v[254:255], v[10:11] op_sel_hi:[1,0,1]
	v_pk_fma_f32 v[12:13], v[228:229], v[254:255], v[12:13] op_sel_hi:[1,0,1]
	v_pk_fma_f32 v[14:15], v[230:231], v[254:255], v[14:15] op_sel_hi:[1,0,1]
	v_cvt_pk_f32_fp8_e32 v[224:225], v188
	v_cvt_pk_f32_fp8_sdwa v[226:227], v188 src0_sel:WORD_1
	v_cvt_pk_f32_fp8_e32 v[228:229], v189
	v_cvt_pk_f32_fp8_sdwa v[230:231], v189 src0_sel:WORD_1
	v_pk_fma_f32 v[0:1], v[224:225], v[254:255], v[0:1] op_sel:[0,1,0] op_sel_hi:[1,1,1]
	v_pk_fma_f32 v[2:3], v[226:227], v[254:255], v[2:3] op_sel:[0,1,0] op_sel_hi:[1,1,1]
	v_pk_fma_f32 v[4:5], v[228:229], v[254:255], v[4:5] op_sel:[0,1,0] op_sel_hi:[1,1,1]
	v_pk_fma_f32 v[6:7], v[230:231], v[254:255], v[6:7] op_sel:[0,1,0] op_sel_hi:[1,1,1]
	v_cvt_pk_f32_fp8_e32 v[224:225], v190
	v_cvt_pk_f32_fp8_sdwa v[226:227], v190 src0_sel:WORD_1
	v_cvt_pk_f32_fp8_e32 v[228:229], v191
	v_cvt_pk_f32_fp8_sdwa v[230:231], v191 src0_sel:WORD_1
	v_pk_fma_f32 v[8:9], v[224:225], v[254:255], v[8:9] op_sel:[0,1,0] op_sel_hi:[1,1,1]
	v_pk_fma_f32 v[10:11], v[226:227], v[254:255], v[10:11] op_sel:[0,1,0] op_sel_hi:[1,1,1]
	v_pk_fma_f32 v[12:13], v[228:229], v[254:255], v[12:13] op_sel:[0,1,0] op_sel_hi:[1,1,1]
	v_pk_fma_f32 v[14:15], v[230:231], v[254:255], v[14:15] op_sel:[0,1,0] op_sel_hi:[1,1,1]
	s_sub_i32 s90, s90, 1
	s_cmp_eq_u32 s90, 0
	s_cbranch_scc1 .LV_sw4
.LV_t0_s4:
	s_waitcnt lgkmcnt(0)
	buffer_load_dwordx4 v[176:179], v[232:233], s[60:63], 0 idxen offen
	buffer_load_dwordx4 v[180:183], v[234:235], s[60:63], 0 idxen offen
	buffer_load_dwordx4 v[184:187], v[236:237], s[60:63], 0 idxen offen
	buffer_load_dwordx4 v[188:191], v[238:239], s[60:63], 0 idxen offen
	ds_read_b32 v232, v213 offset:144
	ds_read_b32 v234, v213 offset:148
	ds_read_b32 v236, v213 offset:152
	ds_read_b32 v238, v213 offset:156
	ds_read_b128 v[248:251], v213 offset:5072
	s_waitcnt vmcnt(16)
	v_cvt_pk_f32_fp8_e32 v[224:225], v192
	v_cvt_pk_f32_fp8_sdwa v[226:227], v192 src0_sel:WORD_1
	v_cvt_pk_f32_fp8_e32 v[228:229], v193
	v_cvt_pk_f32_fp8_sdwa v[230:231], v193 src0_sel:WORD_1
	v_pk_fma_f32 v[0:1], v[224:225], v[208:209], v[0:1] op_sel_hi:[1,0,1]
	v_pk_fma_f32 v[2:3], v[226:227], v[208:209], v[2:3] op_sel_hi:[1,0,1]
	v_pk_fma_f32 v[4:5], v[228:229], v[208:209], v[4:5] op_sel_hi:[1,0,1]
	v_pk_fma_f32 v[6:7], v[230:231], v[208:209], v[6:7] op_sel_hi:[1,0,1]
	v_cvt_pk_f32_fp8_e32 v[224:225], v194
	v_cvt_pk_f32_fp8_sdwa v[226:227], v194 src0_sel:WORD_1
	v_cvt_pk_f32_fp8_e32 v[228:229], v195
	v_cvt_pk_f32_fp8_sdwa v[230:231], v195 src0_sel:WORD_1
	v_pk_fma_f32 v[8:9], v[224:225], v[208:209], v[8:9] op_sel_hi:[1,0,1]
	v_pk_fma_f32 v[10:11], v[226:227], v[208:209], v[10:11] op_sel_hi:[1,0,1]
	v_pk_fma_f32 v[12:13], v[228:229], v[208:209], v[12:13] op_sel_hi:[1,0,1]
	v_pk_fma_f32 v[14:15], v[230:231], v[208:209], v[14:15] op_sel_hi:[1,0,1]
	v_cvt_pk_f32_fp8_e32 v[224:225], v196
	v_cvt_pk_f32_fp8_sdwa v[226:227], v196 src0_sel:WORD_1
	v_cvt_pk_f32_fp8_e32 v[228:229], v197
	v_cvt_pk_f32_fp8_sdwa v[230:231], v197 src0_sel:WORD_1
	v_pk_fma_f32 v[0:1], v[224:225], v[208:209], v[0:1] op_sel:[0,1,0] op_sel_hi:[1,1,1]
	v_pk_fma_f32 v[2:3], v[226:227], v[208:209], v[2:3] op_sel:[0,1,0] op_sel_hi:[1,1,1]
	v_pk_fma_f32 v[4:5], v[228:229], v[208:209], v[4:5] op_sel:[0,1,0] op_sel_hi:[1,1,1]
	v_pk_fma_f32 v[6:7], v[230:231], v[208:209], v[6:7] op_sel:[0,1,0] op_sel_hi:[1,1,1]
	v_cvt_pk_f32_fp8_e32 v[224:225], v198
	v_cvt_pk_f32_fp8_sdwa v[226:227], v198 src0_sel:WORD_1
	v_cvt_pk_f32_fp8_e32 v[228:229], v199
	v_cvt_pk_f32_fp8_sdwa v[230:231], v199 src0_sel:WORD_1
	v_pk_fma_f32 v[8:9], v[224:225], v[208:209], v[8:9] op_sel:[0,1,0] op_sel_hi:[1,1,1]
	v_pk_fma_f32 v[10:11], v[226:227], v[208:209], v[10:11] op_sel:[0,1,0] op_sel_hi:[1,1,1]
	v_pk_fma_f32 v[12:13], v[228:229], v[208:209], v[12:13] op_sel:[0,1,0] op_sel_hi:[1,1,1]
	v_pk_fma_f32 v[14:15], v[230:231], v[208:209], v[14:15] op_sel:[0,1,0] op_sel_hi:[1,1,1]
	v_cvt_pk_f32_fp8_e32 v[224:225], v200
	v_cvt_pk_f32_fp8_sdwa v[226:227], v200 src0_sel:WORD_1
	v_cvt_pk_f32_fp8_e32 v[228:229], v201
	v_cvt_pk_f32_fp8_sdwa v[230:231], v201 src0_sel:WORD_1
	v_pk_fma_f32 v[0:1], v[224:225], v[210:211], v[0:1] op_sel_hi:[1,0,1]
	v_pk_fma_f32 v[2:3], v[226:227], v[210:211], v[2:3] op_sel_hi:[1,0,1]
	v_pk_fma_f32 v[4:5], v[228:229], v[210:211], v[4:5] op_sel_hi:[1,0,1]
	v_pk_fma_f32 v[6:7], v[230:231], v[210:211], v[6:7] op_sel_hi:[1,0,1]
	v_cvt_pk_f32_fp8_e32 v[224:225], v202
	v_cvt_pk_f32_fp8_sdwa v[226:227], v202 src0_sel:WORD_1
	v_cvt_pk_f32_fp8_e32 v[228:229], v203
	v_cvt_pk_f32_fp8_sdwa v[230:231], v203 src0_sel:WORD_1
	v_pk_fma_f32 v[8:9], v[224:225], v[210:211], v[8:9] op_sel_hi:[1,0,1]
	v_pk_fma_f32 v[10:11], v[226:227], v[210:211], v[10:11] op_sel_hi:[1,0,1]
	v_pk_fma_f32 v[12:13], v[228:229], v[210:211], v[12:13] op_sel_hi:[1,0,1]
	v_pk_fma_f32 v[14:15], v[230:231], v[210:211], v[14:15] op_sel_hi:[1,0,1]
	v_cvt_pk_f32_fp8_e32 v[224:225], v204
	v_cvt_pk_f32_fp8_sdwa v[226:227], v204 src0_sel:WORD_1
	v_cvt_pk_f32_fp8_e32 v[228:229], v205
	v_cvt_pk_f32_fp8_sdwa v[230:231], v205 src0_sel:WORD_1
	v_pk_fma_f32 v[0:1], v[224:225], v[210:211], v[0:1] op_sel:[0,1,0] op_sel_hi:[1,1,1]
	v_pk_fma_f32 v[2:3], v[226:227], v[210:211], v[2:3] op_sel:[0,1,0] op_sel_hi:[1,1,1]
	v_pk_fma_f32 v[4:5], v[228:229], v[210:211], v[4:5] op_sel:[0,1,0] op_sel_hi:[1,1,1]
	v_pk_fma_f32 v[6:7], v[230:231], v[210:211], v[6:7] op_sel:[0,1,0] op_sel_hi:[1,1,1]
	v_cvt_pk_f32_fp8_e32 v[224:225], v206
	v_cvt_pk_f32_fp8_sdwa v[226:227], v206 src0_sel:WORD_1
	v_cvt_pk_f32_fp8_e32 v[228:229], v207
	v_cvt_pk_f32_fp8_sdwa v[230:231], v207 src0_sel:WORD_1
	v_pk_fma_f32 v[8:9], v[224:225], v[210:211], v[8:9] op_sel:[0,1,0] op_sel_hi:[1,1,1]
	v_pk_fma_f32 v[10:11], v[226:227], v[210:211], v[10:11] op_sel:[0,1,0] op_sel_hi:[1,1,1]
	v_pk_fma_f32 v[12:13], v[228:229], v[210:211], v[12:13] op_sel:[0,1,0] op_sel_hi:[1,1,1]
	v_pk_fma_f32 v[14:15], v[230:231], v[210:211], v[14:15] op_sel:[0,1,0] op_sel_hi:[1,1,1]
	v_add_u32_e32 v213, 80, v213
	s_add_i32 s21, s21, 5
	s_sub_i32 s90, s90, 1
	s_cmp_eq_u32 s90, 0
	s_cbranch_scc1 .LV_sw0
	s_branch .LV_t0_s0
.LV_t1_s0:
	s_cmp_ge_u32 s21, s20
	s_cbranch_scc1 .LV_done
	s_waitcnt lgkmcnt(0)
	buffer_load_dwordx4 v[192:195], v[232:233], s[60:63], 0 idxen offen
	buffer_load_dwordx4 v[196:199], v[234:235], s[60:63], 0 idxen offen
	buffer_load_dwordx4 v[200:203], v[236:237], s[60:63], 0 idxen offen
	buffer_load_dwordx4 v[204:207], v[238:239], s[60:63], 0 idxen offen
	ds_read_b32 v232, v213 offset:80
	ds_read_b32 v234, v213 offset:84
	ds_read_b32 v236, v213 offset:88
	ds_read_b32 v238, v213 offset:92
	ds_read_b128 v[252:255], v213 offset:5008
	s_waitcnt vmcnt(16)
	v_cvt_pk_f32_fp8_e32 v[224:225], v128
	v_cvt_pk_f32_fp8_sdwa v[226:227], v128 src0_sel:WORD_1
	v_cvt_pk_f32_fp8_e32 v[228:229], v129
	v_cvt_pk_f32_fp8_sdwa v[230:231], v129 src0_sel:WORD_1
	v_pk_fma_f32 v[16:17], v[224:225], v[248:249], v[16:17] op_sel_hi:[1,0,1]
	v_pk_fma_f32 v[18:19], v[226:227], v[248:249], v[18:19] op_sel_hi:[1,0,1]
	v_pk_fma_f32 v[20:21], v[228:229], v[248:249], v[20:21] op_sel_hi:[1,0,1]
	v_pk_fma_f32 v[22:23], v[230:231], v[248:249], v[22:23] op_sel_hi:[1,0,1]
	v_cvt_pk_f32_fp8_e32 v[224:225], v130
	v_cvt_pk_f32_fp8_sdwa v[226:227], v130 src0_sel:WORD_1
	v_cvt_pk_f32_fp8_e32 v[228:229], v131
	v_cvt_pk_f32_fp8_sdwa v[230:231], v131 src0_sel:WORD_1
	v_pk_fma_f32 v[24:25], v[224:225], v[248:249], v[24:25] op_sel_hi:[1,0,1]
	v_pk_fma_f32 v[26:27], v[226:227], v[248:249], v[26:27] op_sel_hi:[1,0,1]
	v_pk_fma_f32 v[28:29], v[228:229], v[248:249], v[28:29] op_sel_hi:[1,0,1]
	v_pk_fma_f32 v[30:31], v[230:231], v[248:249], v[30:31] op_sel_hi:[1,0,1]
	v_cvt_pk_f32_fp8_e32 v[224:225], v132
	v_cvt_pk_f32_fp8_sdwa v[226:227], v132 src0_sel:WORD_1
	v_cvt_pk_f32_fp8_e32 v[228:229], v133
	v_cvt_pk_f32_fp8_sdwa v[230:231], v133 src0_sel:WORD_1
	v_pk_fma_f32 v[16:17], v[224:225], v[248:249], v[16:17] op_sel:[0,1,0] op_sel_hi:[1,1,1]
	v_pk_fma_f32 v[18:19], v[226:227], v[248:249], v[18:19] op_sel:[0,1,0] op_sel_hi:[1,1,1]
	v_pk_fma_f32 v[20:21], v[228:229], v[248:249], v[20:21] op_sel:[0,1,0] op_sel_hi:[1,1,1]
	v_pk_fma_f32 v[22:23], v[230:231], v[248:249], v[22:23] op_sel:[0,1,0] op_sel_hi:[1,1,1]
	v_cvt_pk_f32_fp8_e32 v[224:225], v134
	v_cvt_pk_f32_fp8_sdwa v[226:227], v134 src0_sel:WORD_1
	v_cvt_pk_f32_fp8_e32 v[228:229], v135
	v_cvt_pk_f32_fp8_sdwa v[230:231], v135 src0_sel:WORD_1
	v_pk_fma_f32 v[24:25], v[224:225], v[248:249], v[24:25] op_sel:[0,1,0] op_sel_hi:[1,1,1]
	v_pk_fma_f32 v[26:27], v[226:227], v[248:249], v[26:27] op_sel:[0,1,0] op_sel_hi:[1,1,1]
	v_pk_fma_f32 v[28:29], v[228:229], v[248:249], v[28:29] op_sel:[0,1,0] op_sel_hi:[1,1,1]
	v_pk_fma_f32 v[30:31], v[230:231], v[248:249], v[30:31] op_sel:[0,1,0] op_sel_hi:[1,1,1]
	v_cvt_pk_f32_fp8_e32 v[224:225], v136
	v_cvt_pk_f32_fp8_sdwa v[226:227], v136 src0_sel:WORD_1
	v_cvt_pk_f32_fp8_e32 v[228:229], v137
	v_cvt_pk_f32_fp8_sdwa v[230:231], v137 src0_sel:WORD_1
	v_pk_fma_f32 v[16:17], v[224:225], v[250:251], v[16:17] op_sel_hi:[1,0,1]
	v_pk_fma_f32 v[18:19], v[226:227], v[250:251], v[18:19] op_sel_hi:[1,0,1]
	v_pk_fma_f32 v[20:21], v[228:229], v[250:251], v[20:21] op_sel_hi:[1,0,1]
	v_pk_fma_f32 v[22:23], v[230:231], v[250:251], v[22:23] op_sel_hi:[1,0,1]
	v_cvt_pk_f32_fp8_e32 v[224:225], v138
	v_cvt_pk_f32_fp8_sdwa v[226:227], v138 src0_sel:WORD_1
	v_cvt_pk_f32_fp8_e32 v[228:229], v139
	v_cvt_pk_f32_fp8_sdwa v[230:231], v139 src0_sel:WORD_1
	v_pk_fma_f32 v[24:25], v[224:225], v[250:251], v[24:25] op_sel_hi:[1,0,1]
	v_pk_fma_f32 v[26:27], v[226:227], v[250:251], v[26:27] op_sel_hi:[1,0,1]
	v_pk_fma_f32 v[28:29], v[228:229], v[250:251], v[28:29] op_sel_hi:[1,0,1]
	v_pk_fma_f32 v[30:31], v[230:231], v[250:251], v[30:31] op_sel_hi:[1,0,1]
	v_cvt_pk_f32_fp8_e32 v[224:225], v140
	v_cvt_pk_f32_fp8_sdwa v[226:227], v140 src0_sel:WORD_1
	v_cvt_pk_f32_fp8_e32 v[228:229], v141
	v_cvt_pk_f32_fp8_sdwa v[230:231], v141 src0_sel:WORD_1
	v_pk_fma_f32 v[16:17], v[224:225], v[250:251], v[16:17] op_sel:[0,1,0] op_sel_hi:[1,1,1]
	v_pk_fma_f32 v[18:19], v[226:227], v[250:251], v[18:19] op_sel:[0,1,0] op_sel_hi:[1,1,1]
	v_pk_fma_f32 v[20:21], v[228:229], v[250:251], v[20:21] op_sel:[0,1,0] op_sel_hi:[1,1,1]
	v_pk_fma_f32 v[22:23], v[230:231], v[250:251], v[22:23] op_sel:[0,1,0] op_sel_hi:[1,1,1]
	v_cvt_pk_f32_fp8_e32 v[224:225], v142
	v_cvt_pk_f32_fp8_sdwa v[226:227], v142 src0_sel:WORD_1
	v_cvt_pk_f32_fp8_e32 v[228:229], v143
	v_cvt_pk_f32_fp8_sdwa v[230:231], v143 src0_sel:WORD_1
	v_pk_fma_f32 v[24:25], v[224:225], v[250:251], v[24:25] op_sel:[0,1,0] op_sel_hi:[1,1,1]
	v_pk_fma_f32 v[26:27], v[226:227], v[250:251], v[26:27] op_sel:[0,1,0] op_sel_hi:[1,1,1]
	v_pk_fma_f32 v[28:29], v[228:229], v[250:251], v[28:29] op_sel:[0,1,0] op_sel_hi:[1,1,1]
	v_pk_fma_f32 v[30:31], v[230:231], v[250:251], v[30:31] op_sel:[0,1,0] op_sel_hi:[1,1,1]
	s_sub_i32 s90, s90, 1
	s_cmp_eq_u32 s90, 0
	s_cbranch_scc1 .LV_sw1
.LV_t1_s1:
	s_waitcnt lgkmcnt(0)
	buffer_load_dwordx4 v[128:131], v[232:233], s[60:63], 0 idxen offen
	buffer_load_dwordx4 v[132:135], v[234:235], s[60:63], 0 idxen offen
	buffer_load_dwordx4 v[136:139], v[236:237], s[60:63], 0 idxen offen
	buffer_load_dwordx4 v[140:143], v[238:239], s[60:63], 0 idxen offen
	ds_read_b32 v232, v213 offset:96
	ds_read_b32 v234, v213 offset:100
	ds_read_b32 v236, v213 offset:104
	ds_read_b32 v238, v213 offset:108
	ds_read_b128 v[248:251], v213 offset:5024
	s_waitcnt vmcnt(16)
	v_cvt_pk_f32_fp8_e32 v[224:225], v144
	v_cvt_pk_f32_fp8_sdwa v[226:227], v144 src0_sel:WORD_1
	v_cvt_pk_f32_fp8_e32 v[228:229], v145
	v_cvt_pk_f32_fp8_sdwa v[230:231], v145 src0_sel:WORD_1
	v_pk_fma_f32 v[16:17], v[224:225], v[252:253], v[16:17] op_sel_hi:[1,0,1]
	v_pk_fma_f32 v[18:19], v[226:227], v[252:253], v[18:19] op_sel_hi:[1,0,1]
	v_pk_fma_f32 v[20:21], v[228:229], v[252:253], v[20:21] op_sel_hi:[1,0,1]
	v_pk_fma_f32 v[22:23], v[230:231], v[252:253], v[22:23] op_sel_hi:[1,0,1]
	v_cvt_pk_f32_fp8_e32 v[224:225], v146
	v_cvt_pk_f32_fp8_sdwa v[226:227], v146 src0_sel:WORD_1
	v_cvt_pk_f32_fp8_e32 v[228:229], v147
	v_cvt_pk_f32_fp8_sdwa v[230:231], v147 src0_sel:WORD_1
	v_pk_fma_f32 v[24:25], v[224:225], v[252:253], v[24:25] op_sel_hi:[1,0,1]
	v_pk_fma_f32 v[26:27], v[226:227], v[252:253], v[26:27] op_sel_hi:[1,0,1]
	v_pk_fma_f32 v[28:29], v[228:229], v[252:253], v[28:29] op_sel_hi:[1,0,1]
	v_pk_fma_f32 v[30:31], v[230:231], v[252:253], v[30:31] op_sel_hi:[1,0,1]
	v_cvt_pk_f32_fp8_e32 v[224:225], v148
	v_cvt_pk_f32_fp8_sdwa v[226:227], v148 src0_sel:WORD_1
	v_cvt_pk_f32_fp8_e32 v[228:229], v149
	v_cvt_pk_f32_fp8_sdwa v[230:231], v149 src0_sel:WORD_1
	v_pk_fma_f32 v[16:17], v[224:225], v[252:253], v[16:17] op_sel:[0,1,0] op_sel_hi:[1,1,1]
	v_pk_fma_f32 v[18:19], v[226:227], v[252:253], v[18:19] op_sel:[0,1,0] op_sel_hi:[1,1,1]
	v_pk_fma_f32 v[20:21], v[228:229], v[252:253], v[20:21] op_sel:[0,1,0] op_sel_hi:[1,1,1]
	v_pk_fma_f32 v[22:23], v[230:231], v[252:253], v[22:23] op_sel:[0,1,0] op_sel_hi:[1,1,1]
	v_cvt_pk_f32_fp8_e32 v[224:225], v150
	v_cvt_pk_f32_fp8_sdwa v[226:227], v150 src0_sel:WORD_1
	v_cvt_pk_f32_fp8_e32 v[228:229], v151
	v_cvt_pk_f32_fp8_sdwa v[230:231], v151 src0_sel:WORD_1
	v_pk_fma_f32 v[24:25], v[224:225], v[252:253], v[24:25] op_sel:[0,1,0] op_sel_hi:[1,1,1]
	v_pk_fma_f32 v[26:27], v[226:227], v[252:253], v[26:27] op_sel:[0,1,0] op_sel_hi:[1,1,1]
	v_pk_fma_f32 v[28:29], v[228:229], v[252:253], v[28:29] op_sel:[0,1,0] op_sel_hi:[1,1,1]
	v_pk_fma_f32 v[30:31], v[230:231], v[252:253], v[30:31] op_sel:[0,1,0] op_sel_hi:[1,1,1]
	v_cvt_pk_f32_fp8_e32 v[224:225], v152
	v_cvt_pk_f32_fp8_sdwa v[226:227], v152 src0_sel:WORD_1
	v_cvt_pk_f32_fp8_e32 v[228:229], v153
	v_cvt_pk_f32_fp8_sdwa v[230:231], v153 src0_sel:WORD_1
	v_pk_fma_f32 v[16:17], v[224:225], v[254:255], v[16:17] op_sel_hi:[1,0,1]
	v_pk_fma_f32 v[18:19], v[226:227], v[254:255], v[18:19] op_sel_hi:[1,0,1]
	v_pk_fma_f32 v[20:21], v[228:229], v[254:255], v[20:21] op_sel_hi:[1,0,1]
	v_pk_fma_f32 v[22:23], v[230:231], v[254:255], v[22:23] op_sel_hi:[1,0,1]
	v_cvt_pk_f32_fp8_e32 v[224:225], v154
	v_cvt_pk_f32_fp8_sdwa v[226:227], v154 src0_sel:WORD_1
	v_cvt_pk_f32_fp8_e32 v[228:229], v155
	v_cvt_pk_f32_fp8_sdwa v[230:231], v155 src0_sel:WORD_1
	v_pk_fma_f32 v[24:25], v[224:225], v[254:255], v[24:25] op_sel_hi:[1,0,1]
	v_pk_fma_f32 v[26:27], v[226:227], v[254:255], v[26:27] op_sel_hi:[1,0,1]
	v_pk_fma_f32 v[28:29], v[228:229], v[254:255], v[28:29] op_sel_hi:[1,0,1]
	v_pk_fma_f32 v[30:31], v[230:231], v[254:255], v[30:31] op_sel_hi:[1,0,1]
	v_cvt_pk_f32_fp8_e32 v[224:225], v156
	v_cvt_pk_f32_fp8_sdwa v[226:227], v156 src0_sel:WORD_1
	v_cvt_pk_f32_fp8_e32 v[228:229], v157
	v_cvt_pk_f32_fp8_sdwa v[230:231], v157 src0_sel:WORD_1
	v_pk_fma_f32 v[16:17], v[224:225], v[254:255], v[16:17] op_sel:[0,1,0] op_sel_hi:[1,1,1]
	v_pk_fma_f32 v[18:19], v[226:227], v[254:255], v[18:19] op_sel:[0,1,0] op_sel_hi:[1,1,1]
	v_pk_fma_f32 v[20:21], v[228:229], v[254:255], v[20:21] op_sel:[0,1,0] op_sel_hi:[1,1,1]
	v_pk_fma_f32 v[22:23], v[230:231], v[254:255], v[22:23] op_sel:[0,1,0] op_sel_hi:[1,1,1]
	v_cvt_pk_f32_fp8_e32 v[224:225], v158
	v_cvt_pk_f32_fp8_sdwa v[226:227], v158 src0_sel:WORD_1
	v_cvt_pk_f32_fp8_e32 v[228:229], v159
	v_cvt_pk_f32_fp8_sdwa v[230:231], v159 src0_sel:WORD_1
	v_pk_fma_f32 v[24:25], v[224:225], v[254:255], v[24:25] op_sel:[0,1,0] op_sel_hi:[1,1,1]
	v_pk_fma_f32 v[26:27], v[226:227], v[254:255], v[26:27] op_sel:[0,1,0] op_sel_hi:[1,1,1]
	v_pk_fma_f32 v[28:29], v[228:229], v[254:255], v[28:29] op_sel:[0,1,0] op_sel_hi:[1,1,1]
	v_pk_fma_f32 v[30:31], v[230:231], v[254:255], v[30:31] op_sel:[0,1,0] op_sel_hi:[1,1,1]
	s_sub_i32 s90, s90, 1
	s_cmp_eq_u32 s90, 0
	s_cbranch_scc1 .LV_sw2
.LV_t1_s2:
	s_waitcnt lgkmcnt(0)
	buffer_load_dwordx4 v[144:147], v[232:233], s[60:63], 0 idxen offen
	buffer_load_dwordx4 v[148:151], v[234:235], s[60:63], 0 idxen offen
	buffer_load_dwordx4 v[152:155], v[236:237], s[60:63], 0 idxen offen
	buffer_load_dwordx4 v[156:159], v[238:239], s[60:63], 0 idxen offen
	ds_read_b32 v232, v213 offset:112
	ds_read_b32 v234, v213 offset:116
	ds_read_b32 v236, v213 offset:120
	ds_read_b32 v238, v213 offset:124
	ds_read_b128 v[252:255], v213 offset:5040
	s_waitcnt vmcnt(16)
	v_cvt_pk_f32_fp8_e32 v[224:225], v160
	v_cvt_pk_f32_fp8_sdwa v[226:227], v160 src0_sel:WORD_1
	v_cvt_pk_f32_fp8_e32 v[228:229], v161
	v_cvt_pk_f32_fp8_sdwa v[230:231], v161 src0_sel:WORD_1
	v_pk_fma_f32 v[16:17], v[224:225], v[248:249], v[16:17] op_sel_hi:[1,0,1]
	v_pk_fma_f32 v[18:19], v[226:227], v[248:249], v[18:19] op_sel_hi:[1,0,1]
	v_pk_fma_f32 v[20:21], v[228:229], v[248:249], v[20:21] op_sel_hi:[1,0,1]
	v_pk_fma_f32 v[22:23], v[230:231], v[248:249], v[22:23] op_sel_hi:[1,0,1]
	v_cvt_pk_f32_fp8_e32 v[224:225], v162
	v_cvt_pk_f32_fp8_sdwa v[226:227], v162 src0_sel:WORD_1
	v_cvt_pk_f32_fp8_e32 v[228:229], v163
	v_cvt_pk_f32_fp8_sdwa v[230:231], v163 src0_sel:WORD_1
	v_pk_fma_f32 v[24:25], v[224:225], v[248:249], v[24:25] op_sel_hi:[1,0,1]
	v_pk_fma_f32 v[26:27], v[226:227], v[248:249], v[26:27] op_sel_hi:[1,0,1]
	v_pk_fma_f32 v[28:29], v[228:229], v[248:249], v[28:29] op_sel_hi:[1,0,1]
	v_pk_fma_f32 v[30:31], v[230:231], v[248:249], v[30:31] op_sel_hi:[1,0,1]
	v_cvt_pk_f32_fp8_e32 v[224:225], v164
	v_cvt_pk_f32_fp8_sdwa v[226:227], v164 src0_sel:WORD_1
	v_cvt_pk_f32_fp8_e32 v[228:229], v165
	v_cvt_pk_f32_fp8_sdwa v[230:231], v165 src0_sel:WORD_1
	v_pk_fma_f32 v[16:17], v[224:225], v[248:249], v[16:17] op_sel:[0,1,0] op_sel_hi:[1,1,1]
	v_pk_fma_f32 v[18:19], v[226:227], v[248:249], v[18:19] op_sel:[0,1,0] op_sel_hi:[1,1,1]
	v_pk_fma_f32 v[20:21], v[228:229], v[248:249], v[20:21] op_sel:[0,1,0] op_sel_hi:[1,1,1]
	v_pk_fma_f32 v[22:23], v[230:231], v[248:249], v[22:23] op_sel:[0,1,0] op_sel_hi:[1,1,1]
	v_cvt_pk_f32_fp8_e32 v[224:225], v166
	v_cvt_pk_f32_fp8_sdwa v[226:227], v166 src0_sel:WORD_1
	v_cvt_pk_f32_fp8_e32 v[228:229], v167
	v_cvt_pk_f32_fp8_sdwa v[230:231], v167 src0_sel:WORD_1
	v_pk_fma_f32 v[24:25], v[224:225], v[248:249], v[24:25] op_sel:[0,1,0] op_sel_hi:[1,1,1]
	v_pk_fma_f32 v[26:27], v[226:227], v[248:249], v[26:27] op_sel:[0,1,0] op_sel_hi:[1,1,1]
	v_pk_fma_f32 v[28:29], v[228:229], v[248:249], v[28:29] op_sel:[0,1,0] op_sel_hi:[1,1,1]
	v_pk_fma_f32 v[30:31], v[230:231], v[248:249], v[30:31] op_sel:[0,1,0] op_sel_hi:[1,1,1]
	v_cvt_pk_f32_fp8_e32 v[224:225], v168
	v_cvt_pk_f32_fp8_sdwa v[226:227], v168 src0_sel:WORD_1
	v_cvt_pk_f32_fp8_e32 v[228:229], v169
	v_cvt_pk_f32_fp8_sdwa v[230:231], v169 src0_sel:WORD_1
	v_pk_fma_f32 v[16:17], v[224:225], v[250:251], v[16:17] op_sel_hi:[1,0,1]
	v_pk_fma_f32 v[18:19], v[226:227], v[250:251], v[18:19] op_sel_hi:[1,0,1]
	v_pk_fma_f32 v[20:21], v[228:229], v[250:251], v[20:21] op_sel_hi:[1,0,1]
	v_pk_fma_f32 v[22:23], v[230:231], v[250:251], v[22:23] op_sel_hi:[1,0,1]
	v_cvt_pk_f32_fp8_e32 v[224:225], v170
	v_cvt_pk_f32_fp8_sdwa v[226:227], v170 src0_sel:WORD_1
	v_cvt_pk_f32_fp8_e32 v[228:229], v171
	v_cvt_pk_f32_fp8_sdwa v[230:231], v171 src0_sel:WORD_1
	v_pk_fma_f32 v[24:25], v[224:225], v[250:251], v[24:25] op_sel_hi:[1,0,1]
	v_pk_fma_f32 v[26:27], v[226:227], v[250:251], v[26:27] op_sel_hi:[1,0,1]
	v_pk_fma_f32 v[28:29], v[228:229], v[250:251], v[28:29] op_sel_hi:[1,0,1]
	v_pk_fma_f32 v[30:31], v[230:231], v[250:251], v[30:31] op_sel_hi:[1,0,1]
	v_cvt_pk_f32_fp8_e32 v[224:225], v172
	v_cvt_pk_f32_fp8_sdwa v[226:227], v172 src0_sel:WORD_1
	v_cvt_pk_f32_fp8_e32 v[228:229], v173
	v_cvt_pk_f32_fp8_sdwa v[230:231], v173 src0_sel:WORD_1
	v_pk_fma_f32 v[16:17], v[224:225], v[250:251], v[16:17] op_sel:[0,1,0] op_sel_hi:[1,1,1]
	v_pk_fma_f32 v[18:19], v[226:227], v[250:251], v[18:19] op_sel:[0,1,0] op_sel_hi:[1,1,1]
	v_pk_fma_f32 v[20:21], v[228:229], v[250:251], v[20:21] op_sel:[0,1,0] op_sel_hi:[1,1,1]
	v_pk_fma_f32 v[22:23], v[230:231], v[250:251], v[22:23] op_sel:[0,1,0] op_sel_hi:[1,1,1]
	v_cvt_pk_f32_fp8_e32 v[224:225], v174
	v_cvt_pk_f32_fp8_sdwa v[226:227], v174 src0_sel:WORD_1
	v_cvt_pk_f32_fp8_e32 v[228:229], v175
	v_cvt_pk_f32_fp8_sdwa v[230:231], v175 src0_sel:WORD_1
	v_pk_fma_f32 v[24:25], v[224:225], v[250:251], v[24:25] op_sel:[0,1,0] op_sel_hi:[1,1,1]
	v_pk_fma_f32 v[26:27], v[226:227], v[250:251], v[26:27] op_sel:[0,1,0] op_sel_hi:[1,1,1]
	v_pk_fma_f32 v[28:29], v[228:229], v[250:251], v[28:29] op_sel:[0,1,0] op_sel_hi:[1,1,1]
	v_pk_fma_f32 v[30:31], v[230:231], v[250:251], v[30:31] op_sel:[0,1,0] op_sel_hi:[1,1,1]
	s_sub_i32 s90, s90, 1
	s_cmp_eq_u32 s90, 0
	s_cbranch_scc1 .LV_sw3
.LV_t1_s3:
	s_waitcnt lgkmcnt(0)
	buffer_load_dwordx4 v[160:163], v[232:233], s[60:63], 0 idxen offen
	buffer_load_dwordx4 v[164:167], v[234:235], s[60:63], 0 idxen offen
	buffer_load_dwordx4 v[168:171], v[236:237], s[60:63], 0 idxen offen
	buffer_load_dwordx4 v[172:175], v[238:239], s[60:63], 0 idxen offen
	ds_read_b32 v232, v213 offset:128
	ds_read_b32 v234, v213 offset:132
	ds_read_b32 v236, v213 offset:136
	ds_read_b32 v238, v213 offset:140
	ds_read_b128 v[208:211], v213 offset:5056
	s_waitcnt vmcnt(16)
	v_cvt_pk_f32_fp8_e32 v[224:225], v176
	v_cvt_pk_f32_fp8_sdwa v[226:227], v176 src0_sel:WORD_1
	v_cvt_pk_f32_fp8_e32 v[228:229], v177
	v_cvt_pk_f32_fp8_sdwa v[230:231], v177 src0_sel:WORD_1
	v_pk_fma_f32 v[16:17], v[224:225], v[252:253], v[16:17] op_sel_hi:[1,0,1]
	v_pk_fma_f32 v[18:19], v[226:227], v[252:253], v[18:19] op_sel_hi:[1,0,1]
	v_pk_fma_f32 v[20:21], v[228:229], v[252:253], v[20:21] op_sel_hi:[1,0,1]
	v_pk_fma_f32 v[22:23], v[230:231], v[252:253], v[22:23] op_sel_hi:[1,0,1]
	v_cvt_pk_f32_fp8_e32 v[224:225], v178
	v_cvt_pk_f32_fp8_sdwa v[226:227], v178 src0_sel:WORD_1
	v_cvt_pk_f32_fp8_e32 v[228:229], v179
	v_cvt_pk_f32_fp8_sdwa v[230:231], v179 src0_sel:WORD_1
	v_pk_fma_f32 v[24:25], v[224:225], v[252:253], v[24:25] op_sel_hi:[1,0,1]
	v_pk_fma_f32 v[26:27], v[226:227], v[252:253], v[26:27] op_sel_hi:[1,0,1]
	v_pk_fma_f32 v[28:29], v[228:229], v[252:253], v[28:29] op_sel_hi:[1,0,1]
	v_pk_fma_f32 v[30:31], v[230:231], v[252:253], v[30:31] op_sel_hi:[1,0,1]
	v_cvt_pk_f32_fp8_e32 v[224:225], v180
	v_cvt_pk_f32_fp8_sdwa v[226:227], v180 src0_sel:WORD_1
	v_cvt_pk_f32_fp8_e32 v[228:229], v181
	v_cvt_pk_f32_fp8_sdwa v[230:231], v181 src0_sel:WORD_1
	v_pk_fma_f32 v[16:17], v[224:225], v[252:253], v[16:17] op_sel:[0,1,0] op_sel_hi:[1,1,1]
	v_pk_fma_f32 v[18:19], v[226:227], v[252:253], v[18:19] op_sel:[0,1,0] op_sel_hi:[1,1,1]
	v_pk_fma_f32 v[20:21], v[228:229], v[252:253], v[20:21] op_sel:[0,1,0] op_sel_hi:[1,1,1]
	v_pk_fma_f32 v[22:23], v[230:231], v[252:253], v[22:23] op_sel:[0,1,0] op_sel_hi:[1,1,1]
	v_cvt_pk_f32_fp8_e32 v[224:225], v182
	v_cvt_pk_f32_fp8_sdwa v[226:227], v182 src0_sel:WORD_1
	v_cvt_pk_f32_fp8_e32 v[228:229], v183
	v_cvt_pk_f32_fp8_sdwa v[230:231], v183 src0_sel:WORD_1
	v_pk_fma_f32 v[24:25], v[224:225], v[252:253], v[24:25] op_sel:[0,1,0] op_sel_hi:[1,1,1]
	v_pk_fma_f32 v[26:27], v[226:227], v[252:253], v[26:27] op_sel:[0,1,0] op_sel_hi:[1,1,1]
	v_pk_fma_f32 v[28:29], v[228:229], v[252:253], v[28:29] op_sel:[0,1,0] op_sel_hi:[1,1,1]
	v_pk_fma_f32 v[30:31], v[230:231], v[252:253], v[30:31] op_sel:[0,1,0] op_sel_hi:[1,1,1]
	v_cvt_pk_f32_fp8_e32 v[224:225], v184
	v_cvt_pk_f32_fp8_sdwa v[226:227], v184 src0_sel:WORD_1
	v_cvt_pk_f32_fp8_e32 v[228:229], v185
	v_cvt_pk_f32_fp8_sdwa v[230:231], v185 src0_sel:WORD_1
	v_pk_fma_f32 v[16:17], v[224:225], v[254:255], v[16:17] op_sel_hi:[1,0,1]
	v_pk_fma_f32 v[18:19], v[226:227], v[254:255], v[18:19] op_sel_hi:[1,0,1]
	v_pk_fma_f32 v[20:21], v[228:229], v[254:255], v[20:21] op_sel_hi:[1,0,1]
	v_pk_fma_f32 v[22:23], v[230:231], v[254:255], v[22:23] op_sel_hi:[1,0,1]
	v_cvt_pk_f32_fp8_e32 v[224:225], v186
	v_cvt_pk_f32_fp8_sdwa v[226:227], v186 src0_sel:WORD_1
	v_cvt_pk_f32_fp8_e32 v[228:229], v187
	v_cvt_pk_f32_fp8_sdwa v[230:231], v187 src0_sel:WORD_1
	v_pk_fma_f32 v[24:25], v[224:225], v[254:255], v[24:25] op_sel_hi:[1,0,1]
	v_pk_fma_f32 v[26:27], v[226:227], v[254:255], v[26:27] op_sel_hi:[1,0,1]
	v_pk_fma_f32 v[28:29], v[228:229], v[254:255], v[28:29] op_sel_hi:[1,0,1]
	v_pk_fma_f32 v[30:31], v[230:231], v[254:255], v[30:31] op_sel_hi:[1,0,1]
	v_cvt_pk_f32_fp8_e32 v[224:225], v188
	v_cvt_pk_f32_fp8_sdwa v[226:227], v188 src0_sel:WORD_1
	v_cvt_pk_f32_fp8_e32 v[228:229], v189
	v_cvt_pk_f32_fp8_sdwa v[230:231], v189 src0_sel:WORD_1
	v_pk_fma_f32 v[16:17], v[224:225], v[254:255], v[16:17] op_sel:[0,1,0] op_sel_hi:[1,1,1]
	v_pk_fma_f32 v[18:19], v[226:227], v[254:255], v[18:19] op_sel:[0,1,0] op_sel_hi:[1,1,1]
	v_pk_fma_f32 v[20:21], v[228:229], v[254:255], v[20:21] op_sel:[0,1,0] op_sel_hi:[1,1,1]
	v_pk_fma_f32 v[22:23], v[230:231], v[254:255], v[22:23] op_sel:[0,1,0] op_sel_hi:[1,1,1]
	v_cvt_pk_f32_fp8_e32 v[224:225], v190
	v_cvt_pk_f32_fp8_sdwa v[226:227], v190 src0_sel:WORD_1
	v_cvt_pk_f32_fp8_e32 v[228:229], v191
	v_cvt_pk_f32_fp8_sdwa v[230:231], v191 src0_sel:WORD_1
	v_pk_fma_f32 v[24:25], v[224:225], v[254:255], v[24:25] op_sel:[0,1,0] op_sel_hi:[1,1,1]
	v_pk_fma_f32 v[26:27], v[226:227], v[254:255], v[26:27] op_sel:[0,1,0] op_sel_hi:[1,1,1]
	v_pk_fma_f32 v[28:29], v[228:229], v[254:255], v[28:29] op_sel:[0,1,0] op_sel_hi:[1,1,1]
	v_pk_fma_f32 v[30:31], v[230:231], v[254:255], v[30:31] op_sel:[0,1,0] op_sel_hi:[1,1,1]
	s_sub_i32 s90, s90, 1
	s_cmp_eq_u32 s90, 0
	s_cbranch_scc1 .LV_sw4
.LV_t1_s4:
	s_waitcnt lgkmcnt(0)
	buffer_load_dwordx4 v[176:179], v[232:233], s[60:63], 0 idxen offen
	buffer_load_dwordx4 v[180:183], v[234:235], s[60:63], 0 idxen offen
	buffer_load_dwordx4 v[184:187], v[236:237], s[60:63], 0 idxen offen
	buffer_load_dwordx4 v[188:191], v[238:239], s[60:63], 0 idxen offen
	ds_read_b32 v232, v213 offset:144
	ds_read_b32 v234, v213 offset:148
	ds_read_b32 v236, v213 offset:152
	ds_read_b32 v238, v213 offset:156
	ds_read_b128 v[248:251], v213 offset:5072
	s_waitcnt vmcnt(16)
	v_cvt_pk_f32_fp8_e32 v[224:225], v192
	v_cvt_pk_f32_fp8_sdwa v[226:227], v192 src0_sel:WORD_1
	v_cvt_pk_f32_fp8_e32 v[228:229], v193
	v_cvt_pk_f32_fp8_sdwa v[230:231], v193 src0_sel:WORD_1
	v_pk_fma_f32 v[16:17], v[224:225], v[208:209], v[16:17] op_sel_hi:[1,0,1]
	v_pk_fma_f32 v[18:19], v[226:227], v[208:209], v[18:19] op_sel_hi:[1,0,1]
	v_pk_fma_f32 v[20:21], v[228:229], v[208:209], v[20:21] op_sel_hi:[1,0,1]
	v_pk_fma_f32 v[22:23], v[230:231], v[208:209], v[22:23] op_sel_hi:[1,0,1]
	v_cvt_pk_f32_fp8_e32 v[224:225], v194
	v_cvt_pk_f32_fp8_sdwa v[226:227], v194 src0_sel:WORD_1
	v_cvt_pk_f32_fp8_e32 v[228:229], v195
	v_cvt_pk_f32_fp8_sdwa v[230:231], v195 src0_sel:WORD_1
	v_pk_fma_f32 v[24:25], v[224:225], v[208:209], v[24:25] op_sel_hi:[1,0,1]
	v_pk_fma_f32 v[26:27], v[226:227], v[208:209], v[26:27] op_sel_hi:[1,0,1]
	v_pk_fma_f32 v[28:29], v[228:229], v[208:209], v[28:29] op_sel_hi:[1,0,1]
	v_pk_fma_f32 v[30:31], v[230:231], v[208:209], v[30:31] op_sel_hi:[1,0,1]
	v_cvt_pk_f32_fp8_e32 v[224:225], v196
	v_cvt_pk_f32_fp8_sdwa v[226:227], v196 src0_sel:WORD_1
	v_cvt_pk_f32_fp8_e32 v[228:229], v197
	v_cvt_pk_f32_fp8_sdwa v[230:231], v197 src0_sel:WORD_1
	v_pk_fma_f32 v[16:17], v[224:225], v[208:209], v[16:17] op_sel:[0,1,0] op_sel_hi:[1,1,1]
	v_pk_fma_f32 v[18:19], v[226:227], v[208:209], v[18:19] op_sel:[0,1,0] op_sel_hi:[1,1,1]
	v_pk_fma_f32 v[20:21], v[228:229], v[208:209], v[20:21] op_sel:[0,1,0] op_sel_hi:[1,1,1]
	v_pk_fma_f32 v[22:23], v[230:231], v[208:209], v[22:23] op_sel:[0,1,0] op_sel_hi:[1,1,1]
	v_cvt_pk_f32_fp8_e32 v[224:225], v198
	v_cvt_pk_f32_fp8_sdwa v[226:227], v198 src0_sel:WORD_1
	v_cvt_pk_f32_fp8_e32 v[228:229], v199
	v_cvt_pk_f32_fp8_sdwa v[230:231], v199 src0_sel:WORD_1
	v_pk_fma_f32 v[24:25], v[224:225], v[208:209], v[24:25] op_sel:[0,1,0] op_sel_hi:[1,1,1]
	v_pk_fma_f32 v[26:27], v[226:227], v[208:209], v[26:27] op_sel:[0,1,0] op_sel_hi:[1,1,1]
	v_pk_fma_f32 v[28:29], v[228:229], v[208:209], v[28:29] op_sel:[0,1,0] op_sel_hi:[1,1,1]
	v_pk_fma_f32 v[30:31], v[230:231], v[208:209], v[30:31] op_sel:[0,1,0] op_sel_hi:[1,1,1]
	v_cvt_pk_f32_fp8_e32 v[224:225], v200
	v_cvt_pk_f32_fp8_sdwa v[226:227], v200 src0_sel:WORD_1
	v_cvt_pk_f32_fp8_e32 v[228:229], v201
	v_cvt_pk_f32_fp8_sdwa v[230:231], v201 src0_sel:WORD_1
	v_pk_fma_f32 v[16:17], v[224:225], v[210:211], v[16:17] op_sel_hi:[1,0,1]
	v_pk_fma_f32 v[18:19], v[226:227], v[210:211], v[18:19] op_sel_hi:[1,0,1]
	v_pk_fma_f32 v[20:21], v[228:229], v[210:211], v[20:21] op_sel_hi:[1,0,1]
	v_pk_fma_f32 v[22:23], v[230:231], v[210:211], v[22:23] op_sel_hi:[1,0,1]
	v_cvt_pk_f32_fp8_e32 v[224:225], v202
	v_cvt_pk_f32_fp8_sdwa v[226:227], v202 src0_sel:WORD_1
	v_cvt_pk_f32_fp8_e32 v[228:229], v203
	v_cvt_pk_f32_fp8_sdwa v[230:231], v203 src0_sel:WORD_1
	v_pk_fma_f32 v[24:25], v[224:225], v[210:211], v[24:25] op_sel_hi:[1,0,1]
	v_pk_fma_f32 v[26:27], v[226:227], v[210:211], v[26:27] op_sel_hi:[1,0,1]
	v_pk_fma_f32 v[28:29], v[228:229], v[210:211], v[28:29] op_sel_hi:[1,0,1]
	v_pk_fma_f32 v[30:31], v[230:231], v[210:211], v[30:31] op_sel_hi:[1,0,1]
	v_cvt_pk_f32_fp8_e32 v[224:225], v204
	v_cvt_pk_f32_fp8_sdwa v[226:227], v204 src0_sel:WORD_1
	v_cvt_pk_f32_fp8_e32 v[228:229], v205
	v_cvt_pk_f32_fp8_sdwa v[230:231], v205 src0_sel:WORD_1
	v_pk_fma_f32 v[16:17], v[224:225], v[210:211], v[16:17] op_sel:[0,1,0] op_sel_hi:[1,1,1]
	v_pk_fma_f32 v[18:19], v[226:227], v[210:211], v[18:19] op_sel:[0,1,0] op_sel_hi:[1,1,1]
	v_pk_fma_f32 v[20:21], v[228:229], v[210:211], v[20:21] op_sel:[0,1,0] op_sel_hi:[1,1,1]
	v_pk_fma_f32 v[22:23], v[230:231], v[210:211], v[22:23] op_sel:[0,1,0] op_sel_hi:[1,1,1]
	v_cvt_pk_f32_fp8_e32 v[224:225], v206
	v_cvt_pk_f32_fp8_sdwa v[226:227], v206 src0_sel:WORD_1
	v_cvt_pk_f32_fp8_e32 v[228:229], v207
	v_cvt_pk_f32_fp8_sdwa v[230:231], v207 src0_sel:WORD_1
	v_pk_fma_f32 v[24:25], v[224:225], v[210:211], v[24:25] op_sel:[0,1,0] op_sel_hi:[1,1,1]
	v_pk_fma_f32 v[26:27], v[226:227], v[210:211], v[26:27] op_sel:[0,1,0] op_sel_hi:[1,1,1]
	v_pk_fma_f32 v[28:29], v[228:229], v[210:211], v[28:29] op_sel:[0,1,0] op_sel_hi:[1,1,1]
	v_pk_fma_f32 v[30:31], v[230:231], v[210:211], v[30:31] op_sel:[0,1,0] op_sel_hi:[1,1,1]
	v_add_u32_e32 v213, 80, v213
	s_add_i32 s21, s21, 5
	s_sub_i32 s90, s90, 1
	s_cmp_eq_u32 s90, 0
	s_cbranch_scc1 .LV_sw0
	s_branch .LV_t1_s0
.LV_t2_s0:
	s_cmp_ge_u32 s21, s20
	s_cbranch_scc1 .LV_done
	s_waitcnt lgkmcnt(0)
	buffer_load_dwordx4 v[192:195], v[232:233], s[60:63], 0 idxen offen
	buffer_load_dwordx4 v[196:199], v[234:235], s[60:63], 0 idxen offen
	buffer_load_dwordx4 v[200:203], v[236:237], s[60:63], 0 idxen offen
	buffer_load_dwordx4 v[204:207], v[238:239], s[60:63], 0 idxen offen
	ds_read_b32 v232, v213 offset:80
	ds_read_b32 v234, v213 offset:84
	ds_read_b32 v236, v213 offset:88
	ds_read_b32 v238, v213 offset:92
	ds_read_b128 v[252:255], v213 offset:5008
	s_waitcnt vmcnt(16)
	v_cvt_pk_f32_fp8_e32 v[224:225], v128
	v_cvt_pk_f32_fp8_sdwa v[226:227], v128 src0_sel:WORD_1
	v_cvt_pk_f32_fp8_e32 v[228:229], v129
	v_cvt_pk_f32_fp8_sdwa v[230:231], v129 src0_sel:WORD_1
	v_pk_fma_f32 v[32:33], v[224:225], v[248:249], v[32:33] op_sel_hi:[1,0,1]
	v_pk_fma_f32 v[34:35], v[226:227], v[248:249], v[34:35] op_sel_hi:[1,0,1]
	v_pk_fma_f32 v[36:37], v[228:229], v[248:249], v[36:37] op_sel_hi:[1,0,1]
	v_pk_fma_f32 v[38:39], v[230:231], v[248:249], v[38:39] op_sel_hi:[1,0,1]
	v_cvt_pk_f32_fp8_e32 v[224:225], v130
	v_cvt_pk_f32_fp8_sdwa v[226:227], v130 src0_sel:WORD_1
	v_cvt_pk_f32_fp8_e32 v[228:229], v131
	v_cvt_pk_f32_fp8_sdwa v[230:231], v131 src0_sel:WORD_1
	v_pk_fma_f32 v[40:41], v[224:225], v[248:249], v[40:41] op_sel_hi:[1,0,1]
	v_pk_fma_f32 v[42:43], v[226:227], v[248:249], v[42:43] op_sel_hi:[1,0,1]
	v_pk_fma_f32 v[44:45], v[228:229], v[248:249], v[44:45] op_sel_hi:[1,0,1]
	v_pk_fma_f32 v[46:47], v[230:231], v[248:249], v[46:47] op_sel_hi:[1,0,1]
	v_cvt_pk_f32_fp8_e32 v[224:225], v132
	v_cvt_pk_f32_fp8_sdwa v[226:227], v132 src0_sel:WORD_1
	v_cvt_pk_f32_fp8_e32 v[228:229], v133
	v_cvt_pk_f32_fp8_sdwa v[230:231], v133 src0_sel:WORD_1
	v_pk_fma_f32 v[32:33], v[224:225], v[248:249], v[32:33] op_sel:[0,1,0] op_sel_hi:[1,1,1]
	v_pk_fma_f32 v[34:35], v[226:227], v[248:249], v[34:35] op_sel:[0,1,0] op_sel_hi:[1,1,1]
	v_pk_fma_f32 v[36:37], v[228:229], v[248:249], v[36:37] op_sel:[0,1,0] op_sel_hi:[1,1,1]
	v_pk_fma_f32 v[38:39], v[230:231], v[248:249], v[38:39] op_sel:[0,1,0] op_sel_hi:[1,1,1]
	v_cvt_pk_f32_fp8_e32 v[224:225], v134
	v_cvt_pk_f32_fp8_sdwa v[226:227], v134 src0_sel:WORD_1
	v_cvt_pk_f32_fp8_e32 v[228:229], v135
	v_cvt_pk_f32_fp8_sdwa v[230:231], v135 src0_sel:WORD_1
	v_pk_fma_f32 v[40:41], v[224:225], v[248:249], v[40:41] op_sel:[0,1,0] op_sel_hi:[1,1,1]
	v_pk_fma_f32 v[42:43], v[226:227], v[248:249], v[42:43] op_sel:[0,1,0] op_sel_hi:[1,1,1]
	v_pk_fma_f32 v[44:45], v[228:229], v[248:249], v[44:45] op_sel:[0,1,0] op_sel_hi:[1,1,1]
	v_pk_fma_f32 v[46:47], v[230:231], v[248:249], v[46:47] op_sel:[0,1,0] op_sel_hi:[1,1,1]
	v_cvt_pk_f32_fp8_e32 v[224:225], v136
	v_cvt_pk_f32_fp8_sdwa v[226:227], v136 src0_sel:WORD_1
	v_cvt_pk_f32_fp8_e32 v[228:229], v137
	v_cvt_pk_f32_fp8_sdwa v[230:231], v137 src0_sel:WORD_1
	v_pk_fma_f32 v[32:33], v[224:225], v[250:251], v[32:33] op_sel_hi:[1,0,1]
	v_pk_fma_f32 v[34:35], v[226:227], v[250:251], v[34:35] op_sel_hi:[1,0,1]
	v_pk_fma_f32 v[36:37], v[228:229], v[250:251], v[36:37] op_sel_hi:[1,0,1]
	v_pk_fma_f32 v[38:39], v[230:231], v[250:251], v[38:39] op_sel_hi:[1,0,1]
	v_cvt_pk_f32_fp8_e32 v[224:225], v138
	v_cvt_pk_f32_fp8_sdwa v[226:227], v138 src0_sel:WORD_1
	v_cvt_pk_f32_fp8_e32 v[228:229], v139
	v_cvt_pk_f32_fp8_sdwa v[230:231], v139 src0_sel:WORD_1
	v_pk_fma_f32 v[40:41], v[224:225], v[250:251], v[40:41] op_sel_hi:[1,0,1]
	v_pk_fma_f32 v[42:43], v[226:227], v[250:251], v[42:43] op_sel_hi:[1,0,1]
	v_pk_fma_f32 v[44:45], v[228:229], v[250:251], v[44:45] op_sel_hi:[1,0,1]
	v_pk_fma_f32 v[46:47], v[230:231], v[250:251], v[46:47] op_sel_hi:[1,0,1]
	v_cvt_pk_f32_fp8_e32 v[224:225], v140
	v_cvt_pk_f32_fp8_sdwa v[226:227], v140 src0_sel:WORD_1
	v_cvt_pk_f32_fp8_e32 v[228:229], v141
	v_cvt_pk_f32_fp8_sdwa v[230:231], v141 src0_sel:WORD_1
	v_pk_fma_f32 v[32:33], v[224:225], v[250:251], v[32:33] op_sel:[0,1,0] op_sel_hi:[1,1,1]
	v_pk_fma_f32 v[34:35], v[226:227], v[250:251], v[34:35] op_sel:[0,1,0] op_sel_hi:[1,1,1]
	v_pk_fma_f32 v[36:37], v[228:229], v[250:251], v[36:37] op_sel:[0,1,0] op_sel_hi:[1,1,1]
	v_pk_fma_f32 v[38:39], v[230:231], v[250:251], v[38:39] op_sel:[0,1,0] op_sel_hi:[1,1,1]
	v_cvt_pk_f32_fp8_e32 v[224:225], v142
	v_cvt_pk_f32_fp8_sdwa v[226:227], v142 src0_sel:WORD_1
	v_cvt_pk_f32_fp8_e32 v[228:229], v143
	v_cvt_pk_f32_fp8_sdwa v[230:231], v143 src0_sel:WORD_1
	v_pk_fma_f32 v[40:41], v[224:225], v[250:251], v[40:41] op_sel:[0,1,0] op_sel_hi:[1,1,1]
	v_pk_fma_f32 v[42:43], v[226:227], v[250:251], v[42:43] op_sel:[0,1,0] op_sel_hi:[1,1,1]
	v_pk_fma_f32 v[44:45], v[228:229], v[250:251], v[44:45] op_sel:[0,1,0] op_sel_hi:[1,1,1]
	v_pk_fma_f32 v[46:47], v[230:231], v[250:251], v[46:47] op_sel:[0,1,0] op_sel_hi:[1,1,1]
	s_sub_i32 s90, s90, 1
	s_cmp_eq_u32 s90, 0
	s_cbranch_scc1 .LV_sw1
.LV_t2_s1:
	s_waitcnt lgkmcnt(0)
	buffer_load_dwordx4 v[128:131], v[232:233], s[60:63], 0 idxen offen
	buffer_load_dwordx4 v[132:135], v[234:235], s[60:63], 0 idxen offen
	buffer_load_dwordx4 v[136:139], v[236:237], s[60:63], 0 idxen offen
	buffer_load_dwordx4 v[140:143], v[238:239], s[60:63], 0 idxen offen
	ds_read_b32 v232, v213 offset:96
	ds_read_b32 v234, v213 offset:100
	ds_read_b32 v236, v213 offset:104
	ds_read_b32 v238, v213 offset:108
	ds_read_b128 v[248:251], v213 offset:5024
	s_waitcnt vmcnt(16)
	v_cvt_pk_f32_fp8_e32 v[224:225], v144
	v_cvt_pk_f32_fp8_sdwa v[226:227], v144 src0_sel:WORD_1
	v_cvt_pk_f32_fp8_e32 v[228:229], v145
	v_cvt_pk_f32_fp8_sdwa v[230:231], v145 src0_sel:WORD_1
	v_pk_fma_f32 v[32:33], v[224:225], v[252:253], v[32:33] op_sel_hi:[1,0,1]
	v_pk_fma_f32 v[34:35], v[226:227], v[252:253], v[34:35] op_sel_hi:[1,0,1]
	v_pk_fma_f32 v[36:37], v[228:229], v[252:253], v[36:37] op_sel_hi:[1,0,1]
	v_pk_fma_f32 v[38:39], v[230:231], v[252:253], v[38:39] op_sel_hi:[1,0,1]
	v_cvt_pk_f32_fp8_e32 v[224:225], v146
	v_cvt_pk_f32_fp8_sdwa v[226:227], v146 src0_sel:WORD_1
	v_cvt_pk_f32_fp8_e32 v[228:229], v147
	v_cvt_pk_f32_fp8_sdwa v[230:231], v147 src0_sel:WORD_1
	v_pk_fma_f32 v[40:41], v[224:225], v[252:253], v[40:41] op_sel_hi:[1,0,1]
	v_pk_fma_f32 v[42:43], v[226:227], v[252:253], v[42:43] op_sel_hi:[1,0,1]
	v_pk_fma_f32 v[44:45], v[228:229], v[252:253], v[44:45] op_sel_hi:[1,0,1]
	v_pk_fma_f32 v[46:47], v[230:231], v[252:253], v[46:47] op_sel_hi:[1,0,1]
	v_cvt_pk_f32_fp8_e32 v[224:225], v148
	v_cvt_pk_f32_fp8_sdwa v[226:227], v148 src0_sel:WORD_1
	v_cvt_pk_f32_fp8_e32 v[228:229], v149
	v_cvt_pk_f32_fp8_sdwa v[230:231], v149 src0_sel:WORD_1
	v_pk_fma_f32 v[32:33], v[224:225], v[252:253], v[32:33] op_sel:[0,1,0] op_sel_hi:[1,1,1]
	v_pk_fma_f32 v[34:35], v[226:227], v[252:253], v[34:35] op_sel:[0,1,0] op_sel_hi:[1,1,1]
	v_pk_fma_f32 v[36:37], v[228:229], v[252:253], v[36:37] op_sel:[0,1,0] op_sel_hi:[1,1,1]
	v_pk_fma_f32 v[38:39], v[230:231], v[252:253], v[38:39] op_sel:[0,1,0] op_sel_hi:[1,1,1]
	v_cvt_pk_f32_fp8_e32 v[224:225], v150
	v_cvt_pk_f32_fp8_sdwa v[226:227], v150 src0_sel:WORD_1
	v_cvt_pk_f32_fp8_e32 v[228:229], v151
	v_cvt_pk_f32_fp8_sdwa v[230:231], v151 src0_sel:WORD_1
	v_pk_fma_f32 v[40:41], v[224:225], v[252:253], v[40:41] op_sel:[0,1,0] op_sel_hi:[1,1,1]
	v_pk_fma_f32 v[42:43], v[226:227], v[252:253], v[42:43] op_sel:[0,1,0] op_sel_hi:[1,1,1]
	v_pk_fma_f32 v[44:45], v[228:229], v[252:253], v[44:45] op_sel:[0,1,0] op_sel_hi:[1,1,1]
	v_pk_fma_f32 v[46:47], v[230:231], v[252:253], v[46:47] op_sel:[0,1,0] op_sel_hi:[1,1,1]
	v_cvt_pk_f32_fp8_e32 v[224:225], v152
	v_cvt_pk_f32_fp8_sdwa v[226:227], v152 src0_sel:WORD_1
	v_cvt_pk_f32_fp8_e32 v[228:229], v153
	v_cvt_pk_f32_fp8_sdwa v[230:231], v153 src0_sel:WORD_1
	v_pk_fma_f32 v[32:33], v[224:225], v[254:255], v[32:33] op_sel_hi:[1,0,1]
	v_pk_fma_f32 v[34:35], v[226:227], v[254:255], v[34:35] op_sel_hi:[1,0,1]
	v_pk_fma_f32 v[36:37], v[228:229], v[254:255], v[36:37] op_sel_hi:[1,0,1]
	v_pk_fma_f32 v[38:39], v[230:231], v[254:255], v[38:39] op_sel_hi:[1,0,1]
	v_cvt_pk_f32_fp8_e32 v[224:225], v154
	v_cvt_pk_f32_fp8_sdwa v[226:227], v154 src0_sel:WORD_1
	v_cvt_pk_f32_fp8_e32 v[228:229], v155
	v_cvt_pk_f32_fp8_sdwa v[230:231], v155 src0_sel:WORD_1
	v_pk_fma_f32 v[40:41], v[224:225], v[254:255], v[40:41] op_sel_hi:[1,0,1]
	v_pk_fma_f32 v[42:43], v[226:227], v[254:255], v[42:43] op_sel_hi:[1,0,1]
	v_pk_fma_f32 v[44:45], v[228:229], v[254:255], v[44:45] op_sel_hi:[1,0,1]
	v_pk_fma_f32 v[46:47], v[230:231], v[254:255], v[46:47] op_sel_hi:[1,0,1]
	v_cvt_pk_f32_fp8_e32 v[224:225], v156
	v_cvt_pk_f32_fp8_sdwa v[226:227], v156 src0_sel:WORD_1
	v_cvt_pk_f32_fp8_e32 v[228:229], v157
	v_cvt_pk_f32_fp8_sdwa v[230:231], v157 src0_sel:WORD_1
	v_pk_fma_f32 v[32:33], v[224:225], v[254:255], v[32:33] op_sel:[0,1,0] op_sel_hi:[1,1,1]
	v_pk_fma_f32 v[34:35], v[226:227], v[254:255], v[34:35] op_sel:[0,1,0] op_sel_hi:[1,1,1]
	v_pk_fma_f32 v[36:37], v[228:229], v[254:255], v[36:37] op_sel:[0,1,0] op_sel_hi:[1,1,1]
	v_pk_fma_f32 v[38:39], v[230:231], v[254:255], v[38:39] op_sel:[0,1,0] op_sel_hi:[1,1,1]
	v_cvt_pk_f32_fp8_e32 v[224:225], v158
	v_cvt_pk_f32_fp8_sdwa v[226:227], v158 src0_sel:WORD_1
	v_cvt_pk_f32_fp8_e32 v[228:229], v159
	v_cvt_pk_f32_fp8_sdwa v[230:231], v159 src0_sel:WORD_1
	v_pk_fma_f32 v[40:41], v[224:225], v[254:255], v[40:41] op_sel:[0,1,0] op_sel_hi:[1,1,1]
	v_pk_fma_f32 v[42:43], v[226:227], v[254:255], v[42:43] op_sel:[0,1,0] op_sel_hi:[1,1,1]
	v_pk_fma_f32 v[44:45], v[228:229], v[254:255], v[44:45] op_sel:[0,1,0] op_sel_hi:[1,1,1]
	v_pk_fma_f32 v[46:47], v[230:231], v[254:255], v[46:47] op_sel:[0,1,0] op_sel_hi:[1,1,1]
	s_sub_i32 s90, s90, 1
	s_cmp_eq_u32 s90, 0
	s_cbranch_scc1 .LV_sw2
.LV_t2_s2:
	s_waitcnt lgkmcnt(0)
	buffer_load_dwordx4 v[144:147], v[232:233], s[60:63], 0 idxen offen
	buffer_load_dwordx4 v[148:151], v[234:235], s[60:63], 0 idxen offen
	buffer_load_dwordx4 v[152:155], v[236:237], s[60:63], 0 idxen offen
	buffer_load_dwordx4 v[156:159], v[238:239], s[60:63], 0 idxen offen
	ds_read_b32 v232, v213 offset:112
	ds_read_b32 v234, v213 offset:116
	ds_read_b32 v236, v213 offset:120
	ds_read_b32 v238, v213 offset:124
	ds_read_b128 v[252:255], v213 offset:5040
	s_waitcnt vmcnt(16)
	v_cvt_pk_f32_fp8_e32 v[224:225], v160
	v_cvt_pk_f32_fp8_sdwa v[226:227], v160 src0_sel:WORD_1
	v_cvt_pk_f32_fp8_e32 v[228:229], v161
	v_cvt_pk_f32_fp8_sdwa v[230:231], v161 src0_sel:WORD_1
	v_pk_fma_f32 v[32:33], v[224:225], v[248:249], v[32:33] op_sel_hi:[1,0,1]
	v_pk_fma_f32 v[34:35], v[226:227], v[248:249], v[34:35] op_sel_hi:[1,0,1]
	v_pk_fma_f32 v[36:37], v[228:229], v[248:249], v[36:37] op_sel_hi:[1,0,1]
	v_pk_fma_f32 v[38:39], v[230:231], v[248:249], v[38:39] op_sel_hi:[1,0,1]
	v_cvt_pk_f32_fp8_e32 v[224:225], v162
	v_cvt_pk_f32_fp8_sdwa v[226:227], v162 src0_sel:WORD_1
	v_cvt_pk_f32_fp8_e32 v[228:229], v163
	v_cvt_pk_f32_fp8_sdwa v[230:231], v163 src0_sel:WORD_1
	v_pk_fma_f32 v[40:41], v[224:225], v[248:249], v[40:41] op_sel_hi:[1,0,1]
	v_pk_fma_f32 v[42:43], v[226:227], v[248:249], v[42:43] op_sel_hi:[1,0,1]
	v_pk_fma_f32 v[44:45], v[228:229], v[248:249], v[44:45] op_sel_hi:[1,0,1]
	v_pk_fma_f32 v[46:47], v[230:231], v[248:249], v[46:47] op_sel_hi:[1,0,1]
	v_cvt_pk_f32_fp8_e32 v[224:225], v164
	v_cvt_pk_f32_fp8_sdwa v[226:227], v164 src0_sel:WORD_1
	v_cvt_pk_f32_fp8_e32 v[228:229], v165
	v_cvt_pk_f32_fp8_sdwa v[230:231], v165 src0_sel:WORD_1
	v_pk_fma_f32 v[32:33], v[224:225], v[248:249], v[32:33] op_sel:[0,1,0] op_sel_hi:[1,1,1]
	v_pk_fma_f32 v[34:35], v[226:227], v[248:249], v[34:35] op_sel:[0,1,0] op_sel_hi:[1,1,1]
	v_pk_fma_f32 v[36:37], v[228:229], v[248:249], v[36:37] op_sel:[0,1,0] op_sel_hi:[1,1,1]
	v_pk_fma_f32 v[38:39], v[230:231], v[248:249], v[38:39] op_sel:[0,1,0] op_sel_hi:[1,1,1]
	v_cvt_pk_f32_fp8_e32 v[224:225], v166
	v_cvt_pk_f32_fp8_sdwa v[226:227], v166 src0_sel:WORD_1
	v_cvt_pk_f32_fp8_e32 v[228:229], v167
	v_cvt_pk_f32_fp8_sdwa v[230:231], v167 src0_sel:WORD_1
	v_pk_fma_f32 v[40:41], v[224:225], v[248:249], v[40:41] op_sel:[0,1,0] op_sel_hi:[1,1,1]
	v_pk_fma_f32 v[42:43], v[226:227], v[248:249], v[42:43] op_sel:[0,1,0] op_sel_hi:[1,1,1]
	v_pk_fma_f32 v[44:45], v[228:229], v[248:249], v[44:45] op_sel:[0,1,0] op_sel_hi:[1,1,1]
	v_pk_fma_f32 v[46:47], v[230:231], v[248:249], v[46:47] op_sel:[0,1,0] op_sel_hi:[1,1,1]
	v_cvt_pk_f32_fp8_e32 v[224:225], v168
	v_cvt_pk_f32_fp8_sdwa v[226:227], v168 src0_sel:WORD_1
	v_cvt_pk_f32_fp8_e32 v[228:229], v169
	v_cvt_pk_f32_fp8_sdwa v[230:231], v169 src0_sel:WORD_1
	v_pk_fma_f32 v[32:33], v[224:225], v[250:251], v[32:33] op_sel_hi:[1,0,1]
	v_pk_fma_f32 v[34:35], v[226:227], v[250:251], v[34:35] op_sel_hi:[1,0,1]
	v_pk_fma_f32 v[36:37], v[228:229], v[250:251], v[36:37] op_sel_hi:[1,0,1]
	v_pk_fma_f32 v[38:39], v[230:231], v[250:251], v[38:39] op_sel_hi:[1,0,1]
	v_cvt_pk_f32_fp8_e32 v[224:225], v170
	v_cvt_pk_f32_fp8_sdwa v[226:227], v170 src0_sel:WORD_1
	v_cvt_pk_f32_fp8_e32 v[228:229], v171
	v_cvt_pk_f32_fp8_sdwa v[230:231], v171 src0_sel:WORD_1
	v_pk_fma_f32 v[40:41], v[224:225], v[250:251], v[40:41] op_sel_hi:[1,0,1]
	v_pk_fma_f32 v[42:43], v[226:227], v[250:251], v[42:43] op_sel_hi:[1,0,1]
	v_pk_fma_f32 v[44:45], v[228:229], v[250:251], v[44:45] op_sel_hi:[1,0,1]
	v_pk_fma_f32 v[46:47], v[230:231], v[250:251], v[46:47] op_sel_hi:[1,0,1]
	v_cvt_pk_f32_fp8_e32 v[224:225], v172
	v_cvt_pk_f32_fp8_sdwa v[226:227], v172 src0_sel:WORD_1
	v_cvt_pk_f32_fp8_e32 v[228:229], v173
	v_cvt_pk_f32_fp8_sdwa v[230:231], v173 src0_sel:WORD_1
	v_pk_fma_f32 v[32:33], v[224:225], v[250:251], v[32:33] op_sel:[0,1,0] op_sel_hi:[1,1,1]
	v_pk_fma_f32 v[34:35], v[226:227], v[250:251], v[34:35] op_sel:[0,1,0] op_sel_hi:[1,1,1]
	v_pk_fma_f32 v[36:37], v[228:229], v[250:251], v[36:37] op_sel:[0,1,0] op_sel_hi:[1,1,1]
	v_pk_fma_f32 v[38:39], v[230:231], v[250:251], v[38:39] op_sel:[0,1,0] op_sel_hi:[1,1,1]
	v_cvt_pk_f32_fp8_e32 v[224:225], v174
	v_cvt_pk_f32_fp8_sdwa v[226:227], v174 src0_sel:WORD_1
	v_cvt_pk_f32_fp8_e32 v[228:229], v175
	v_cvt_pk_f32_fp8_sdwa v[230:231], v175 src0_sel:WORD_1
	v_pk_fma_f32 v[40:41], v[224:225], v[250:251], v[40:41] op_sel:[0,1,0] op_sel_hi:[1,1,1]
	v_pk_fma_f32 v[42:43], v[226:227], v[250:251], v[42:43] op_sel:[0,1,0] op_sel_hi:[1,1,1]
	v_pk_fma_f32 v[44:45], v[228:229], v[250:251], v[44:45] op_sel:[0,1,0] op_sel_hi:[1,1,1]
	v_pk_fma_f32 v[46:47], v[230:231], v[250:251], v[46:47] op_sel:[0,1,0] op_sel_hi:[1,1,1]
	s_sub_i32 s90, s90, 1
	s_cmp_eq_u32 s90, 0
	s_cbranch_scc1 .LV_sw3
.LV_t2_s3:
	s_waitcnt lgkmcnt(0)
	buffer_load_dwordx4 v[160:163], v[232:233], s[60:63], 0 idxen offen
	buffer_load_dwordx4 v[164:167], v[234:235], s[60:63], 0 idxen offen
	buffer_load_dwordx4 v[168:171], v[236:237], s[60:63], 0 idxen offen
	buffer_load_dwordx4 v[172:175], v[238:239], s[60:63], 0 idxen offen
	ds_read_b32 v232, v213 offset:128
	ds_read_b32 v234, v213 offset:132
	ds_read_b32 v236, v213 offset:136
	ds_read_b32 v238, v213 offset:140
	ds_read_b128 v[208:211], v213 offset:5056
	s_waitcnt vmcnt(16)
	v_cvt_pk_f32_fp8_e32 v[224:225], v176
	v_cvt_pk_f32_fp8_sdwa v[226:227], v176 src0_sel:WORD_1
	v_cvt_pk_f32_fp8_e32 v[228:229], v177
	v_cvt_pk_f32_fp8_sdwa v[230:231], v177 src0_sel:WORD_1
	v_pk_fma_f32 v[32:33], v[224:225], v[252:253], v[32:33] op_sel_hi:[1,0,1]
	v_pk_fma_f32 v[34:35], v[226:227], v[252:253], v[34:35] op_sel_hi:[1,0,1]
	v_pk_fma_f32 v[36:37], v[228:229], v[252:253], v[36:37] op_sel_hi:[1,0,1]
	v_pk_fma_f32 v[38:39], v[230:231], v[252:253], v[38:39] op_sel_hi:[1,0,1]
	v_cvt_pk_f32_fp8_e32 v[224:225], v178
	v_cvt_pk_f32_fp8_sdwa v[226:227], v178 src0_sel:WORD_1
	v_cvt_pk_f32_fp8_e32 v[228:229], v179
	v_cvt_pk_f32_fp8_sdwa v[230:231], v179 src0_sel:WORD_1
	v_pk_fma_f32 v[40:41], v[224:225], v[252:253], v[40:41] op_sel_hi:[1,0,1]
	v_pk_fma_f32 v[42:43], v[226:227], v[252:253], v[42:43] op_sel_hi:[1,0,1]
	v_pk_fma_f32 v[44:45], v[228:229], v[252:253], v[44:45] op_sel_hi:[1,0,1]
	v_pk_fma_f32 v[46:47], v[230:231], v[252:253], v[46:47] op_sel_hi:[1,0,1]
	v_cvt_pk_f32_fp8_e32 v[224:225], v180
	v_cvt_pk_f32_fp8_sdwa v[226:227], v180 src0_sel:WORD_1
	v_cvt_pk_f32_fp8_e32 v[228:229], v181
	v_cvt_pk_f32_fp8_sdwa v[230:231], v181 src0_sel:WORD_1
	v_pk_fma_f32 v[32:33], v[224:225], v[252:253], v[32:33] op_sel:[0,1,0] op_sel_hi:[1,1,1]
	v_pk_fma_f32 v[34:35], v[226:227], v[252:253], v[34:35] op_sel:[0,1,0] op_sel_hi:[1,1,1]
	v_pk_fma_f32 v[36:37], v[228:229], v[252:253], v[36:37] op_sel:[0,1,0] op_sel_hi:[1,1,1]
	v_pk_fma_f32 v[38:39], v[230:231], v[252:253], v[38:39] op_sel:[0,1,0] op_sel_hi:[1,1,1]
	v_cvt_pk_f32_fp8_e32 v[224:225], v182
	v_cvt_pk_f32_fp8_sdwa v[226:227], v182 src0_sel:WORD_1
	v_cvt_pk_f32_fp8_e32 v[228:229], v183
	v_cvt_pk_f32_fp8_sdwa v[230:231], v183 src0_sel:WORD_1
	v_pk_fma_f32 v[40:41], v[224:225], v[252:253], v[40:41] op_sel:[0,1,0] op_sel_hi:[1,1,1]
	v_pk_fma_f32 v[42:43], v[226:227], v[252:253], v[42:43] op_sel:[0,1,0] op_sel_hi:[1,1,1]
	v_pk_fma_f32 v[44:45], v[228:229], v[252:253], v[44:45] op_sel:[0,1,0] op_sel_hi:[1,1,1]
	v_pk_fma_f32 v[46:47], v[230:231], v[252:253], v[46:47] op_sel:[0,1,0] op_sel_hi:[1,1,1]
	v_cvt_pk_f32_fp8_e32 v[224:225], v184
	v_cvt_pk_f32_fp8_sdwa v[226:227], v184 src0_sel:WORD_1
	v_cvt_pk_f32_fp8_e32 v[228:229], v185
	v_cvt_pk_f32_fp8_sdwa v[230:231], v185 src0_sel:WORD_1
	v_pk_fma_f32 v[32:33], v[224:225], v[254:255], v[32:33] op_sel_hi:[1,0,1]
	v_pk_fma_f32 v[34:35], v[226:227], v[254:255], v[34:35] op_sel_hi:[1,0,1]
	v_pk_fma_f32 v[36:37], v[228:229], v[254:255], v[36:37] op_sel_hi:[1,0,1]
	v_pk_fma_f32 v[38:39], v[230:231], v[254:255], v[38:39] op_sel_hi:[1,0,1]
	v_cvt_pk_f32_fp8_e32 v[224:225], v186
	v_cvt_pk_f32_fp8_sdwa v[226:227], v186 src0_sel:WORD_1
	v_cvt_pk_f32_fp8_e32 v[228:229], v187
	v_cvt_pk_f32_fp8_sdwa v[230:231], v187 src0_sel:WORD_1
	v_pk_fma_f32 v[40:41], v[224:225], v[254:255], v[40:41] op_sel_hi:[1,0,1]
	v_pk_fma_f32 v[42:43], v[226:227], v[254:255], v[42:43] op_sel_hi:[1,0,1]
	v_pk_fma_f32 v[44:45], v[228:229], v[254:255], v[44:45] op_sel_hi:[1,0,1]
	v_pk_fma_f32 v[46:47], v[230:231], v[254:255], v[46:47] op_sel_hi:[1,0,1]
	v_cvt_pk_f32_fp8_e32 v[224:225], v188
	v_cvt_pk_f32_fp8_sdwa v[226:227], v188 src0_sel:WORD_1
	v_cvt_pk_f32_fp8_e32 v[228:229], v189
	v_cvt_pk_f32_fp8_sdwa v[230:231], v189 src0_sel:WORD_1
	v_pk_fma_f32 v[32:33], v[224:225], v[254:255], v[32:33] op_sel:[0,1,0] op_sel_hi:[1,1,1]
	v_pk_fma_f32 v[34:35], v[226:227], v[254:255], v[34:35] op_sel:[0,1,0] op_sel_hi:[1,1,1]
	v_pk_fma_f32 v[36:37], v[228:229], v[254:255], v[36:37] op_sel:[0,1,0] op_sel_hi:[1,1,1]
	v_pk_fma_f32 v[38:39], v[230:231], v[254:255], v[38:39] op_sel:[0,1,0] op_sel_hi:[1,1,1]
	v_cvt_pk_f32_fp8_e32 v[224:225], v190
	v_cvt_pk_f32_fp8_sdwa v[226:227], v190 src0_sel:WORD_1
	v_cvt_pk_f32_fp8_e32 v[228:229], v191
	v_cvt_pk_f32_fp8_sdwa v[230:231], v191 src0_sel:WORD_1
	v_pk_fma_f32 v[40:41], v[224:225], v[254:255], v[40:41] op_sel:[0,1,0] op_sel_hi:[1,1,1]
	v_pk_fma_f32 v[42:43], v[226:227], v[254:255], v[42:43] op_sel:[0,1,0] op_sel_hi:[1,1,1]
	v_pk_fma_f32 v[44:45], v[228:229], v[254:255], v[44:45] op_sel:[0,1,0] op_sel_hi:[1,1,1]
	v_pk_fma_f32 v[46:47], v[230:231], v[254:255], v[46:47] op_sel:[0,1,0] op_sel_hi:[1,1,1]
	s_sub_i32 s90, s90, 1
	s_cmp_eq_u32 s90, 0
	s_cbranch_scc1 .LV_sw4
.LV_t2_s4:
	s_waitcnt lgkmcnt(0)
	buffer_load_dwordx4 v[176:179], v[232:233], s[60:63], 0 idxen offen
	buffer_load_dwordx4 v[180:183], v[234:235], s[60:63], 0 idxen offen
	buffer_load_dwordx4 v[184:187], v[236:237], s[60:63], 0 idxen offen
	buffer_load_dwordx4 v[188:191], v[238:239], s[60:63], 0 idxen offen
	ds_read_b32 v232, v213 offset:144
	ds_read_b32 v234, v213 offset:148
	ds_read_b32 v236, v213 offset:152
	ds_read_b32 v238, v213 offset:156
	ds_read_b128 v[248:251], v213 offset:5072
	s_waitcnt vmcnt(16)
	v_cvt_pk_f32_fp8_e32 v[224:225], v192
	v_cvt_pk_f32_fp8_sdwa v[226:227], v192 src0_sel:WORD_1
	v_cvt_pk_f32_fp8_e32 v[228:229], v193
	v_cvt_pk_f32_fp8_sdwa v[230:231], v193 src0_sel:WORD_1
	v_pk_fma_f32 v[32:33], v[224:225], v[208:209], v[32:33] op_sel_hi:[1,0,1]
	v_pk_fma_f32 v[34:35], v[226:227], v[208:209], v[34:35] op_sel_hi:[1,0,1]
	v_pk_fma_f32 v[36:37], v[228:229], v[208:209], v[36:37] op_sel_hi:[1,0,1]
	v_pk_fma_f32 v[38:39], v[230:231], v[208:209], v[38:39] op_sel_hi:[1,0,1]
	v_cvt_pk_f32_fp8_e32 v[224:225], v194
	v_cvt_pk_f32_fp8_sdwa v[226:227], v194 src0_sel:WORD_1
	v_cvt_pk_f32_fp8_e32 v[228:229], v195
	v_cvt_pk_f32_fp8_sdwa v[230:231], v195 src0_sel:WORD_1
	v_pk_fma_f32 v[40:41], v[224:225], v[208:209], v[40:41] op_sel_hi:[1,0,1]
	v_pk_fma_f32 v[42:43], v[226:227], v[208:209], v[42:43] op_sel_hi:[1,0,1]
	v_pk_fma_f32 v[44:45], v[228:229], v[208:209], v[44:45] op_sel_hi:[1,0,1]
	v_pk_fma_f32 v[46:47], v[230:231], v[208:209], v[46:47] op_sel_hi:[1,0,1]
	v_cvt_pk_f32_fp8_e32 v[224:225], v196
	v_cvt_pk_f32_fp8_sdwa v[226:227], v196 src0_sel:WORD_1
	v_cvt_pk_f32_fp8_e32 v[228:229], v197
	v_cvt_pk_f32_fp8_sdwa v[230:231], v197 src0_sel:WORD_1
	v_pk_fma_f32 v[32:33], v[224:225], v[208:209], v[32:33] op_sel:[0,1,0] op_sel_hi:[1,1,1]
	v_pk_fma_f32 v[34:35], v[226:227], v[208:209], v[34:35] op_sel:[0,1,0] op_sel_hi:[1,1,1]
	v_pk_fma_f32 v[36:37], v[228:229], v[208:209], v[36:37] op_sel:[0,1,0] op_sel_hi:[1,1,1]
	v_pk_fma_f32 v[38:39], v[230:231], v[208:209], v[38:39] op_sel:[0,1,0] op_sel_hi:[1,1,1]
	v_cvt_pk_f32_fp8_e32 v[224:225], v198
	v_cvt_pk_f32_fp8_sdwa v[226:227], v198 src0_sel:WORD_1
	v_cvt_pk_f32_fp8_e32 v[228:229], v199
	v_cvt_pk_f32_fp8_sdwa v[230:231], v199 src0_sel:WORD_1
	v_pk_fma_f32 v[40:41], v[224:225], v[208:209], v[40:41] op_sel:[0,1,0] op_sel_hi:[1,1,1]
	v_pk_fma_f32 v[42:43], v[226:227], v[208:209], v[42:43] op_sel:[0,1,0] op_sel_hi:[1,1,1]
	v_pk_fma_f32 v[44:45], v[228:229], v[208:209], v[44:45] op_sel:[0,1,0] op_sel_hi:[1,1,1]
	v_pk_fma_f32 v[46:47], v[230:231], v[208:209], v[46:47] op_sel:[0,1,0] op_sel_hi:[1,1,1]
	v_cvt_pk_f32_fp8_e32 v[224:225], v200
	v_cvt_pk_f32_fp8_sdwa v[226:227], v200 src0_sel:WORD_1
	v_cvt_pk_f32_fp8_e32 v[228:229], v201
	v_cvt_pk_f32_fp8_sdwa v[230:231], v201 src0_sel:WORD_1
	v_pk_fma_f32 v[32:33], v[224:225], v[210:211], v[32:33] op_sel_hi:[1,0,1]
	v_pk_fma_f32 v[34:35], v[226:227], v[210:211], v[34:35] op_sel_hi:[1,0,1]
	v_pk_fma_f32 v[36:37], v[228:229], v[210:211], v[36:37] op_sel_hi:[1,0,1]
	v_pk_fma_f32 v[38:39], v[230:231], v[210:211], v[38:39] op_sel_hi:[1,0,1]
	v_cvt_pk_f32_fp8_e32 v[224:225], v202
	v_cvt_pk_f32_fp8_sdwa v[226:227], v202 src0_sel:WORD_1
	v_cvt_pk_f32_fp8_e32 v[228:229], v203
	v_cvt_pk_f32_fp8_sdwa v[230:231], v203 src0_sel:WORD_1
	v_pk_fma_f32 v[40:41], v[224:225], v[210:211], v[40:41] op_sel_hi:[1,0,1]
	v_pk_fma_f32 v[42:43], v[226:227], v[210:211], v[42:43] op_sel_hi:[1,0,1]
	v_pk_fma_f32 v[44:45], v[228:229], v[210:211], v[44:45] op_sel_hi:[1,0,1]
	v_pk_fma_f32 v[46:47], v[230:231], v[210:211], v[46:47] op_sel_hi:[1,0,1]
	v_cvt_pk_f32_fp8_e32 v[224:225], v204
	v_cvt_pk_f32_fp8_sdwa v[226:227], v204 src0_sel:WORD_1
	v_cvt_pk_f32_fp8_e32 v[228:229], v205
	v_cvt_pk_f32_fp8_sdwa v[230:231], v205 src0_sel:WORD_1
	v_pk_fma_f32 v[32:33], v[224:225], v[210:211], v[32:33] op_sel:[0,1,0] op_sel_hi:[1,1,1]
	v_pk_fma_f32 v[34:35], v[226:227], v[210:211], v[34:35] op_sel:[0,1,0] op_sel_hi:[1,1,1]
	v_pk_fma_f32 v[36:37], v[228:229], v[210:211], v[36:37] op_sel:[0,1,0] op_sel_hi:[1,1,1]
	v_pk_fma_f32 v[38:39], v[230:231], v[210:211], v[38:39] op_sel:[0,1,0] op_sel_hi:[1,1,1]
	v_cvt_pk_f32_fp8_e32 v[224:225], v206
	v_cvt_pk_f32_fp8_sdwa v[226:227], v206 src0_sel:WORD_1
	v_cvt_pk_f32_fp8_e32 v[228:229], v207
	v_cvt_pk_f32_fp8_sdwa v[230:231], v207 src0_sel:WORD_1
	v_pk_fma_f32 v[40:41], v[224:225], v[210:211], v[40:41] op_sel:[0,1,0] op_sel_hi:[1,1,1]
	v_pk_fma_f32 v[42:43], v[226:227], v[210:211], v[42:43] op_sel:[0,1,0] op_sel_hi:[1,1,1]
	v_pk_fma_f32 v[44:45], v[228:229], v[210:211], v[44:45] op_sel:[0,1,0] op_sel_hi:[1,1,1]
	v_pk_fma_f32 v[46:47], v[230:231], v[210:211], v[46:47] op_sel:[0,1,0] op_sel_hi:[1,1,1]
	v_add_u32_e32 v213, 80, v213
	s_add_i32 s21, s21, 5
	s_sub_i32 s90, s90, 1
	s_cmp_eq_u32 s90, 0
	s_cbranch_scc1 .LV_sw0
	s_branch .LV_t2_s0
.LV_t3_s0:
	s_cmp_ge_u32 s21, s20
	s_cbranch_scc1 .LV_done
	s_waitcnt lgkmcnt(0)
	buffer_load_dwordx4 v[192:195], v[232:233], s[60:63], 0 idxen offen
	buffer_load_dwordx4 v[196:199], v[234:235], s[60:63], 0 idxen offen
	buffer_load_dwordx4 v[200:203], v[236:237], s[60:63], 0 idxen offen
	buffer_load_dwordx4 v[204:207], v[238:239], s[60:63], 0 idxen offen
	ds_read_b32 v232, v213 offset:80
	ds_read_b32 v234, v213 offset:84
	ds_read_b32 v236, v213 offset:88
	ds_read_b32 v238, v213 offset:92
	ds_read_b128 v[252:255], v213 offset:5008
	s_waitcnt vmcnt(16)
	v_cvt_pk_f32_fp8_e32 v[224:225], v128
	v_cvt_pk_f32_fp8_sdwa v[226:227], v128 src0_sel:WORD_1
	v_cvt_pk_f32_fp8_e32 v[228:229], v129
	v_cvt_pk_f32_fp8_sdwa v[230:231], v129 src0_sel:WORD_1
	v_pk_fma_f32 v[48:49], v[224:225], v[248:249], v[48:49] op_sel_hi:[1,0,1]
	v_pk_fma_f32 v[50:51], v[226:227], v[248:249], v[50:51] op_sel_hi:[1,0,1]
	v_pk_fma_f32 v[52:53], v[228:229], v[248:249], v[52:53] op_sel_hi:[1,0,1]
	v_pk_fma_f32 v[54:55], v[230:231], v[248:249], v[54:55] op_sel_hi:[1,0,1]
	v_cvt_pk_f32_fp8_e32 v[224:225], v130
	v_cvt_pk_f32_fp8_sdwa v[226:227], v130 src0_sel:WORD_1
	v_cvt_pk_f32_fp8_e32 v[228:229], v131
	v_cvt_pk_f32_fp8_sdwa v[230:231], v131 src0_sel:WORD_1
	v_pk_fma_f32 v[56:57], v[224:225], v[248:249], v[56:57] op_sel_hi:[1,0,1]
	v_pk_fma_f32 v[58:59], v[226:227], v[248:249], v[58:59] op_sel_hi:[1,0,1]
	v_pk_fma_f32 v[60:61], v[228:229], v[248:249], v[60:61] op_sel_hi:[1,0,1]
	v_pk_fma_f32 v[62:63], v[230:231], v[248:249], v[62:63] op_sel_hi:[1,0,1]
	v_cvt_pk_f32_fp8_e32 v[224:225], v132
	v_cvt_pk_f32_fp8_sdwa v[226:227], v132 src0_sel:WORD_1
	v_cvt_pk_f32_fp8_e32 v[228:229], v133
	v_cvt_pk_f32_fp8_sdwa v[230:231], v133 src0_sel:WORD_1
	v_pk_fma_f32 v[48:49], v[224:225], v[248:249], v[48:49] op_sel:[0,1,0] op_sel_hi:[1,1,1]
	v_pk_fma_f32 v[50:51], v[226:227], v[248:249], v[50:51] op_sel:[0,1,0] op_sel_hi:[1,1,1]
	v_pk_fma_f32 v[52:53], v[228:229], v[248:249], v[52:53] op_sel:[0,1,0] op_sel_hi:[1,1,1]
	v_pk_fma_f32 v[54:55], v[230:231], v[248:249], v[54:55] op_sel:[0,1,0] op_sel_hi:[1,1,1]
	v_cvt_pk_f32_fp8_e32 v[224:225], v134
	v_cvt_pk_f32_fp8_sdwa v[226:227], v134 src0_sel:WORD_1
	v_cvt_pk_f32_fp8_e32 v[228:229], v135
	v_cvt_pk_f32_fp8_sdwa v[230:231], v135 src0_sel:WORD_1
	v_pk_fma_f32 v[56:57], v[224:225], v[248:249], v[56:57] op_sel:[0,1,0] op_sel_hi:[1,1,1]
	v_pk_fma_f32 v[58:59], v[226:227], v[248:249], v[58:59] op_sel:[0,1,0] op_sel_hi:[1,1,1]
	v_pk_fma_f32 v[60:61], v[228:229], v[248:249], v[60:61] op_sel:[0,1,0] op_sel_hi:[1,1,1]
	v_pk_fma_f32 v[62:63], v[230:231], v[248:249], v[62:63] op_sel:[0,1,0] op_sel_hi:[1,1,1]
	v_cvt_pk_f32_fp8_e32 v[224:225], v136
	v_cvt_pk_f32_fp8_sdwa v[226:227], v136 src0_sel:WORD_1
	v_cvt_pk_f32_fp8_e32 v[228:229], v137
	v_cvt_pk_f32_fp8_sdwa v[230:231], v137 src0_sel:WORD_1
	v_pk_fma_f32 v[48:49], v[224:225], v[250:251], v[48:49] op_sel_hi:[1,0,1]
	v_pk_fma_f32 v[50:51], v[226:227], v[250:251], v[50:51] op_sel_hi:[1,0,1]
	v_pk_fma_f32 v[52:53], v[228:229], v[250:251], v[52:53] op_sel_hi:[1,0,1]
	v_pk_fma_f32 v[54:55], v[230:231], v[250:251], v[54:55] op_sel_hi:[1,0,1]
	v_cvt_pk_f32_fp8_e32 v[224:225], v138
	v_cvt_pk_f32_fp8_sdwa v[226:227], v138 src0_sel:WORD_1
	v_cvt_pk_f32_fp8_e32 v[228:229], v139
	v_cvt_pk_f32_fp8_sdwa v[230:231], v139 src0_sel:WORD_1
	v_pk_fma_f32 v[56:57], v[224:225], v[250:251], v[56:57] op_sel_hi:[1,0,1]
	v_pk_fma_f32 v[58:59], v[226:227], v[250:251], v[58:59] op_sel_hi:[1,0,1]
	v_pk_fma_f32 v[60:61], v[228:229], v[250:251], v[60:61] op_sel_hi:[1,0,1]
	v_pk_fma_f32 v[62:63], v[230:231], v[250:251], v[62:63] op_sel_hi:[1,0,1]
	v_cvt_pk_f32_fp8_e32 v[224:225], v140
	v_cvt_pk_f32_fp8_sdwa v[226:227], v140 src0_sel:WORD_1
	v_cvt_pk_f32_fp8_e32 v[228:229], v141
	v_cvt_pk_f32_fp8_sdwa v[230:231], v141 src0_sel:WORD_1
	v_pk_fma_f32 v[48:49], v[224:225], v[250:251], v[48:49] op_sel:[0,1,0] op_sel_hi:[1,1,1]
	v_pk_fma_f32 v[50:51], v[226:227], v[250:251], v[50:51] op_sel:[0,1,0] op_sel_hi:[1,1,1]
	v_pk_fma_f32 v[52:53], v[228:229], v[250:251], v[52:53] op_sel:[0,1,0] op_sel_hi:[1,1,1]
	v_pk_fma_f32 v[54:55], v[230:231], v[250:251], v[54:55] op_sel:[0,1,0] op_sel_hi:[1,1,1]
	v_cvt_pk_f32_fp8_e32 v[224:225], v142
	v_cvt_pk_f32_fp8_sdwa v[226:227], v142 src0_sel:WORD_1
	v_cvt_pk_f32_fp8_e32 v[228:229], v143
	v_cvt_pk_f32_fp8_sdwa v[230:231], v143 src0_sel:WORD_1
	v_pk_fma_f32 v[56:57], v[224:225], v[250:251], v[56:57] op_sel:[0,1,0] op_sel_hi:[1,1,1]
	v_pk_fma_f32 v[58:59], v[226:227], v[250:251], v[58:59] op_sel:[0,1,0] op_sel_hi:[1,1,1]
	v_pk_fma_f32 v[60:61], v[228:229], v[250:251], v[60:61] op_sel:[0,1,0] op_sel_hi:[1,1,1]
	v_pk_fma_f32 v[62:63], v[230:231], v[250:251], v[62:63] op_sel:[0,1,0] op_sel_hi:[1,1,1]
	s_sub_i32 s90, s90, 1
	s_cmp_eq_u32 s90, 0
	s_cbranch_scc1 .LV_sw1
.LV_t3_s1:
	s_waitcnt lgkmcnt(0)
	buffer_load_dwordx4 v[128:131], v[232:233], s[60:63], 0 idxen offen
	buffer_load_dwordx4 v[132:135], v[234:235], s[60:63], 0 idxen offen
	buffer_load_dwordx4 v[136:139], v[236:237], s[60:63], 0 idxen offen
	buffer_load_dwordx4 v[140:143], v[238:239], s[60:63], 0 idxen offen
	ds_read_b32 v232, v213 offset:96
	ds_read_b32 v234, v213 offset:100
	ds_read_b32 v236, v213 offset:104
	ds_read_b32 v238, v213 offset:108
	ds_read_b128 v[248:251], v213 offset:5024
	s_waitcnt vmcnt(16)
	v_cvt_pk_f32_fp8_e32 v[224:225], v144
	v_cvt_pk_f32_fp8_sdwa v[226:227], v144 src0_sel:WORD_1
	v_cvt_pk_f32_fp8_e32 v[228:229], v145
	v_cvt_pk_f32_fp8_sdwa v[230:231], v145 src0_sel:WORD_1
	v_pk_fma_f32 v[48:49], v[224:225], v[252:253], v[48:49] op_sel_hi:[1,0,1]
	v_pk_fma_f32 v[50:51], v[226:227], v[252:253], v[50:51] op_sel_hi:[1,0,1]
	v_pk_fma_f32 v[52:53], v[228:229], v[252:253], v[52:53] op_sel_hi:[1,0,1]
	v_pk_fma_f32 v[54:55], v[230:231], v[252:253], v[54:55] op_sel_hi:[1,0,1]
	v_cvt_pk_f32_fp8_e32 v[224:225], v146
	v_cvt_pk_f32_fp8_sdwa v[226:227], v146 src0_sel:WORD_1
	v_cvt_pk_f32_fp8_e32 v[228:229], v147
	v_cvt_pk_f32_fp8_sdwa v[230:231], v147 src0_sel:WORD_1
	v_pk_fma_f32 v[56:57], v[224:225], v[252:253], v[56:57] op_sel_hi:[1,0,1]
	v_pk_fma_f32 v[58:59], v[226:227], v[252:253], v[58:59] op_sel_hi:[1,0,1]
	v_pk_fma_f32 v[60:61], v[228:229], v[252:253], v[60:61] op_sel_hi:[1,0,1]
	v_pk_fma_f32 v[62:63], v[230:231], v[252:253], v[62:63] op_sel_hi:[1,0,1]
	v_cvt_pk_f32_fp8_e32 v[224:225], v148
	v_cvt_pk_f32_fp8_sdwa v[226:227], v148 src0_sel:WORD_1
	v_cvt_pk_f32_fp8_e32 v[228:229], v149
	v_cvt_pk_f32_fp8_sdwa v[230:231], v149 src0_sel:WORD_1
	v_pk_fma_f32 v[48:49], v[224:225], v[252:253], v[48:49] op_sel:[0,1,0] op_sel_hi:[1,1,1]
	v_pk_fma_f32 v[50:51], v[226:227], v[252:253], v[50:51] op_sel:[0,1,0] op_sel_hi:[1,1,1]
	v_pk_fma_f32 v[52:53], v[228:229], v[252:253], v[52:53] op_sel:[0,1,0] op_sel_hi:[1,1,1]
	v_pk_fma_f32 v[54:55], v[230:231], v[252:253], v[54:55] op_sel:[0,1,0] op_sel_hi:[1,1,1]
	v_cvt_pk_f32_fp8_e32 v[224:225], v150
	v_cvt_pk_f32_fp8_sdwa v[226:227], v150 src0_sel:WORD_1
	v_cvt_pk_f32_fp8_e32 v[228:229], v151
	v_cvt_pk_f32_fp8_sdwa v[230:231], v151 src0_sel:WORD_1
	v_pk_fma_f32 v[56:57], v[224:225], v[252:253], v[56:57] op_sel:[0,1,0] op_sel_hi:[1,1,1]
	v_pk_fma_f32 v[58:59], v[226:227], v[252:253], v[58:59] op_sel:[0,1,0] op_sel_hi:[1,1,1]
	v_pk_fma_f32 v[60:61], v[228:229], v[252:253], v[60:61] op_sel:[0,1,0] op_sel_hi:[1,1,1]
	v_pk_fma_f32 v[62:63], v[230:231], v[252:253], v[62:63] op_sel:[0,1,0] op_sel_hi:[1,1,1]
	v_cvt_pk_f32_fp8_e32 v[224:225], v152
	v_cvt_pk_f32_fp8_sdwa v[226:227], v152 src0_sel:WORD_1
	v_cvt_pk_f32_fp8_e32 v[228:229], v153
	v_cvt_pk_f32_fp8_sdwa v[230:231], v153 src0_sel:WORD_1
	v_pk_fma_f32 v[48:49], v[224:225], v[254:255], v[48:49] op_sel_hi:[1,0,1]
	v_pk_fma_f32 v[50:51], v[226:227], v[254:255], v[50:51] op_sel_hi:[1,0,1]
	v_pk_fma_f32 v[52:53], v[228:229], v[254:255], v[52:53] op_sel_hi:[1,0,1]
	v_pk_fma_f32 v[54:55], v[230:231], v[254:255], v[54:55] op_sel_hi:[1,0,1]
	v_cvt_pk_f32_fp8_e32 v[224:225], v154
	v_cvt_pk_f32_fp8_sdwa v[226:227], v154 src0_sel:WORD_1
	v_cvt_pk_f32_fp8_e32 v[228:229], v155
	v_cvt_pk_f32_fp8_sdwa v[230:231], v155 src0_sel:WORD_1
	v_pk_fma_f32 v[56:57], v[224:225], v[254:255], v[56:57] op_sel_hi:[1,0,1]
	v_pk_fma_f32 v[58:59], v[226:227], v[254:255], v[58:59] op_sel_hi:[1,0,1]
	v_pk_fma_f32 v[60:61], v[228:229], v[254:255], v[60:61] op_sel_hi:[1,0,1]
	v_pk_fma_f32 v[62:63], v[230:231], v[254:255], v[62:63] op_sel_hi:[1,0,1]
	v_cvt_pk_f32_fp8_e32 v[224:225], v156
	v_cvt_pk_f32_fp8_sdwa v[226:227], v156 src0_sel:WORD_1
	v_cvt_pk_f32_fp8_e32 v[228:229], v157
	v_cvt_pk_f32_fp8_sdwa v[230:231], v157 src0_sel:WORD_1
	v_pk_fma_f32 v[48:49], v[224:225], v[254:255], v[48:49] op_sel:[0,1,0] op_sel_hi:[1,1,1]
	v_pk_fma_f32 v[50:51], v[226:227], v[254:255], v[50:51] op_sel:[0,1,0] op_sel_hi:[1,1,1]
	v_pk_fma_f32 v[52:53], v[228:229], v[254:255], v[52:53] op_sel:[0,1,0] op_sel_hi:[1,1,1]
	v_pk_fma_f32 v[54:55], v[230:231], v[254:255], v[54:55] op_sel:[0,1,0] op_sel_hi:[1,1,1]
	v_cvt_pk_f32_fp8_e32 v[224:225], v158
	v_cvt_pk_f32_fp8_sdwa v[226:227], v158 src0_sel:WORD_1
	v_cvt_pk_f32_fp8_e32 v[228:229], v159
	v_cvt_pk_f32_fp8_sdwa v[230:231], v159 src0_sel:WORD_1
	v_pk_fma_f32 v[56:57], v[224:225], v[254:255], v[56:57] op_sel:[0,1,0] op_sel_hi:[1,1,1]
	v_pk_fma_f32 v[58:59], v[226:227], v[254:255], v[58:59] op_sel:[0,1,0] op_sel_hi:[1,1,1]
	v_pk_fma_f32 v[60:61], v[228:229], v[254:255], v[60:61] op_sel:[0,1,0] op_sel_hi:[1,1,1]
	v_pk_fma_f32 v[62:63], v[230:231], v[254:255], v[62:63] op_sel:[0,1,0] op_sel_hi:[1,1,1]
	s_sub_i32 s90, s90, 1
	s_cmp_eq_u32 s90, 0
	s_cbranch_scc1 .LV_sw2
.LV_t3_s2:
	s_waitcnt lgkmcnt(0)
	buffer_load_dwordx4 v[144:147], v[232:233], s[60:63], 0 idxen offen
	buffer_load_dwordx4 v[148:151], v[234:235], s[60:63], 0 idxen offen
	buffer_load_dwordx4 v[152:155], v[236:237], s[60:63], 0 idxen offen
	buffer_load_dwordx4 v[156:159], v[238:239], s[60:63], 0 idxen offen
	ds_read_b32 v232, v213 offset:112
	ds_read_b32 v234, v213 offset:116
	ds_read_b32 v236, v213 offset:120
	ds_read_b32 v238, v213 offset:124
	ds_read_b128 v[252:255], v213 offset:5040
	s_waitcnt vmcnt(16)
	v_cvt_pk_f32_fp8_e32 v[224:225], v160
	v_cvt_pk_f32_fp8_sdwa v[226:227], v160 src0_sel:WORD_1
	v_cvt_pk_f32_fp8_e32 v[228:229], v161
	v_cvt_pk_f32_fp8_sdwa v[230:231], v161 src0_sel:WORD_1
	v_pk_fma_f32 v[48:49], v[224:225], v[248:249], v[48:49] op_sel_hi:[1,0,1]
	v_pk_fma_f32 v[50:51], v[226:227], v[248:249], v[50:51] op_sel_hi:[1,0,1]
	v_pk_fma_f32 v[52:53], v[228:229], v[248:249], v[52:53] op_sel_hi:[1,0,1]
	v_pk_fma_f32 v[54:55], v[230:231], v[248:249], v[54:55] op_sel_hi:[1,0,1]
	v_cvt_pk_f32_fp8_e32 v[224:225], v162
	v_cvt_pk_f32_fp8_sdwa v[226:227], v162 src0_sel:WORD_1
	v_cvt_pk_f32_fp8_e32 v[228:229], v163
	v_cvt_pk_f32_fp8_sdwa v[230:231], v163 src0_sel:WORD_1
	v_pk_fma_f32 v[56:57], v[224:225], v[248:249], v[56:57] op_sel_hi:[1,0,1]
	v_pk_fma_f32 v[58:59], v[226:227], v[248:249], v[58:59] op_sel_hi:[1,0,1]
	v_pk_fma_f32 v[60:61], v[228:229], v[248:249], v[60:61] op_sel_hi:[1,0,1]
	v_pk_fma_f32 v[62:63], v[230:231], v[248:249], v[62:63] op_sel_hi:[1,0,1]
	v_cvt_pk_f32_fp8_e32 v[224:225], v164
	v_cvt_pk_f32_fp8_sdwa v[226:227], v164 src0_sel:WORD_1
	v_cvt_pk_f32_fp8_e32 v[228:229], v165
	v_cvt_pk_f32_fp8_sdwa v[230:231], v165 src0_sel:WORD_1
	v_pk_fma_f32 v[48:49], v[224:225], v[248:249], v[48:49] op_sel:[0,1,0] op_sel_hi:[1,1,1]
	v_pk_fma_f32 v[50:51], v[226:227], v[248:249], v[50:51] op_sel:[0,1,0] op_sel_hi:[1,1,1]
	v_pk_fma_f32 v[52:53], v[228:229], v[248:249], v[52:53] op_sel:[0,1,0] op_sel_hi:[1,1,1]
	v_pk_fma_f32 v[54:55], v[230:231], v[248:249], v[54:55] op_sel:[0,1,0] op_sel_hi:[1,1,1]
	v_cvt_pk_f32_fp8_e32 v[224:225], v166
	v_cvt_pk_f32_fp8_sdwa v[226:227], v166 src0_sel:WORD_1
	v_cvt_pk_f32_fp8_e32 v[228:229], v167
	v_cvt_pk_f32_fp8_sdwa v[230:231], v167 src0_sel:WORD_1
	v_pk_fma_f32 v[56:57], v[224:225], v[248:249], v[56:57] op_sel:[0,1,0] op_sel_hi:[1,1,1]
	v_pk_fma_f32 v[58:59], v[226:227], v[248:249], v[58:59] op_sel:[0,1,0] op_sel_hi:[1,1,1]
	v_pk_fma_f32 v[60:61], v[228:229], v[248:249], v[60:61] op_sel:[0,1,0] op_sel_hi:[1,1,1]
	v_pk_fma_f32 v[62:63], v[230:231], v[248:249], v[62:63] op_sel:[0,1,0] op_sel_hi:[1,1,1]
	v_cvt_pk_f32_fp8_e32 v[224:225], v168
	v_cvt_pk_f32_fp8_sdwa v[226:227], v168 src0_sel:WORD_1
	v_cvt_pk_f32_fp8_e32 v[228:229], v169
	v_cvt_pk_f32_fp8_sdwa v[230:231], v169 src0_sel:WORD_1
	v_pk_fma_f32 v[48:49], v[224:225], v[250:251], v[48:49] op_sel_hi:[1,0,1]
	v_pk_fma_f32 v[50:51], v[226:227], v[250:251], v[50:51] op_sel_hi:[1,0,1]
	v_pk_fma_f32 v[52:53], v[228:229], v[250:251], v[52:53] op_sel_hi:[1,0,1]
	v_pk_fma_f32 v[54:55], v[230:231], v[250:251], v[54:55] op_sel_hi:[1,0,1]
	v_cvt_pk_f32_fp8_e32 v[224:225], v170
	v_cvt_pk_f32_fp8_sdwa v[226:227], v170 src0_sel:WORD_1
	v_cvt_pk_f32_fp8_e32 v[228:229], v171
	v_cvt_pk_f32_fp8_sdwa v[230:231], v171 src0_sel:WORD_1
	v_pk_fma_f32 v[56:57], v[224:225], v[250:251], v[56:57] op_sel_hi:[1,0,1]
	v_pk_fma_f32 v[58:59], v[226:227], v[250:251], v[58:59] op_sel_hi:[1,0,1]
	v_pk_fma_f32 v[60:61], v[228:229], v[250:251], v[60:61] op_sel_hi:[1,0,1]
	v_pk_fma_f32 v[62:63], v[230:231], v[250:251], v[62:63] op_sel_hi:[1,0,1]
	v_cvt_pk_f32_fp8_e32 v[224:225], v172
	v_cvt_pk_f32_fp8_sdwa v[226:227], v172 src0_sel:WORD_1
	v_cvt_pk_f32_fp8_e32 v[228:229], v173
	v_cvt_pk_f32_fp8_sdwa v[230:231], v173 src0_sel:WORD_1
	v_pk_fma_f32 v[48:49], v[224:225], v[250:251], v[48:49] op_sel:[0,1,0] op_sel_hi:[1,1,1]
	v_pk_fma_f32 v[50:51], v[226:227], v[250:251], v[50:51] op_sel:[0,1,0] op_sel_hi:[1,1,1]
	v_pk_fma_f32 v[52:53], v[228:229], v[250:251], v[52:53] op_sel:[0,1,0] op_sel_hi:[1,1,1]
	v_pk_fma_f32 v[54:55], v[230:231], v[250:251], v[54:55] op_sel:[0,1,0] op_sel_hi:[1,1,1]
	v_cvt_pk_f32_fp8_e32 v[224:225], v174
	v_cvt_pk_f32_fp8_sdwa v[226:227], v174 src0_sel:WORD_1
	v_cvt_pk_f32_fp8_e32 v[228:229], v175
	v_cvt_pk_f32_fp8_sdwa v[230:231], v175 src0_sel:WORD_1
	v_pk_fma_f32 v[56:57], v[224:225], v[250:251], v[56:57] op_sel:[0,1,0] op_sel_hi:[1,1,1]
	v_pk_fma_f32 v[58:59], v[226:227], v[250:251], v[58:59] op_sel:[0,1,0] op_sel_hi:[1,1,1]
	v_pk_fma_f32 v[60:61], v[228:229], v[250:251], v[60:61] op_sel:[0,1,0] op_sel_hi:[1,1,1]
	v_pk_fma_f32 v[62:63], v[230:231], v[250:251], v[62:63] op_sel:[0,1,0] op_sel_hi:[1,1,1]
	s_sub_i32 s90, s90, 1
	s_cmp_eq_u32 s90, 0
	s_cbranch_scc1 .LV_sw3
.LV_t3_s3:
	s_waitcnt lgkmcnt(0)
	buffer_load_dwordx4 v[160:163], v[232:233], s[60:63], 0 idxen offen
	buffer_load_dwordx4 v[164:167], v[234:235], s[60:63], 0 idxen offen
	buffer_load_dwordx4 v[168:171], v[236:237], s[60:63], 0 idxen offen
	buffer_load_dwordx4 v[172:175], v[238:239], s[60:63], 0 idxen offen
	ds_read_b32 v232, v213 offset:128
	ds_read_b32 v234, v213 offset:132
	ds_read_b32 v236, v213 offset:136
	ds_read_b32 v238, v213 offset:140
	ds_read_b128 v[208:211], v213 offset:5056
	s_waitcnt vmcnt(16)
	v_cvt_pk_f32_fp8_e32 v[224:225], v176
	v_cvt_pk_f32_fp8_sdwa v[226:227], v176 src0_sel:WORD_1
	v_cvt_pk_f32_fp8_e32 v[228:229], v177
	v_cvt_pk_f32_fp8_sdwa v[230:231], v177 src0_sel:WORD_1
	v_pk_fma_f32 v[48:49], v[224:225], v[252:253], v[48:49] op_sel_hi:[1,0,1]
	v_pk_fma_f32 v[50:51], v[226:227], v[252:253], v[50:51] op_sel_hi:[1,0,1]
	v_pk_fma_f32 v[52:53], v[228:229], v[252:253], v[52:53] op_sel_hi:[1,0,1]
	v_pk_fma_f32 v[54:55], v[230:231], v[252:253], v[54:55] op_sel_hi:[1,0,1]
	v_cvt_pk_f32_fp8_e32 v[224:225], v178
	v_cvt_pk_f32_fp8_sdwa v[226:227], v178 src0_sel:WORD_1
	v_cvt_pk_f32_fp8_e32 v[228:229], v179
	v_cvt_pk_f32_fp8_sdwa v[230:231], v179 src0_sel:WORD_1
	v_pk_fma_f32 v[56:57], v[224:225], v[252:253], v[56:57] op_sel_hi:[1,0,1]
	v_pk_fma_f32 v[58:59], v[226:227], v[252:253], v[58:59] op_sel_hi:[1,0,1]
	v_pk_fma_f32 v[60:61], v[228:229], v[252:253], v[60:61] op_sel_hi:[1,0,1]
	v_pk_fma_f32 v[62:63], v[230:231], v[252:253], v[62:63] op_sel_hi:[1,0,1]
	v_cvt_pk_f32_fp8_e32 v[224:225], v180
	v_cvt_pk_f32_fp8_sdwa v[226:227], v180 src0_sel:WORD_1
	v_cvt_pk_f32_fp8_e32 v[228:229], v181
	v_cvt_pk_f32_fp8_sdwa v[230:231], v181 src0_sel:WORD_1
	v_pk_fma_f32 v[48:49], v[224:225], v[252:253], v[48:49] op_sel:[0,1,0] op_sel_hi:[1,1,1]
	v_pk_fma_f32 v[50:51], v[226:227], v[252:253], v[50:51] op_sel:[0,1,0] op_sel_hi:[1,1,1]
	v_pk_fma_f32 v[52:53], v[228:229], v[252:253], v[52:53] op_sel:[0,1,0] op_sel_hi:[1,1,1]
	v_pk_fma_f32 v[54:55], v[230:231], v[252:253], v[54:55] op_sel:[0,1,0] op_sel_hi:[1,1,1]
	v_cvt_pk_f32_fp8_e32 v[224:225], v182
	v_cvt_pk_f32_fp8_sdwa v[226:227], v182 src0_sel:WORD_1
	v_cvt_pk_f32_fp8_e32 v[228:229], v183
	v_cvt_pk_f32_fp8_sdwa v[230:231], v183 src0_sel:WORD_1
	v_pk_fma_f32 v[56:57], v[224:225], v[252:253], v[56:57] op_sel:[0,1,0] op_sel_hi:[1,1,1]
	v_pk_fma_f32 v[58:59], v[226:227], v[252:253], v[58:59] op_sel:[0,1,0] op_sel_hi:[1,1,1]
	v_pk_fma_f32 v[60:61], v[228:229], v[252:253], v[60:61] op_sel:[0,1,0] op_sel_hi:[1,1,1]
	v_pk_fma_f32 v[62:63], v[230:231], v[252:253], v[62:63] op_sel:[0,1,0] op_sel_hi:[1,1,1]
	v_cvt_pk_f32_fp8_e32 v[224:225], v184
	v_cvt_pk_f32_fp8_sdwa v[226:227], v184 src0_sel:WORD_1
	v_cvt_pk_f32_fp8_e32 v[228:229], v185
	v_cvt_pk_f32_fp8_sdwa v[230:231], v185 src0_sel:WORD_1
	v_pk_fma_f32 v[48:49], v[224:225], v[254:255], v[48:49] op_sel_hi:[1,0,1]
	v_pk_fma_f32 v[50:51], v[226:227], v[254:255], v[50:51] op_sel_hi:[1,0,1]
	v_pk_fma_f32 v[52:53], v[228:229], v[254:255], v[52:53] op_sel_hi:[1,0,1]
	v_pk_fma_f32 v[54:55], v[230:231], v[254:255], v[54:55] op_sel_hi:[1,0,1]
	v_cvt_pk_f32_fp8_e32 v[224:225], v186
	v_cvt_pk_f32_fp8_sdwa v[226:227], v186 src0_sel:WORD_1
	v_cvt_pk_f32_fp8_e32 v[228:229], v187
	v_cvt_pk_f32_fp8_sdwa v[230:231], v187 src0_sel:WORD_1
	v_pk_fma_f32 v[56:57], v[224:225], v[254:255], v[56:57] op_sel_hi:[1,0,1]
	v_pk_fma_f32 v[58:59], v[226:227], v[254:255], v[58:59] op_sel_hi:[1,0,1]
	v_pk_fma_f32 v[60:61], v[228:229], v[254:255], v[60:61] op_sel_hi:[1,0,1]
	v_pk_fma_f32 v[62:63], v[230:231], v[254:255], v[62:63] op_sel_hi:[1,0,1]
	v_cvt_pk_f32_fp8_e32 v[224:225], v188
	v_cvt_pk_f32_fp8_sdwa v[226:227], v188 src0_sel:WORD_1
	v_cvt_pk_f32_fp8_e32 v[228:229], v189
	v_cvt_pk_f32_fp8_sdwa v[230:231], v189 src0_sel:WORD_1
	v_pk_fma_f32 v[48:49], v[224:225], v[254:255], v[48:49] op_sel:[0,1,0] op_sel_hi:[1,1,1]
	v_pk_fma_f32 v[50:51], v[226:227], v[254:255], v[50:51] op_sel:[0,1,0] op_sel_hi:[1,1,1]
	v_pk_fma_f32 v[52:53], v[228:229], v[254:255], v[52:53] op_sel:[0,1,0] op_sel_hi:[1,1,1]
	v_pk_fma_f32 v[54:55], v[230:231], v[254:255], v[54:55] op_sel:[0,1,0] op_sel_hi:[1,1,1]
	v_cvt_pk_f32_fp8_e32 v[224:225], v190
	v_cvt_pk_f32_fp8_sdwa v[226:227], v190 src0_sel:WORD_1
	v_cvt_pk_f32_fp8_e32 v[228:229], v191
	v_cvt_pk_f32_fp8_sdwa v[230:231], v191 src0_sel:WORD_1
	v_pk_fma_f32 v[56:57], v[224:225], v[254:255], v[56:57] op_sel:[0,1,0] op_sel_hi:[1,1,1]
	v_pk_fma_f32 v[58:59], v[226:227], v[254:255], v[58:59] op_sel:[0,1,0] op_sel_hi:[1,1,1]
	v_pk_fma_f32 v[60:61], v[228:229], v[254:255], v[60:61] op_sel:[0,1,0] op_sel_hi:[1,1,1]
	v_pk_fma_f32 v[62:63], v[230:231], v[254:255], v[62:63] op_sel:[0,1,0] op_sel_hi:[1,1,1]
	s_sub_i32 s90, s90, 1
	s_cmp_eq_u32 s90, 0
	s_cbranch_scc1 .LV_sw4
.LV_t3_s4:
	s_waitcnt lgkmcnt(0)
	buffer_load_dwordx4 v[176:179], v[232:233], s[60:63], 0 idxen offen
	buffer_load_dwordx4 v[180:183], v[234:235], s[60:63], 0 idxen offen
	buffer_load_dwordx4 v[184:187], v[236:237], s[60:63], 0 idxen offen
	buffer_load_dwordx4 v[188:191], v[238:239], s[60:63], 0 idxen offen
	ds_read_b32 v232, v213 offset:144
	ds_read_b32 v234, v213 offset:148
	ds_read_b32 v236, v213 offset:152
	ds_read_b32 v238, v213 offset:156
	ds_read_b128 v[248:251], v213 offset:5072
	s_waitcnt vmcnt(16)
	v_cvt_pk_f32_fp8_e32 v[224:225], v192
	v_cvt_pk_f32_fp8_sdwa v[226:227], v192 src0_sel:WORD_1
	v_cvt_pk_f32_fp8_e32 v[228:229], v193
	v_cvt_pk_f32_fp8_sdwa v[230:231], v193 src0_sel:WORD_1
	v_pk_fma_f32 v[48:49], v[224:225], v[208:209], v[48:49] op_sel_hi:[1,0,1]
	v_pk_fma_f32 v[50:51], v[226:227], v[208:209], v[50:51] op_sel_hi:[1,0,1]
	v_pk_fma_f32 v[52:53], v[228:229], v[208:209], v[52:53] op_sel_hi:[1,0,1]
	v_pk_fma_f32 v[54:55], v[230:231], v[208:209], v[54:55] op_sel_hi:[1,0,1]
	v_cvt_pk_f32_fp8_e32 v[224:225], v194
	v_cvt_pk_f32_fp8_sdwa v[226:227], v194 src0_sel:WORD_1
	v_cvt_pk_f32_fp8_e32 v[228:229], v195
	v_cvt_pk_f32_fp8_sdwa v[230:231], v195 src0_sel:WORD_1
	v_pk_fma_f32 v[56:57], v[224:225], v[208:209], v[56:57] op_sel_hi:[1,0,1]
	v_pk_fma_f32 v[58:59], v[226:227], v[208:209], v[58:59] op_sel_hi:[1,0,1]
	v_pk_fma_f32 v[60:61], v[228:229], v[208:209], v[60:61] op_sel_hi:[1,0,1]
	v_pk_fma_f32 v[62:63], v[230:231], v[208:209], v[62:63] op_sel_hi:[1,0,1]
	v_cvt_pk_f32_fp8_e32 v[224:225], v196
	v_cvt_pk_f32_fp8_sdwa v[226:227], v196 src0_sel:WORD_1
	v_cvt_pk_f32_fp8_e32 v[228:229], v197
	v_cvt_pk_f32_fp8_sdwa v[230:231], v197 src0_sel:WORD_1
	v_pk_fma_f32 v[48:49], v[224:225], v[208:209], v[48:49] op_sel:[0,1,0] op_sel_hi:[1,1,1]
	v_pk_fma_f32 v[50:51], v[226:227], v[208:209], v[50:51] op_sel:[0,1,0] op_sel_hi:[1,1,1]
	v_pk_fma_f32 v[52:53], v[228:229], v[208:209], v[52:53] op_sel:[0,1,0] op_sel_hi:[1,1,1]
	v_pk_fma_f32 v[54:55], v[230:231], v[208:209], v[54:55] op_sel:[0,1,0] op_sel_hi:[1,1,1]
	v_cvt_pk_f32_fp8_e32 v[224:225], v198
	v_cvt_pk_f32_fp8_sdwa v[226:227], v198 src0_sel:WORD_1
	v_cvt_pk_f32_fp8_e32 v[228:229], v199
	v_cvt_pk_f32_fp8_sdwa v[230:231], v199 src0_sel:WORD_1
	v_pk_fma_f32 v[56:57], v[224:225], v[208:209], v[56:57] op_sel:[0,1,0] op_sel_hi:[1,1,1]
	v_pk_fma_f32 v[58:59], v[226:227], v[208:209], v[58:59] op_sel:[0,1,0] op_sel_hi:[1,1,1]
	v_pk_fma_f32 v[60:61], v[228:229], v[208:209], v[60:61] op_sel:[0,1,0] op_sel_hi:[1,1,1]
	v_pk_fma_f32 v[62:63], v[230:231], v[208:209], v[62:63] op_sel:[0,1,0] op_sel_hi:[1,1,1]
	v_cvt_pk_f32_fp8_e32 v[224:225], v200
	v_cvt_pk_f32_fp8_sdwa v[226:227], v200 src0_sel:WORD_1
	v_cvt_pk_f32_fp8_e32 v[228:229], v201
	v_cvt_pk_f32_fp8_sdwa v[230:231], v201 src0_sel:WORD_1
	v_pk_fma_f32 v[48:49], v[224:225], v[210:211], v[48:49] op_sel_hi:[1,0,1]
	v_pk_fma_f32 v[50:51], v[226:227], v[210:211], v[50:51] op_sel_hi:[1,0,1]
	v_pk_fma_f32 v[52:53], v[228:229], v[210:211], v[52:53] op_sel_hi:[1,0,1]
	v_pk_fma_f32 v[54:55], v[230:231], v[210:211], v[54:55] op_sel_hi:[1,0,1]
	v_cvt_pk_f32_fp8_e32 v[224:225], v202
	v_cvt_pk_f32_fp8_sdwa v[226:227], v202 src0_sel:WORD_1
	v_cvt_pk_f32_fp8_e32 v[228:229], v203
	v_cvt_pk_f32_fp8_sdwa v[230:231], v203 src0_sel:WORD_1
	v_pk_fma_f32 v[56:57], v[224:225], v[210:211], v[56:57] op_sel_hi:[1,0,1]
	v_pk_fma_f32 v[58:59], v[226:227], v[210:211], v[58:59] op_sel_hi:[1,0,1]
	v_pk_fma_f32 v[60:61], v[228:229], v[210:211], v[60:61] op_sel_hi:[1,0,1]
	v_pk_fma_f32 v[62:63], v[230:231], v[210:211], v[62:63] op_sel_hi:[1,0,1]
	v_cvt_pk_f32_fp8_e32 v[224:225], v204
	v_cvt_pk_f32_fp8_sdwa v[226:227], v204 src0_sel:WORD_1
	v_cvt_pk_f32_fp8_e32 v[228:229], v205
	v_cvt_pk_f32_fp8_sdwa v[230:231], v205 src0_sel:WORD_1
	v_pk_fma_f32 v[48:49], v[224:225], v[210:211], v[48:49] op_sel:[0,1,0] op_sel_hi:[1,1,1]
	v_pk_fma_f32 v[50:51], v[226:227], v[210:211], v[50:51] op_sel:[0,1,0] op_sel_hi:[1,1,1]
	v_pk_fma_f32 v[52:53], v[228:229], v[210:211], v[52:53] op_sel:[0,1,0] op_sel_hi:[1,1,1]
	v_pk_fma_f32 v[54:55], v[230:231], v[210:211], v[54:55] op_sel:[0,1,0] op_sel_hi:[1,1,1]
	v_cvt_pk_f32_fp8_e32 v[224:225], v206
	v_cvt_pk_f32_fp8_sdwa v[226:227], v206 src0_sel:WORD_1
	v_cvt_pk_f32_fp8_e32 v[228:229], v207
	v_cvt_pk_f32_fp8_sdwa v[230:231], v207 src0_sel:WORD_1
	v_pk_fma_f32 v[56:57], v[224:225], v[210:211], v[56:57] op_sel:[0,1,0] op_sel_hi:[1,1,1]
	v_pk_fma_f32 v[58:59], v[226:227], v[210:211], v[58:59] op_sel:[0,1,0] op_sel_hi:[1,1,1]
	v_pk_fma_f32 v[60:61], v[228:229], v[210:211], v[60:61] op_sel:[0,1,0] op_sel_hi:[1,1,1]
	v_pk_fma_f32 v[62:63], v[230:231], v[210:211], v[62:63] op_sel:[0,1,0] op_sel_hi:[1,1,1]
	v_add_u32_e32 v213, 80, v213
	s_add_i32 s21, s21, 5
	s_sub_i32 s90, s90, 1
	s_cmp_eq_u32 s90, 0
	s_cbranch_scc1 .LV_sw0
	s_branch .LV_t3_s0
.LV_t4_s0:
	s_cmp_ge_u32 s21, s20
	s_cbranch_scc1 .LV_done
	s_waitcnt lgkmcnt(0)
	buffer_load_dwordx4 v[192:195], v[232:233], s[60:63], 0 idxen offen
	buffer_load_dwordx4 v[196:199], v[234:235], s[60:63], 0 idxen offen
	buffer_load_dwordx4 v[200:203], v[236:237], s[60:63], 0 idxen offen
	buffer_load_dwordx4 v[204:207], v[238:239], s[60:63], 0 idxen offen
	ds_read_b32 v232, v213 offset:80
	ds_read_b32 v234, v213 offset:84
	ds_read_b32 v236, v213 offset:88
	ds_read_b32 v238, v213 offset:92
	ds_read_b128 v[252:255], v213 offset:5008
	s_waitcnt vmcnt(16)
	v_cvt_pk_f32_fp8_e32 v[224:225], v128
	v_cvt_pk_f32_fp8_sdwa v[226:227], v128 src0_sel:WORD_1
	v_cvt_pk_f32_fp8_e32 v[228:229], v129
	v_cvt_pk_f32_fp8_sdwa v[230:231], v129 src0_sel:WORD_1
	v_pk_fma_f32 v[64:65], v[224:225], v[248:249], v[64:65] op_sel_hi:[1,0,1]
	v_pk_fma_f32 v[66:67], v[226:227], v[248:249], v[66:67] op_sel_hi:[1,0,1]
	v_pk_fma_f32 v[68:69], v[228:229], v[248:249], v[68:69] op_sel_hi:[1,0,1]
	v_pk_fma_f32 v[70:71], v[230:231], v[248:249], v[70:71] op_sel_hi:[1,0,1]
	v_cvt_pk_f32_fp8_e32 v[224:225], v130
	v_cvt_pk_f32_fp8_sdwa v[226:227], v130 src0_sel:WORD_1
	v_cvt_pk_f32_fp8_e32 v[228:229], v131
	v_cvt_pk_f32_fp8_sdwa v[230:231], v131 src0_sel:WORD_1
	v_pk_fma_f32 v[72:73], v[224:225], v[248:249], v[72:73] op_sel_hi:[1,0,1]
	v_pk_fma_f32 v[74:75], v[226:227], v[248:249], v[74:75] op_sel_hi:[1,0,1]
	v_pk_fma_f32 v[76:77], v[228:229], v[248:249], v[76:77] op_sel_hi:[1,0,1]
	v_pk_fma_f32 v[78:79], v[230:231], v[248:249], v[78:79] op_sel_hi:[1,0,1]
	v_cvt_pk_f32_fp8_e32 v[224:225], v132
	v_cvt_pk_f32_fp8_sdwa v[226:227], v132 src0_sel:WORD_1
	v_cvt_pk_f32_fp8_e32 v[228:229], v133
	v_cvt_pk_f32_fp8_sdwa v[230:231], v133 src0_sel:WORD_1
	v_pk_fma_f32 v[64:65], v[224:225], v[248:249], v[64:65] op_sel:[0,1,0] op_sel_hi:[1,1,1]
	v_pk_fma_f32 v[66:67], v[226:227], v[248:249], v[66:67] op_sel:[0,1,0] op_sel_hi:[1,1,1]
	v_pk_fma_f32 v[68:69], v[228:229], v[248:249], v[68:69] op_sel:[0,1,0] op_sel_hi:[1,1,1]
	v_pk_fma_f32 v[70:71], v[230:231], v[248:249], v[70:71] op_sel:[0,1,0] op_sel_hi:[1,1,1]
	v_cvt_pk_f32_fp8_e32 v[224:225], v134
	v_cvt_pk_f32_fp8_sdwa v[226:227], v134 src0_sel:WORD_1
	v_cvt_pk_f32_fp8_e32 v[228:229], v135
	v_cvt_pk_f32_fp8_sdwa v[230:231], v135 src0_sel:WORD_1
	v_pk_fma_f32 v[72:73], v[224:225], v[248:249], v[72:73] op_sel:[0,1,0] op_sel_hi:[1,1,1]
	v_pk_fma_f32 v[74:75], v[226:227], v[248:249], v[74:75] op_sel:[0,1,0] op_sel_hi:[1,1,1]
	v_pk_fma_f32 v[76:77], v[228:229], v[248:249], v[76:77] op_sel:[0,1,0] op_sel_hi:[1,1,1]
	v_pk_fma_f32 v[78:79], v[230:231], v[248:249], v[78:79] op_sel:[0,1,0] op_sel_hi:[1,1,1]
	v_cvt_pk_f32_fp8_e32 v[224:225], v136
	v_cvt_pk_f32_fp8_sdwa v[226:227], v136 src0_sel:WORD_1
	v_cvt_pk_f32_fp8_e32 v[228:229], v137
	v_cvt_pk_f32_fp8_sdwa v[230:231], v137 src0_sel:WORD_1
	v_pk_fma_f32 v[64:65], v[224:225], v[250:251], v[64:65] op_sel_hi:[1,0,1]
	v_pk_fma_f32 v[66:67], v[226:227], v[250:251], v[66:67] op_sel_hi:[1,0,1]
	v_pk_fma_f32 v[68:69], v[228:229], v[250:251], v[68:69] op_sel_hi:[1,0,1]
	v_pk_fma_f32 v[70:71], v[230:231], v[250:251], v[70:71] op_sel_hi:[1,0,1]
	v_cvt_pk_f32_fp8_e32 v[224:225], v138
	v_cvt_pk_f32_fp8_sdwa v[226:227], v138 src0_sel:WORD_1
	v_cvt_pk_f32_fp8_e32 v[228:229], v139
	v_cvt_pk_f32_fp8_sdwa v[230:231], v139 src0_sel:WORD_1
	v_pk_fma_f32 v[72:73], v[224:225], v[250:251], v[72:73] op_sel_hi:[1,0,1]
	v_pk_fma_f32 v[74:75], v[226:227], v[250:251], v[74:75] op_sel_hi:[1,0,1]
	v_pk_fma_f32 v[76:77], v[228:229], v[250:251], v[76:77] op_sel_hi:[1,0,1]
	v_pk_fma_f32 v[78:79], v[230:231], v[250:251], v[78:79] op_sel_hi:[1,0,1]
	v_cvt_pk_f32_fp8_e32 v[224:225], v140
	v_cvt_pk_f32_fp8_sdwa v[226:227], v140 src0_sel:WORD_1
	v_cvt_pk_f32_fp8_e32 v[228:229], v141
	v_cvt_pk_f32_fp8_sdwa v[230:231], v141 src0_sel:WORD_1
	v_pk_fma_f32 v[64:65], v[224:225], v[250:251], v[64:65] op_sel:[0,1,0] op_sel_hi:[1,1,1]
	v_pk_fma_f32 v[66:67], v[226:227], v[250:251], v[66:67] op_sel:[0,1,0] op_sel_hi:[1,1,1]
	v_pk_fma_f32 v[68:69], v[228:229], v[250:251], v[68:69] op_sel:[0,1,0] op_sel_hi:[1,1,1]
	v_pk_fma_f32 v[70:71], v[230:231], v[250:251], v[70:71] op_sel:[0,1,0] op_sel_hi:[1,1,1]
	v_cvt_pk_f32_fp8_e32 v[224:225], v142
	v_cvt_pk_f32_fp8_sdwa v[226:227], v142 src0_sel:WORD_1
	v_cvt_pk_f32_fp8_e32 v[228:229], v143
	v_cvt_pk_f32_fp8_sdwa v[230:231], v143 src0_sel:WORD_1
	v_pk_fma_f32 v[72:73], v[224:225], v[250:251], v[72:73] op_sel:[0,1,0] op_sel_hi:[1,1,1]
	v_pk_fma_f32 v[74:75], v[226:227], v[250:251], v[74:75] op_sel:[0,1,0] op_sel_hi:[1,1,1]
	v_pk_fma_f32 v[76:77], v[228:229], v[250:251], v[76:77] op_sel:[0,1,0] op_sel_hi:[1,1,1]
	v_pk_fma_f32 v[78:79], v[230:231], v[250:251], v[78:79] op_sel:[0,1,0] op_sel_hi:[1,1,1]
	s_sub_i32 s90, s90, 1
	s_cmp_eq_u32 s90, 0
	s_cbranch_scc1 .LV_sw1
.LV_t4_s1:
	s_waitcnt lgkmcnt(0)
	buffer_load_dwordx4 v[128:131], v[232:233], s[60:63], 0 idxen offen
	buffer_load_dwordx4 v[132:135], v[234:235], s[60:63], 0 idxen offen
	buffer_load_dwordx4 v[136:139], v[236:237], s[60:63], 0 idxen offen
	buffer_load_dwordx4 v[140:143], v[238:239], s[60:63], 0 idxen offen
	ds_read_b32 v232, v213 offset:96
	ds_read_b32 v234, v213 offset:100
	ds_read_b32 v236, v213 offset:104
	ds_read_b32 v238, v213 offset:108
	ds_read_b128 v[248:251], v213 offset:5024
	s_waitcnt vmcnt(16)
	v_cvt_pk_f32_fp8_e32 v[224:225], v144
	v_cvt_pk_f32_fp8_sdwa v[226:227], v144 src0_sel:WORD_1
	v_cvt_pk_f32_fp8_e32 v[228:229], v145
	v_cvt_pk_f32_fp8_sdwa v[230:231], v145 src0_sel:WORD_1
	v_pk_fma_f32 v[64:65], v[224:225], v[252:253], v[64:65] op_sel_hi:[1,0,1]
	v_pk_fma_f32 v[66:67], v[226:227], v[252:253], v[66:67] op_sel_hi:[1,0,1]
	v_pk_fma_f32 v[68:69], v[228:229], v[252:253], v[68:69] op_sel_hi:[1,0,1]
	v_pk_fma_f32 v[70:71], v[230:231], v[252:253], v[70:71] op_sel_hi:[1,0,1]
	v_cvt_pk_f32_fp8_e32 v[224:225], v146
	v_cvt_pk_f32_fp8_sdwa v[226:227], v146 src0_sel:WORD_1
	v_cvt_pk_f32_fp8_e32 v[228:229], v147
	v_cvt_pk_f32_fp8_sdwa v[230:231], v147 src0_sel:WORD_1
	v_pk_fma_f32 v[72:73], v[224:225], v[252:253], v[72:73] op_sel_hi:[1,0,1]
	v_pk_fma_f32 v[74:75], v[226:227], v[252:253], v[74:75] op_sel_hi:[1,0,1]
	v_pk_fma_f32 v[76:77], v[228:229], v[252:253], v[76:77] op_sel_hi:[1,0,1]
	v_pk_fma_f32 v[78:79], v[230:231], v[252:253], v[78:79] op_sel_hi:[1,0,1]
	v_cvt_pk_f32_fp8_e32 v[224:225], v148
	v_cvt_pk_f32_fp8_sdwa v[226:227], v148 src0_sel:WORD_1
	v_cvt_pk_f32_fp8_e32 v[228:229], v149
	v_cvt_pk_f32_fp8_sdwa v[230:231], v149 src0_sel:WORD_1
	v_pk_fma_f32 v[64:65], v[224:225], v[252:253], v[64:65] op_sel:[0,1,0] op_sel_hi:[1,1,1]
	v_pk_fma_f32 v[66:67], v[226:227], v[252:253], v[66:67] op_sel:[0,1,0] op_sel_hi:[1,1,1]
	v_pk_fma_f32 v[68:69], v[228:229], v[252:253], v[68:69] op_sel:[0,1,0] op_sel_hi:[1,1,1]
	v_pk_fma_f32 v[70:71], v[230:231], v[252:253], v[70:71] op_sel:[0,1,0] op_sel_hi:[1,1,1]
	v_cvt_pk_f32_fp8_e32 v[224:225], v150
	v_cvt_pk_f32_fp8_sdwa v[226:227], v150 src0_sel:WORD_1
	v_cvt_pk_f32_fp8_e32 v[228:229], v151
	v_cvt_pk_f32_fp8_sdwa v[230:231], v151 src0_sel:WORD_1
	v_pk_fma_f32 v[72:73], v[224:225], v[252:253], v[72:73] op_sel:[0,1,0] op_sel_hi:[1,1,1]
	v_pk_fma_f32 v[74:75], v[226:227], v[252:253], v[74:75] op_sel:[0,1,0] op_sel_hi:[1,1,1]
	v_pk_fma_f32 v[76:77], v[228:229], v[252:253], v[76:77] op_sel:[0,1,0] op_sel_hi:[1,1,1]
	v_pk_fma_f32 v[78:79], v[230:231], v[252:253], v[78:79] op_sel:[0,1,0] op_sel_hi:[1,1,1]
	v_cvt_pk_f32_fp8_e32 v[224:225], v152
	v_cvt_pk_f32_fp8_sdwa v[226:227], v152 src0_sel:WORD_1
	v_cvt_pk_f32_fp8_e32 v[228:229], v153
	v_cvt_pk_f32_fp8_sdwa v[230:231], v153 src0_sel:WORD_1
	v_pk_fma_f32 v[64:65], v[224:225], v[254:255], v[64:65] op_sel_hi:[1,0,1]
	v_pk_fma_f32 v[66:67], v[226:227], v[254:255], v[66:67] op_sel_hi:[1,0,1]
	v_pk_fma_f32 v[68:69], v[228:229], v[254:255], v[68:69] op_sel_hi:[1,0,1]
	v_pk_fma_f32 v[70:71], v[230:231], v[254:255], v[70:71] op_sel_hi:[1,0,1]
	v_cvt_pk_f32_fp8_e32 v[224:225], v154
	v_cvt_pk_f32_fp8_sdwa v[226:227], v154 src0_sel:WORD_1
	v_cvt_pk_f32_fp8_e32 v[228:229], v155
	v_cvt_pk_f32_fp8_sdwa v[230:231], v155 src0_sel:WORD_1
	v_pk_fma_f32 v[72:73], v[224:225], v[254:255], v[72:73] op_sel_hi:[1,0,1]
	v_pk_fma_f32 v[74:75], v[226:227], v[254:255], v[74:75] op_sel_hi:[1,0,1]
	v_pk_fma_f32 v[76:77], v[228:229], v[254:255], v[76:77] op_sel_hi:[1,0,1]
	v_pk_fma_f32 v[78:79], v[230:231], v[254:255], v[78:79] op_sel_hi:[1,0,1]
	v_cvt_pk_f32_fp8_e32 v[224:225], v156
	v_cvt_pk_f32_fp8_sdwa v[226:227], v156 src0_sel:WORD_1
	v_cvt_pk_f32_fp8_e32 v[228:229], v157
	v_cvt_pk_f32_fp8_sdwa v[230:231], v157 src0_sel:WORD_1
	v_pk_fma_f32 v[64:65], v[224:225], v[254:255], v[64:65] op_sel:[0,1,0] op_sel_hi:[1,1,1]
	v_pk_fma_f32 v[66:67], v[226:227], v[254:255], v[66:67] op_sel:[0,1,0] op_sel_hi:[1,1,1]
	v_pk_fma_f32 v[68:69], v[228:229], v[254:255], v[68:69] op_sel:[0,1,0] op_sel_hi:[1,1,1]
	v_pk_fma_f32 v[70:71], v[230:231], v[254:255], v[70:71] op_sel:[0,1,0] op_sel_hi:[1,1,1]
	v_cvt_pk_f32_fp8_e32 v[224:225], v158
	v_cvt_pk_f32_fp8_sdwa v[226:227], v158 src0_sel:WORD_1
	v_cvt_pk_f32_fp8_e32 v[228:229], v159
	v_cvt_pk_f32_fp8_sdwa v[230:231], v159 src0_sel:WORD_1
	v_pk_fma_f32 v[72:73], v[224:225], v[254:255], v[72:73] op_sel:[0,1,0] op_sel_hi:[1,1,1]
	v_pk_fma_f32 v[74:75], v[226:227], v[254:255], v[74:75] op_sel:[0,1,0] op_sel_hi:[1,1,1]
	v_pk_fma_f32 v[76:77], v[228:229], v[254:255], v[76:77] op_sel:[0,1,0] op_sel_hi:[1,1,1]
	v_pk_fma_f32 v[78:79], v[230:231], v[254:255], v[78:79] op_sel:[0,1,0] op_sel_hi:[1,1,1]
	s_sub_i32 s90, s90, 1
	s_cmp_eq_u32 s90, 0
	s_cbranch_scc1 .LV_sw2
.LV_t4_s2:
	s_waitcnt lgkmcnt(0)
	buffer_load_dwordx4 v[144:147], v[232:233], s[60:63], 0 idxen offen
	buffer_load_dwordx4 v[148:151], v[234:235], s[60:63], 0 idxen offen
	buffer_load_dwordx4 v[152:155], v[236:237], s[60:63], 0 idxen offen
	buffer_load_dwordx4 v[156:159], v[238:239], s[60:63], 0 idxen offen
	ds_read_b32 v232, v213 offset:112
	ds_read_b32 v234, v213 offset:116
	ds_read_b32 v236, v213 offset:120
	ds_read_b32 v238, v213 offset:124
	ds_read_b128 v[252:255], v213 offset:5040
	s_waitcnt vmcnt(16)
	v_cvt_pk_f32_fp8_e32 v[224:225], v160
	v_cvt_pk_f32_fp8_sdwa v[226:227], v160 src0_sel:WORD_1
	v_cvt_pk_f32_fp8_e32 v[228:229], v161
	v_cvt_pk_f32_fp8_sdwa v[230:231], v161 src0_sel:WORD_1
	v_pk_fma_f32 v[64:65], v[224:225], v[248:249], v[64:65] op_sel_hi:[1,0,1]
	v_pk_fma_f32 v[66:67], v[226:227], v[248:249], v[66:67] op_sel_hi:[1,0,1]
	v_pk_fma_f32 v[68:69], v[228:229], v[248:249], v[68:69] op_sel_hi:[1,0,1]
	v_pk_fma_f32 v[70:71], v[230:231], v[248:249], v[70:71] op_sel_hi:[1,0,1]
	v_cvt_pk_f32_fp8_e32 v[224:225], v162
	v_cvt_pk_f32_fp8_sdwa v[226:227], v162 src0_sel:WORD_1
	v_cvt_pk_f32_fp8_e32 v[228:229], v163
	v_cvt_pk_f32_fp8_sdwa v[230:231], v163 src0_sel:WORD_1
	v_pk_fma_f32 v[72:73], v[224:225], v[248:249], v[72:73] op_sel_hi:[1,0,1]
	v_pk_fma_f32 v[74:75], v[226:227], v[248:249], v[74:75] op_sel_hi:[1,0,1]
	v_pk_fma_f32 v[76:77], v[228:229], v[248:249], v[76:77] op_sel_hi:[1,0,1]
	v_pk_fma_f32 v[78:79], v[230:231], v[248:249], v[78:79] op_sel_hi:[1,0,1]
	v_cvt_pk_f32_fp8_e32 v[224:225], v164
	v_cvt_pk_f32_fp8_sdwa v[226:227], v164 src0_sel:WORD_1
	v_cvt_pk_f32_fp8_e32 v[228:229], v165
	v_cvt_pk_f32_fp8_sdwa v[230:231], v165 src0_sel:WORD_1
	v_pk_fma_f32 v[64:65], v[224:225], v[248:249], v[64:65] op_sel:[0,1,0] op_sel_hi:[1,1,1]
	v_pk_fma_f32 v[66:67], v[226:227], v[248:249], v[66:67] op_sel:[0,1,0] op_sel_hi:[1,1,1]
	v_pk_fma_f32 v[68:69], v[228:229], v[248:249], v[68:69] op_sel:[0,1,0] op_sel_hi:[1,1,1]
	v_pk_fma_f32 v[70:71], v[230:231], v[248:249], v[70:71] op_sel:[0,1,0] op_sel_hi:[1,1,1]
	v_cvt_pk_f32_fp8_e32 v[224:225], v166
	v_cvt_pk_f32_fp8_sdwa v[226:227], v166 src0_sel:WORD_1
	v_cvt_pk_f32_fp8_e32 v[228:229], v167
	v_cvt_pk_f32_fp8_sdwa v[230:231], v167 src0_sel:WORD_1
	v_pk_fma_f32 v[72:73], v[224:225], v[248:249], v[72:73] op_sel:[0,1,0] op_sel_hi:[1,1,1]
	v_pk_fma_f32 v[74:75], v[226:227], v[248:249], v[74:75] op_sel:[0,1,0] op_sel_hi:[1,1,1]
	v_pk_fma_f32 v[76:77], v[228:229], v[248:249], v[76:77] op_sel:[0,1,0] op_sel_hi:[1,1,1]
	v_pk_fma_f32 v[78:79], v[230:231], v[248:249], v[78:79] op_sel:[0,1,0] op_sel_hi:[1,1,1]
	v_cvt_pk_f32_fp8_e32 v[224:225], v168
	v_cvt_pk_f32_fp8_sdwa v[226:227], v168 src0_sel:WORD_1
	v_cvt_pk_f32_fp8_e32 v[228:229], v169
	v_cvt_pk_f32_fp8_sdwa v[230:231], v169 src0_sel:WORD_1
	v_pk_fma_f32 v[64:65], v[224:225], v[250:251], v[64:65] op_sel_hi:[1,0,1]
	v_pk_fma_f32 v[66:67], v[226:227], v[250:251], v[66:67] op_sel_hi:[1,0,1]
	v_pk_fma_f32 v[68:69], v[228:229], v[250:251], v[68:69] op_sel_hi:[1,0,1]
	v_pk_fma_f32 v[70:71], v[230:231], v[250:251], v[70:71] op_sel_hi:[1,0,1]
	v_cvt_pk_f32_fp8_e32 v[224:225], v170
	v_cvt_pk_f32_fp8_sdwa v[226:227], v170 src0_sel:WORD_1
	v_cvt_pk_f32_fp8_e32 v[228:229], v171
	v_cvt_pk_f32_fp8_sdwa v[230:231], v171 src0_sel:WORD_1
	v_pk_fma_f32 v[72:73], v[224:225], v[250:251], v[72:73] op_sel_hi:[1,0,1]
	v_pk_fma_f32 v[74:75], v[226:227], v[250:251], v[74:75] op_sel_hi:[1,0,1]
	v_pk_fma_f32 v[76:77], v[228:229], v[250:251], v[76:77] op_sel_hi:[1,0,1]
	v_pk_fma_f32 v[78:79], v[230:231], v[250:251], v[78:79] op_sel_hi:[1,0,1]
	v_cvt_pk_f32_fp8_e32 v[224:225], v172
	v_cvt_pk_f32_fp8_sdwa v[226:227], v172 src0_sel:WORD_1
	v_cvt_pk_f32_fp8_e32 v[228:229], v173
	v_cvt_pk_f32_fp8_sdwa v[230:231], v173 src0_sel:WORD_1
	v_pk_fma_f32 v[64:65], v[224:225], v[250:251], v[64:65] op_sel:[0,1,0] op_sel_hi:[1,1,1]
	v_pk_fma_f32 v[66:67], v[226:227], v[250:251], v[66:67] op_sel:[0,1,0] op_sel_hi:[1,1,1]
	v_pk_fma_f32 v[68:69], v[228:229], v[250:251], v[68:69] op_sel:[0,1,0] op_sel_hi:[1,1,1]
	v_pk_fma_f32 v[70:71], v[230:231], v[250:251], v[70:71] op_sel:[0,1,0] op_sel_hi:[1,1,1]
	v_cvt_pk_f32_fp8_e32 v[224:225], v174
	v_cvt_pk_f32_fp8_sdwa v[226:227], v174 src0_sel:WORD_1
	v_cvt_pk_f32_fp8_e32 v[228:229], v175
	v_cvt_pk_f32_fp8_sdwa v[230:231], v175 src0_sel:WORD_1
	v_pk_fma_f32 v[72:73], v[224:225], v[250:251], v[72:73] op_sel:[0,1,0] op_sel_hi:[1,1,1]
	v_pk_fma_f32 v[74:75], v[226:227], v[250:251], v[74:75] op_sel:[0,1,0] op_sel_hi:[1,1,1]
	v_pk_fma_f32 v[76:77], v[228:229], v[250:251], v[76:77] op_sel:[0,1,0] op_sel_hi:[1,1,1]
	v_pk_fma_f32 v[78:79], v[230:231], v[250:251], v[78:79] op_sel:[0,1,0] op_sel_hi:[1,1,1]
	s_sub_i32 s90, s90, 1
	s_cmp_eq_u32 s90, 0
	s_cbranch_scc1 .LV_sw3
.LV_t4_s3:
	s_waitcnt lgkmcnt(0)
	buffer_load_dwordx4 v[160:163], v[232:233], s[60:63], 0 idxen offen
	buffer_load_dwordx4 v[164:167], v[234:235], s[60:63], 0 idxen offen
	buffer_load_dwordx4 v[168:171], v[236:237], s[60:63], 0 idxen offen
	buffer_load_dwordx4 v[172:175], v[238:239], s[60:63], 0 idxen offen
	ds_read_b32 v232, v213 offset:128
	ds_read_b32 v234, v213 offset:132
	ds_read_b32 v236, v213 offset:136
	ds_read_b32 v238, v213 offset:140
	ds_read_b128 v[208:211], v213 offset:5056
	s_waitcnt vmcnt(16)
	v_cvt_pk_f32_fp8_e32 v[224:225], v176
	v_cvt_pk_f32_fp8_sdwa v[226:227], v176 src0_sel:WORD_1
	v_cvt_pk_f32_fp8_e32 v[228:229], v177
	v_cvt_pk_f32_fp8_sdwa v[230:231], v177 src0_sel:WORD_1
	v_pk_fma_f32 v[64:65], v[224:225], v[252:253], v[64:65] op_sel_hi:[1,0,1]
	v_pk_fma_f32 v[66:67], v[226:227], v[252:253], v[66:67] op_sel_hi:[1,0,1]
	v_pk_fma_f32 v[68:69], v[228:229], v[252:253], v[68:69] op_sel_hi:[1,0,1]
	v_pk_fma_f32 v[70:71], v[230:231], v[252:253], v[70:71] op_sel_hi:[1,0,1]
	v_cvt_pk_f32_fp8_e32 v[224:225], v178
	v_cvt_pk_f32_fp8_sdwa v[226:227], v178 src0_sel:WORD_1
	v_cvt_pk_f32_fp8_e32 v[228:229], v179
	v_cvt_pk_f32_fp8_sdwa v[230:231], v179 src0_sel:WORD_1
	v_pk_fma_f32 v[72:73], v[224:225], v[252:253], v[72:73] op_sel_hi:[1,0,1]
	v_pk_fma_f32 v[74:75], v[226:227], v[252:253], v[74:75] op_sel_hi:[1,0,1]
	v_pk_fma_f32 v[76:77], v[228:229], v[252:253], v[76:77] op_sel_hi:[1,0,1]
	v_pk_fma_f32 v[78:79], v[230:231], v[252:253], v[78:79] op_sel_hi:[1,0,1]
	v_cvt_pk_f32_fp8_e32 v[224:225], v180
	v_cvt_pk_f32_fp8_sdwa v[226:227], v180 src0_sel:WORD_1
	v_cvt_pk_f32_fp8_e32 v[228:229], v181
	v_cvt_pk_f32_fp8_sdwa v[230:231], v181 src0_sel:WORD_1
	v_pk_fma_f32 v[64:65], v[224:225], v[252:253], v[64:65] op_sel:[0,1,0] op_sel_hi:[1,1,1]
	v_pk_fma_f32 v[66:67], v[226:227], v[252:253], v[66:67] op_sel:[0,1,0] op_sel_hi:[1,1,1]
	v_pk_fma_f32 v[68:69], v[228:229], v[252:253], v[68:69] op_sel:[0,1,0] op_sel_hi:[1,1,1]
	v_pk_fma_f32 v[70:71], v[230:231], v[252:253], v[70:71] op_sel:[0,1,0] op_sel_hi:[1,1,1]
	v_cvt_pk_f32_fp8_e32 v[224:225], v182
	v_cvt_pk_f32_fp8_sdwa v[226:227], v182 src0_sel:WORD_1
	v_cvt_pk_f32_fp8_e32 v[228:229], v183
	v_cvt_pk_f32_fp8_sdwa v[230:231], v183 src0_sel:WORD_1
	v_pk_fma_f32 v[72:73], v[224:225], v[252:253], v[72:73] op_sel:[0,1,0] op_sel_hi:[1,1,1]
	v_pk_fma_f32 v[74:75], v[226:227], v[252:253], v[74:75] op_sel:[0,1,0] op_sel_hi:[1,1,1]
	v_pk_fma_f32 v[76:77], v[228:229], v[252:253], v[76:77] op_sel:[0,1,0] op_sel_hi:[1,1,1]
	v_pk_fma_f32 v[78:79], v[230:231], v[252:253], v[78:79] op_sel:[0,1,0] op_sel_hi:[1,1,1]
	v_cvt_pk_f32_fp8_e32 v[224:225], v184
	v_cvt_pk_f32_fp8_sdwa v[226:227], v184 src0_sel:WORD_1
	v_cvt_pk_f32_fp8_e32 v[228:229], v185
	v_cvt_pk_f32_fp8_sdwa v[230:231], v185 src0_sel:WORD_1
	v_pk_fma_f32 v[64:65], v[224:225], v[254:255], v[64:65] op_sel_hi:[1,0,1]
	v_pk_fma_f32 v[66:67], v[226:227], v[254:255], v[66:67] op_sel_hi:[1,0,1]
	v_pk_fma_f32 v[68:69], v[228:229], v[254:255], v[68:69] op_sel_hi:[1,0,1]
	v_pk_fma_f32 v[70:71], v[230:231], v[254:255], v[70:71] op_sel_hi:[1,0,1]
	v_cvt_pk_f32_fp8_e32 v[224:225], v186
	v_cvt_pk_f32_fp8_sdwa v[226:227], v186 src0_sel:WORD_1
	v_cvt_pk_f32_fp8_e32 v[228:229], v187
	v_cvt_pk_f32_fp8_sdwa v[230:231], v187 src0_sel:WORD_1
	v_pk_fma_f32 v[72:73], v[224:225], v[254:255], v[72:73] op_sel_hi:[1,0,1]
	v_pk_fma_f32 v[74:75], v[226:227], v[254:255], v[74:75] op_sel_hi:[1,0,1]
	v_pk_fma_f32 v[76:77], v[228:229], v[254:255], v[76:77] op_sel_hi:[1,0,1]
	v_pk_fma_f32 v[78:79], v[230:231], v[254:255], v[78:79] op_sel_hi:[1,0,1]
	v_cvt_pk_f32_fp8_e32 v[224:225], v188
	v_cvt_pk_f32_fp8_sdwa v[226:227], v188 src0_sel:WORD_1
	v_cvt_pk_f32_fp8_e32 v[228:229], v189
	v_cvt_pk_f32_fp8_sdwa v[230:231], v189 src0_sel:WORD_1
	v_pk_fma_f32 v[64:65], v[224:225], v[254:255], v[64:65] op_sel:[0,1,0] op_sel_hi:[1,1,1]
	v_pk_fma_f32 v[66:67], v[226:227], v[254:255], v[66:67] op_sel:[0,1,0] op_sel_hi:[1,1,1]
	v_pk_fma_f32 v[68:69], v[228:229], v[254:255], v[68:69] op_sel:[0,1,0] op_sel_hi:[1,1,1]
	v_pk_fma_f32 v[70:71], v[230:231], v[254:255], v[70:71] op_sel:[0,1,0] op_sel_hi:[1,1,1]
	v_cvt_pk_f32_fp8_e32 v[224:225], v190
	v_cvt_pk_f32_fp8_sdwa v[226:227], v190 src0_sel:WORD_1
	v_cvt_pk_f32_fp8_e32 v[228:229], v191
	v_cvt_pk_f32_fp8_sdwa v[230:231], v191 src0_sel:WORD_1
	v_pk_fma_f32 v[72:73], v[224:225], v[254:255], v[72:73] op_sel:[0,1,0] op_sel_hi:[1,1,1]
	v_pk_fma_f32 v[74:75], v[226:227], v[254:255], v[74:75] op_sel:[0,1,0] op_sel_hi:[1,1,1]
	v_pk_fma_f32 v[76:77], v[228:229], v[254:255], v[76:77] op_sel:[0,1,0] op_sel_hi:[1,1,1]
	v_pk_fma_f32 v[78:79], v[230:231], v[254:255], v[78:79] op_sel:[0,1,0] op_sel_hi:[1,1,1]
	s_sub_i32 s90, s90, 1
	s_cmp_eq_u32 s90, 0
	s_cbranch_scc1 .LV_sw4
.LV_t4_s4:
	s_waitcnt lgkmcnt(0)
	buffer_load_dwordx4 v[176:179], v[232:233], s[60:63], 0 idxen offen
	buffer_load_dwordx4 v[180:183], v[234:235], s[60:63], 0 idxen offen
	buffer_load_dwordx4 v[184:187], v[236:237], s[60:63], 0 idxen offen
	buffer_load_dwordx4 v[188:191], v[238:239], s[60:63], 0 idxen offen
	ds_read_b32 v232, v213 offset:144
	ds_read_b32 v234, v213 offset:148
	ds_read_b32 v236, v213 offset:152
	ds_read_b32 v238, v213 offset:156
	ds_read_b128 v[248:251], v213 offset:5072
	s_waitcnt vmcnt(16)
	v_cvt_pk_f32_fp8_e32 v[224:225], v192
	v_cvt_pk_f32_fp8_sdwa v[226:227], v192 src0_sel:WORD_1
	v_cvt_pk_f32_fp8_e32 v[228:229], v193
	v_cvt_pk_f32_fp8_sdwa v[230:231], v193 src0_sel:WORD_1
	v_pk_fma_f32 v[64:65], v[224:225], v[208:209], v[64:65] op_sel_hi:[1,0,1]
	v_pk_fma_f32 v[66:67], v[226:227], v[208:209], v[66:67] op_sel_hi:[1,0,1]
	v_pk_fma_f32 v[68:69], v[228:229], v[208:209], v[68:69] op_sel_hi:[1,0,1]
	v_pk_fma_f32 v[70:71], v[230:231], v[208:209], v[70:71] op_sel_hi:[1,0,1]
	v_cvt_pk_f32_fp8_e32 v[224:225], v194
	v_cvt_pk_f32_fp8_sdwa v[226:227], v194 src0_sel:WORD_1
	v_cvt_pk_f32_fp8_e32 v[228:229], v195
	v_cvt_pk_f32_fp8_sdwa v[230:231], v195 src0_sel:WORD_1
	v_pk_fma_f32 v[72:73], v[224:225], v[208:209], v[72:73] op_sel_hi:[1,0,1]
	v_pk_fma_f32 v[74:75], v[226:227], v[208:209], v[74:75] op_sel_hi:[1,0,1]
	v_pk_fma_f32 v[76:77], v[228:229], v[208:209], v[76:77] op_sel_hi:[1,0,1]
	v_pk_fma_f32 v[78:79], v[230:231], v[208:209], v[78:79] op_sel_hi:[1,0,1]
	v_cvt_pk_f32_fp8_e32 v[224:225], v196
	v_cvt_pk_f32_fp8_sdwa v[226:227], v196 src0_sel:WORD_1
	v_cvt_pk_f32_fp8_e32 v[228:229], v197
	v_cvt_pk_f32_fp8_sdwa v[230:231], v197 src0_sel:WORD_1
	v_pk_fma_f32 v[64:65], v[224:225], v[208:209], v[64:65] op_sel:[0,1,0] op_sel_hi:[1,1,1]
	v_pk_fma_f32 v[66:67], v[226:227], v[208:209], v[66:67] op_sel:[0,1,0] op_sel_hi:[1,1,1]
	v_pk_fma_f32 v[68:69], v[228:229], v[208:209], v[68:69] op_sel:[0,1,0] op_sel_hi:[1,1,1]
	v_pk_fma_f32 v[70:71], v[230:231], v[208:209], v[70:71] op_sel:[0,1,0] op_sel_hi:[1,1,1]
	v_cvt_pk_f32_fp8_e32 v[224:225], v198
	v_cvt_pk_f32_fp8_sdwa v[226:227], v198 src0_sel:WORD_1
	v_cvt_pk_f32_fp8_e32 v[228:229], v199
	v_cvt_pk_f32_fp8_sdwa v[230:231], v199 src0_sel:WORD_1
	v_pk_fma_f32 v[72:73], v[224:225], v[208:209], v[72:73] op_sel:[0,1,0] op_sel_hi:[1,1,1]
	v_pk_fma_f32 v[74:75], v[226:227], v[208:209], v[74:75] op_sel:[0,1,0] op_sel_hi:[1,1,1]
	v_pk_fma_f32 v[76:77], v[228:229], v[208:209], v[76:77] op_sel:[0,1,0] op_sel_hi:[1,1,1]
	v_pk_fma_f32 v[78:79], v[230:231], v[208:209], v[78:79] op_sel:[0,1,0] op_sel_hi:[1,1,1]
	v_cvt_pk_f32_fp8_e32 v[224:225], v200
	v_cvt_pk_f32_fp8_sdwa v[226:227], v200 src0_sel:WORD_1
	v_cvt_pk_f32_fp8_e32 v[228:229], v201
	v_cvt_pk_f32_fp8_sdwa v[230:231], v201 src0_sel:WORD_1
	v_pk_fma_f32 v[64:65], v[224:225], v[210:211], v[64:65] op_sel_hi:[1,0,1]
	v_pk_fma_f32 v[66:67], v[226:227], v[210:211], v[66:67] op_sel_hi:[1,0,1]
	v_pk_fma_f32 v[68:69], v[228:229], v[210:211], v[68:69] op_sel_hi:[1,0,1]
	v_pk_fma_f32 v[70:71], v[230:231], v[210:211], v[70:71] op_sel_hi:[1,0,1]
	v_cvt_pk_f32_fp8_e32 v[224:225], v202
	v_cvt_pk_f32_fp8_sdwa v[226:227], v202 src0_sel:WORD_1
	v_cvt_pk_f32_fp8_e32 v[228:229], v203
	v_cvt_pk_f32_fp8_sdwa v[230:231], v203 src0_sel:WORD_1
	v_pk_fma_f32 v[72:73], v[224:225], v[210:211], v[72:73] op_sel_hi:[1,0,1]
	v_pk_fma_f32 v[74:75], v[226:227], v[210:211], v[74:75] op_sel_hi:[1,0,1]
	v_pk_fma_f32 v[76:77], v[228:229], v[210:211], v[76:77] op_sel_hi:[1,0,1]
	v_pk_fma_f32 v[78:79], v[230:231], v[210:211], v[78:79] op_sel_hi:[1,0,1]
	v_cvt_pk_f32_fp8_e32 v[224:225], v204
	v_cvt_pk_f32_fp8_sdwa v[226:227], v204 src0_sel:WORD_1
	v_cvt_pk_f32_fp8_e32 v[228:229], v205
	v_cvt_pk_f32_fp8_sdwa v[230:231], v205 src0_sel:WORD_1
	v_pk_fma_f32 v[64:65], v[224:225], v[210:211], v[64:65] op_sel:[0,1,0] op_sel_hi:[1,1,1]
	v_pk_fma_f32 v[66:67], v[226:227], v[210:211], v[66:67] op_sel:[0,1,0] op_sel_hi:[1,1,1]
	v_pk_fma_f32 v[68:69], v[228:229], v[210:211], v[68:69] op_sel:[0,1,0] op_sel_hi:[1,1,1]
	v_pk_fma_f32 v[70:71], v[230:231], v[210:211], v[70:71] op_sel:[0,1,0] op_sel_hi:[1,1,1]
	v_cvt_pk_f32_fp8_e32 v[224:225], v206
	v_cvt_pk_f32_fp8_sdwa v[226:227], v206 src0_sel:WORD_1
	v_cvt_pk_f32_fp8_e32 v[228:229], v207
	v_cvt_pk_f32_fp8_sdwa v[230:231], v207 src0_sel:WORD_1
	v_pk_fma_f32 v[72:73], v[224:225], v[210:211], v[72:73] op_sel:[0,1,0] op_sel_hi:[1,1,1]
	v_pk_fma_f32 v[74:75], v[226:227], v[210:211], v[74:75] op_sel:[0,1,0] op_sel_hi:[1,1,1]
	v_pk_fma_f32 v[76:77], v[228:229], v[210:211], v[76:77] op_sel:[0,1,0] op_sel_hi:[1,1,1]
	v_pk_fma_f32 v[78:79], v[230:231], v[210:211], v[78:79] op_sel:[0,1,0] op_sel_hi:[1,1,1]
	v_add_u32_e32 v213, 80, v213
	s_add_i32 s21, s21, 5
	s_sub_i32 s90, s90, 1
	s_cmp_eq_u32 s90, 0
	s_cbranch_scc1 .LV_sw0
	s_branch .LV_t4_s0
.LV_t5_s0:
	s_cmp_ge_u32 s21, s20
	s_cbranch_scc1 .LV_done
	s_waitcnt lgkmcnt(0)
	buffer_load_dwordx4 v[192:195], v[232:233], s[60:63], 0 idxen offen
	buffer_load_dwordx4 v[196:199], v[234:235], s[60:63], 0 idxen offen
	buffer_load_dwordx4 v[200:203], v[236:237], s[60:63], 0 idxen offen
	buffer_load_dwordx4 v[204:207], v[238:239], s[60:63], 0 idxen offen
	ds_read_b32 v232, v213 offset:80
	ds_read_b32 v234, v213 offset:84
	ds_read_b32 v236, v213 offset:88
	ds_read_b32 v238, v213 offset:92
	ds_read_b128 v[252:255], v213 offset:5008
	s_waitcnt vmcnt(16)
	v_cvt_pk_f32_fp8_e32 v[224:225], v128
	v_cvt_pk_f32_fp8_sdwa v[226:227], v128 src0_sel:WORD_1
	v_cvt_pk_f32_fp8_e32 v[228:229], v129
	v_cvt_pk_f32_fp8_sdwa v[230:231], v129 src0_sel:WORD_1
	v_pk_fma_f32 v[80:81], v[224:225], v[248:249], v[80:81] op_sel_hi:[1,0,1]
	v_pk_fma_f32 v[82:83], v[226:227], v[248:249], v[82:83] op_sel_hi:[1,0,1]
	v_pk_fma_f32 v[84:85], v[228:229], v[248:249], v[84:85] op_sel_hi:[1,0,1]
	v_pk_fma_f32 v[86:87], v[230:231], v[248:249], v[86:87] op_sel_hi:[1,0,1]
	v_cvt_pk_f32_fp8_e32 v[224:225], v130
	v_cvt_pk_f32_fp8_sdwa v[226:227], v130 src0_sel:WORD_1
	v_cvt_pk_f32_fp8_e32 v[228:229], v131
	v_cvt_pk_f32_fp8_sdwa v[230:231], v131 src0_sel:WORD_1
	v_pk_fma_f32 v[88:89], v[224:225], v[248:249], v[88:89] op_sel_hi:[1,0,1]
	v_pk_fma_f32 v[90:91], v[226:227], v[248:249], v[90:91] op_sel_hi:[1,0,1]
	v_pk_fma_f32 v[92:93], v[228:229], v[248:249], v[92:93] op_sel_hi:[1,0,1]
	v_pk_fma_f32 v[94:95], v[230:231], v[248:249], v[94:95] op_sel_hi:[1,0,1]
	v_cvt_pk_f32_fp8_e32 v[224:225], v132
	v_cvt_pk_f32_fp8_sdwa v[226:227], v132 src0_sel:WORD_1
	v_cvt_pk_f32_fp8_e32 v[228:229], v133
	v_cvt_pk_f32_fp8_sdwa v[230:231], v133 src0_sel:WORD_1
	v_pk_fma_f32 v[80:81], v[224:225], v[248:249], v[80:81] op_sel:[0,1,0] op_sel_hi:[1,1,1]
	v_pk_fma_f32 v[82:83], v[226:227], v[248:249], v[82:83] op_sel:[0,1,0] op_sel_hi:[1,1,1]
	v_pk_fma_f32 v[84:85], v[228:229], v[248:249], v[84:85] op_sel:[0,1,0] op_sel_hi:[1,1,1]
	v_pk_fma_f32 v[86:87], v[230:231], v[248:249], v[86:87] op_sel:[0,1,0] op_sel_hi:[1,1,1]
	v_cvt_pk_f32_fp8_e32 v[224:225], v134
	v_cvt_pk_f32_fp8_sdwa v[226:227], v134 src0_sel:WORD_1
	v_cvt_pk_f32_fp8_e32 v[228:229], v135
	v_cvt_pk_f32_fp8_sdwa v[230:231], v135 src0_sel:WORD_1
	v_pk_fma_f32 v[88:89], v[224:225], v[248:249], v[88:89] op_sel:[0,1,0] op_sel_hi:[1,1,1]
	v_pk_fma_f32 v[90:91], v[226:227], v[248:249], v[90:91] op_sel:[0,1,0] op_sel_hi:[1,1,1]
	v_pk_fma_f32 v[92:93], v[228:229], v[248:249], v[92:93] op_sel:[0,1,0] op_sel_hi:[1,1,1]
	v_pk_fma_f32 v[94:95], v[230:231], v[248:249], v[94:95] op_sel:[0,1,0] op_sel_hi:[1,1,1]
	v_cvt_pk_f32_fp8_e32 v[224:225], v136
	v_cvt_pk_f32_fp8_sdwa v[226:227], v136 src0_sel:WORD_1
	v_cvt_pk_f32_fp8_e32 v[228:229], v137
	v_cvt_pk_f32_fp8_sdwa v[230:231], v137 src0_sel:WORD_1
	v_pk_fma_f32 v[80:81], v[224:225], v[250:251], v[80:81] op_sel_hi:[1,0,1]
	v_pk_fma_f32 v[82:83], v[226:227], v[250:251], v[82:83] op_sel_hi:[1,0,1]
	v_pk_fma_f32 v[84:85], v[228:229], v[250:251], v[84:85] op_sel_hi:[1,0,1]
	v_pk_fma_f32 v[86:87], v[230:231], v[250:251], v[86:87] op_sel_hi:[1,0,1]
	v_cvt_pk_f32_fp8_e32 v[224:225], v138
	v_cvt_pk_f32_fp8_sdwa v[226:227], v138 src0_sel:WORD_1
	v_cvt_pk_f32_fp8_e32 v[228:229], v139
	v_cvt_pk_f32_fp8_sdwa v[230:231], v139 src0_sel:WORD_1
	v_pk_fma_f32 v[88:89], v[224:225], v[250:251], v[88:89] op_sel_hi:[1,0,1]
	v_pk_fma_f32 v[90:91], v[226:227], v[250:251], v[90:91] op_sel_hi:[1,0,1]
	v_pk_fma_f32 v[92:93], v[228:229], v[250:251], v[92:93] op_sel_hi:[1,0,1]
	v_pk_fma_f32 v[94:95], v[230:231], v[250:251], v[94:95] op_sel_hi:[1,0,1]
	v_cvt_pk_f32_fp8_e32 v[224:225], v140
	v_cvt_pk_f32_fp8_sdwa v[226:227], v140 src0_sel:WORD_1
	v_cvt_pk_f32_fp8_e32 v[228:229], v141
	v_cvt_pk_f32_fp8_sdwa v[230:231], v141 src0_sel:WORD_1
	v_pk_fma_f32 v[80:81], v[224:225], v[250:251], v[80:81] op_sel:[0,1,0] op_sel_hi:[1,1,1]
	v_pk_fma_f32 v[82:83], v[226:227], v[250:251], v[82:83] op_sel:[0,1,0] op_sel_hi:[1,1,1]
	v_pk_fma_f32 v[84:85], v[228:229], v[250:251], v[84:85] op_sel:[0,1,0] op_sel_hi:[1,1,1]
	v_pk_fma_f32 v[86:87], v[230:231], v[250:251], v[86:87] op_sel:[0,1,0] op_sel_hi:[1,1,1]
	v_cvt_pk_f32_fp8_e32 v[224:225], v142
	v_cvt_pk_f32_fp8_sdwa v[226:227], v142 src0_sel:WORD_1
	v_cvt_pk_f32_fp8_e32 v[228:229], v143
	v_cvt_pk_f32_fp8_sdwa v[230:231], v143 src0_sel:WORD_1
	v_pk_fma_f32 v[88:89], v[224:225], v[250:251], v[88:89] op_sel:[0,1,0] op_sel_hi:[1,1,1]
	v_pk_fma_f32 v[90:91], v[226:227], v[250:251], v[90:91] op_sel:[0,1,0] op_sel_hi:[1,1,1]
	v_pk_fma_f32 v[92:93], v[228:229], v[250:251], v[92:93] op_sel:[0,1,0] op_sel_hi:[1,1,1]
	v_pk_fma_f32 v[94:95], v[230:231], v[250:251], v[94:95] op_sel:[0,1,0] op_sel_hi:[1,1,1]
	s_sub_i32 s90, s90, 1
	s_cmp_eq_u32 s90, 0
	s_cbranch_scc1 .LV_sw1
.LV_t5_s1:
	s_waitcnt lgkmcnt(0)
	buffer_load_dwordx4 v[128:131], v[232:233], s[60:63], 0 idxen offen
	buffer_load_dwordx4 v[132:135], v[234:235], s[60:63], 0 idxen offen
	buffer_load_dwordx4 v[136:139], v[236:237], s[60:63], 0 idxen offen
	buffer_load_dwordx4 v[140:143], v[238:239], s[60:63], 0 idxen offen
	ds_read_b32 v232, v213 offset:96
	ds_read_b32 v234, v213 offset:100
	ds_read_b32 v236, v213 offset:104
	ds_read_b32 v238, v213 offset:108
	ds_read_b128 v[248:251], v213 offset:5024
	s_waitcnt vmcnt(16)
	v_cvt_pk_f32_fp8_e32 v[224:225], v144
	v_cvt_pk_f32_fp8_sdwa v[226:227], v144 src0_sel:WORD_1
	v_cvt_pk_f32_fp8_e32 v[228:229], v145
	v_cvt_pk_f32_fp8_sdwa v[230:231], v145 src0_sel:WORD_1
	v_pk_fma_f32 v[80:81], v[224:225], v[252:253], v[80:81] op_sel_hi:[1,0,1]
	v_pk_fma_f32 v[82:83], v[226:227], v[252:253], v[82:83] op_sel_hi:[1,0,1]
	v_pk_fma_f32 v[84:85], v[228:229], v[252:253], v[84:85] op_sel_hi:[1,0,1]
	v_pk_fma_f32 v[86:87], v[230:231], v[252:253], v[86:87] op_sel_hi:[1,0,1]
	v_cvt_pk_f32_fp8_e32 v[224:225], v146
	v_cvt_pk_f32_fp8_sdwa v[226:227], v146 src0_sel:WORD_1
	v_cvt_pk_f32_fp8_e32 v[228:229], v147
	v_cvt_pk_f32_fp8_sdwa v[230:231], v147 src0_sel:WORD_1
	v_pk_fma_f32 v[88:89], v[224:225], v[252:253], v[88:89] op_sel_hi:[1,0,1]
	v_pk_fma_f32 v[90:91], v[226:227], v[252:253], v[90:91] op_sel_hi:[1,0,1]
	v_pk_fma_f32 v[92:93], v[228:229], v[252:253], v[92:93] op_sel_hi:[1,0,1]
	v_pk_fma_f32 v[94:95], v[230:231], v[252:253], v[94:95] op_sel_hi:[1,0,1]
	v_cvt_pk_f32_fp8_e32 v[224:225], v148
	v_cvt_pk_f32_fp8_sdwa v[226:227], v148 src0_sel:WORD_1
	v_cvt_pk_f32_fp8_e32 v[228:229], v149
	v_cvt_pk_f32_fp8_sdwa v[230:231], v149 src0_sel:WORD_1
	v_pk_fma_f32 v[80:81], v[224:225], v[252:253], v[80:81] op_sel:[0,1,0] op_sel_hi:[1,1,1]
	v_pk_fma_f32 v[82:83], v[226:227], v[252:253], v[82:83] op_sel:[0,1,0] op_sel_hi:[1,1,1]
	v_pk_fma_f32 v[84:85], v[228:229], v[252:253], v[84:85] op_sel:[0,1,0] op_sel_hi:[1,1,1]
	v_pk_fma_f32 v[86:87], v[230:231], v[252:253], v[86:87] op_sel:[0,1,0] op_sel_hi:[1,1,1]
	v_cvt_pk_f32_fp8_e32 v[224:225], v150
	v_cvt_pk_f32_fp8_sdwa v[226:227], v150 src0_sel:WORD_1
	v_cvt_pk_f32_fp8_e32 v[228:229], v151
	v_cvt_pk_f32_fp8_sdwa v[230:231], v151 src0_sel:WORD_1
	v_pk_fma_f32 v[88:89], v[224:225], v[252:253], v[88:89] op_sel:[0,1,0] op_sel_hi:[1,1,1]
	v_pk_fma_f32 v[90:91], v[226:227], v[252:253], v[90:91] op_sel:[0,1,0] op_sel_hi:[1,1,1]
	v_pk_fma_f32 v[92:93], v[228:229], v[252:253], v[92:93] op_sel:[0,1,0] op_sel_hi:[1,1,1]
	v_pk_fma_f32 v[94:95], v[230:231], v[252:253], v[94:95] op_sel:[0,1,0] op_sel_hi:[1,1,1]
	v_cvt_pk_f32_fp8_e32 v[224:225], v152
	v_cvt_pk_f32_fp8_sdwa v[226:227], v152 src0_sel:WORD_1
	v_cvt_pk_f32_fp8_e32 v[228:229], v153
	v_cvt_pk_f32_fp8_sdwa v[230:231], v153 src0_sel:WORD_1
	v_pk_fma_f32 v[80:81], v[224:225], v[254:255], v[80:81] op_sel_hi:[1,0,1]
	v_pk_fma_f32 v[82:83], v[226:227], v[254:255], v[82:83] op_sel_hi:[1,0,1]
	v_pk_fma_f32 v[84:85], v[228:229], v[254:255], v[84:85] op_sel_hi:[1,0,1]
	v_pk_fma_f32 v[86:87], v[230:231], v[254:255], v[86:87] op_sel_hi:[1,0,1]
	v_cvt_pk_f32_fp8_e32 v[224:225], v154
	v_cvt_pk_f32_fp8_sdwa v[226:227], v154 src0_sel:WORD_1
	v_cvt_pk_f32_fp8_e32 v[228:229], v155
	v_cvt_pk_f32_fp8_sdwa v[230:231], v155 src0_sel:WORD_1
	v_pk_fma_f32 v[88:89], v[224:225], v[254:255], v[88:89] op_sel_hi:[1,0,1]
	v_pk_fma_f32 v[90:91], v[226:227], v[254:255], v[90:91] op_sel_hi:[1,0,1]
	v_pk_fma_f32 v[92:93], v[228:229], v[254:255], v[92:93] op_sel_hi:[1,0,1]
	v_pk_fma_f32 v[94:95], v[230:231], v[254:255], v[94:95] op_sel_hi:[1,0,1]
	v_cvt_pk_f32_fp8_e32 v[224:225], v156
	v_cvt_pk_f32_fp8_sdwa v[226:227], v156 src0_sel:WORD_1
	v_cvt_pk_f32_fp8_e32 v[228:229], v157
	v_cvt_pk_f32_fp8_sdwa v[230:231], v157 src0_sel:WORD_1
	v_pk_fma_f32 v[80:81], v[224:225], v[254:255], v[80:81] op_sel:[0,1,0] op_sel_hi:[1,1,1]
	v_pk_fma_f32 v[82:83], v[226:227], v[254:255], v[82:83] op_sel:[0,1,0] op_sel_hi:[1,1,1]
	v_pk_fma_f32 v[84:85], v[228:229], v[254:255], v[84:85] op_sel:[0,1,0] op_sel_hi:[1,1,1]
	v_pk_fma_f32 v[86:87], v[230:231], v[254:255], v[86:87] op_sel:[0,1,0] op_sel_hi:[1,1,1]
	v_cvt_pk_f32_fp8_e32 v[224:225], v158
	v_cvt_pk_f32_fp8_sdwa v[226:227], v158 src0_sel:WORD_1
	v_cvt_pk_f32_fp8_e32 v[228:229], v159
	v_cvt_pk_f32_fp8_sdwa v[230:231], v159 src0_sel:WORD_1
	v_pk_fma_f32 v[88:89], v[224:225], v[254:255], v[88:89] op_sel:[0,1,0] op_sel_hi:[1,1,1]
	v_pk_fma_f32 v[90:91], v[226:227], v[254:255], v[90:91] op_sel:[0,1,0] op_sel_hi:[1,1,1]
	v_pk_fma_f32 v[92:93], v[228:229], v[254:255], v[92:93] op_sel:[0,1,0] op_sel_hi:[1,1,1]
	v_pk_fma_f32 v[94:95], v[230:231], v[254:255], v[94:95] op_sel:[0,1,0] op_sel_hi:[1,1,1]
	s_sub_i32 s90, s90, 1
	s_cmp_eq_u32 s90, 0
	s_cbranch_scc1 .LV_sw2
.LV_t5_s2:
	s_waitcnt lgkmcnt(0)
	buffer_load_dwordx4 v[144:147], v[232:233], s[60:63], 0 idxen offen
	buffer_load_dwordx4 v[148:151], v[234:235], s[60:63], 0 idxen offen
	buffer_load_dwordx4 v[152:155], v[236:237], s[60:63], 0 idxen offen
	buffer_load_dwordx4 v[156:159], v[238:239], s[60:63], 0 idxen offen
	ds_read_b32 v232, v213 offset:112
	ds_read_b32 v234, v213 offset:116
	ds_read_b32 v236, v213 offset:120
	ds_read_b32 v238, v213 offset:124
	ds_read_b128 v[252:255], v213 offset:5040
	s_waitcnt vmcnt(16)
	v_cvt_pk_f32_fp8_e32 v[224:225], v160
	v_cvt_pk_f32_fp8_sdwa v[226:227], v160 src0_sel:WORD_1
	v_cvt_pk_f32_fp8_e32 v[228:229], v161
	v_cvt_pk_f32_fp8_sdwa v[230:231], v161 src0_sel:WORD_1
	v_pk_fma_f32 v[80:81], v[224:225], v[248:249], v[80:81] op_sel_hi:[1,0,1]
	v_pk_fma_f32 v[82:83], v[226:227], v[248:249], v[82:83] op_sel_hi:[1,0,1]
	v_pk_fma_f32 v[84:85], v[228:229], v[248:249], v[84:85] op_sel_hi:[1,0,1]
	v_pk_fma_f32 v[86:87], v[230:231], v[248:249], v[86:87] op_sel_hi:[1,0,1]
	v_cvt_pk_f32_fp8_e32 v[224:225], v162
	v_cvt_pk_f32_fp8_sdwa v[226:227], v162 src0_sel:WORD_1
	v_cvt_pk_f32_fp8_e32 v[228:229], v163
	v_cvt_pk_f32_fp8_sdwa v[230:231], v163 src0_sel:WORD_1
	v_pk_fma_f32 v[88:89], v[224:225], v[248:249], v[88:89] op_sel_hi:[1,0,1]
	v_pk_fma_f32 v[90:91], v[226:227], v[248:249], v[90:91] op_sel_hi:[1,0,1]
	v_pk_fma_f32 v[92:93], v[228:229], v[248:249], v[92:93] op_sel_hi:[1,0,1]
	v_pk_fma_f32 v[94:95], v[230:231], v[248:249], v[94:95] op_sel_hi:[1,0,1]
	v_cvt_pk_f32_fp8_e32 v[224:225], v164
	v_cvt_pk_f32_fp8_sdwa v[226:227], v164 src0_sel:WORD_1
	v_cvt_pk_f32_fp8_e32 v[228:229], v165
	v_cvt_pk_f32_fp8_sdwa v[230:231], v165 src0_sel:WORD_1
	v_pk_fma_f32 v[80:81], v[224:225], v[248:249], v[80:81] op_sel:[0,1,0] op_sel_hi:[1,1,1]
	v_pk_fma_f32 v[82:83], v[226:227], v[248:249], v[82:83] op_sel:[0,1,0] op_sel_hi:[1,1,1]
	v_pk_fma_f32 v[84:85], v[228:229], v[248:249], v[84:85] op_sel:[0,1,0] op_sel_hi:[1,1,1]
	v_pk_fma_f32 v[86:87], v[230:231], v[248:249], v[86:87] op_sel:[0,1,0] op_sel_hi:[1,1,1]
	v_cvt_pk_f32_fp8_e32 v[224:225], v166
	v_cvt_pk_f32_fp8_sdwa v[226:227], v166 src0_sel:WORD_1
	v_cvt_pk_f32_fp8_e32 v[228:229], v167
	v_cvt_pk_f32_fp8_sdwa v[230:231], v167 src0_sel:WORD_1
	v_pk_fma_f32 v[88:89], v[224:225], v[248:249], v[88:89] op_sel:[0,1,0] op_sel_hi:[1,1,1]
	v_pk_fma_f32 v[90:91], v[226:227], v[248:249], v[90:91] op_sel:[0,1,0] op_sel_hi:[1,1,1]
	v_pk_fma_f32 v[92:93], v[228:229], v[248:249], v[92:93] op_sel:[0,1,0] op_sel_hi:[1,1,1]
	v_pk_fma_f32 v[94:95], v[230:231], v[248:249], v[94:95] op_sel:[0,1,0] op_sel_hi:[1,1,1]
	v_cvt_pk_f32_fp8_e32 v[224:225], v168
	v_cvt_pk_f32_fp8_sdwa v[226:227], v168 src0_sel:WORD_1
	v_cvt_pk_f32_fp8_e32 v[228:229], v169
	v_cvt_pk_f32_fp8_sdwa v[230:231], v169 src0_sel:WORD_1
	v_pk_fma_f32 v[80:81], v[224:225], v[250:251], v[80:81] op_sel_hi:[1,0,1]
	v_pk_fma_f32 v[82:83], v[226:227], v[250:251], v[82:83] op_sel_hi:[1,0,1]
	v_pk_fma_f32 v[84:85], v[228:229], v[250:251], v[84:85] op_sel_hi:[1,0,1]
	v_pk_fma_f32 v[86:87], v[230:231], v[250:251], v[86:87] op_sel_hi:[1,0,1]
	v_cvt_pk_f32_fp8_e32 v[224:225], v170
	v_cvt_pk_f32_fp8_sdwa v[226:227], v170 src0_sel:WORD_1
	v_cvt_pk_f32_fp8_e32 v[228:229], v171
	v_cvt_pk_f32_fp8_sdwa v[230:231], v171 src0_sel:WORD_1
	v_pk_fma_f32 v[88:89], v[224:225], v[250:251], v[88:89] op_sel_hi:[1,0,1]
	v_pk_fma_f32 v[90:91], v[226:227], v[250:251], v[90:91] op_sel_hi:[1,0,1]
	v_pk_fma_f32 v[92:93], v[228:229], v[250:251], v[92:93] op_sel_hi:[1,0,1]
	v_pk_fma_f32 v[94:95], v[230:231], v[250:251], v[94:95] op_sel_hi:[1,0,1]
	v_cvt_pk_f32_fp8_e32 v[224:225], v172
	v_cvt_pk_f32_fp8_sdwa v[226:227], v172 src0_sel:WORD_1
	v_cvt_pk_f32_fp8_e32 v[228:229], v173
	v_cvt_pk_f32_fp8_sdwa v[230:231], v173 src0_sel:WORD_1
	v_pk_fma_f32 v[80:81], v[224:225], v[250:251], v[80:81] op_sel:[0,1,0] op_sel_hi:[1,1,1]
	v_pk_fma_f32 v[82:83], v[226:227], v[250:251], v[82:83] op_sel:[0,1,0] op_sel_hi:[1,1,1]
	v_pk_fma_f32 v[84:85], v[228:229], v[250:251], v[84:85] op_sel:[0,1,0] op_sel_hi:[1,1,1]
	v_pk_fma_f32 v[86:87], v[230:231], v[250:251], v[86:87] op_sel:[0,1,0] op_sel_hi:[1,1,1]
	v_cvt_pk_f32_fp8_e32 v[224:225], v174
	v_cvt_pk_f32_fp8_sdwa v[226:227], v174 src0_sel:WORD_1
	v_cvt_pk_f32_fp8_e32 v[228:229], v175
	v_cvt_pk_f32_fp8_sdwa v[230:231], v175 src0_sel:WORD_1
	v_pk_fma_f32 v[88:89], v[224:225], v[250:251], v[88:89] op_sel:[0,1,0] op_sel_hi:[1,1,1]
	v_pk_fma_f32 v[90:91], v[226:227], v[250:251], v[90:91] op_sel:[0,1,0] op_sel_hi:[1,1,1]
	v_pk_fma_f32 v[92:93], v[228:229], v[250:251], v[92:93] op_sel:[0,1,0] op_sel_hi:[1,1,1]
	v_pk_fma_f32 v[94:95], v[230:231], v[250:251], v[94:95] op_sel:[0,1,0] op_sel_hi:[1,1,1]
	s_sub_i32 s90, s90, 1
	s_cmp_eq_u32 s90, 0
	s_cbranch_scc1 .LV_sw3
.LV_t5_s3:
	s_waitcnt lgkmcnt(0)
	buffer_load_dwordx4 v[160:163], v[232:233], s[60:63], 0 idxen offen
	buffer_load_dwordx4 v[164:167], v[234:235], s[60:63], 0 idxen offen
	buffer_load_dwordx4 v[168:171], v[236:237], s[60:63], 0 idxen offen
	buffer_load_dwordx4 v[172:175], v[238:239], s[60:63], 0 idxen offen
	ds_read_b32 v232, v213 offset:128
	ds_read_b32 v234, v213 offset:132
	ds_read_b32 v236, v213 offset:136
	ds_read_b32 v238, v213 offset:140
	ds_read_b128 v[208:211], v213 offset:5056
	s_waitcnt vmcnt(16)
	v_cvt_pk_f32_fp8_e32 v[224:225], v176
	v_cvt_pk_f32_fp8_sdwa v[226:227], v176 src0_sel:WORD_1
	v_cvt_pk_f32_fp8_e32 v[228:229], v177
	v_cvt_pk_f32_fp8_sdwa v[230:231], v177 src0_sel:WORD_1
	v_pk_fma_f32 v[80:81], v[224:225], v[252:253], v[80:81] op_sel_hi:[1,0,1]
	v_pk_fma_f32 v[82:83], v[226:227], v[252:253], v[82:83] op_sel_hi:[1,0,1]
	v_pk_fma_f32 v[84:85], v[228:229], v[252:253], v[84:85] op_sel_hi:[1,0,1]
	v_pk_fma_f32 v[86:87], v[230:231], v[252:253], v[86:87] op_sel_hi:[1,0,1]
	v_cvt_pk_f32_fp8_e32 v[224:225], v178
	v_cvt_pk_f32_fp8_sdwa v[226:227], v178 src0_sel:WORD_1
	v_cvt_pk_f32_fp8_e32 v[228:229], v179
	v_cvt_pk_f32_fp8_sdwa v[230:231], v179 src0_sel:WORD_1
	v_pk_fma_f32 v[88:89], v[224:225], v[252:253], v[88:89] op_sel_hi:[1,0,1]
	v_pk_fma_f32 v[90:91], v[226:227], v[252:253], v[90:91] op_sel_hi:[1,0,1]
	v_pk_fma_f32 v[92:93], v[228:229], v[252:253], v[92:93] op_sel_hi:[1,0,1]
	v_pk_fma_f32 v[94:95], v[230:231], v[252:253], v[94:95] op_sel_hi:[1,0,1]
	v_cvt_pk_f32_fp8_e32 v[224:225], v180
	v_cvt_pk_f32_fp8_sdwa v[226:227], v180 src0_sel:WORD_1
	v_cvt_pk_f32_fp8_e32 v[228:229], v181
	v_cvt_pk_f32_fp8_sdwa v[230:231], v181 src0_sel:WORD_1
	v_pk_fma_f32 v[80:81], v[224:225], v[252:253], v[80:81] op_sel:[0,1,0] op_sel_hi:[1,1,1]
	v_pk_fma_f32 v[82:83], v[226:227], v[252:253], v[82:83] op_sel:[0,1,0] op_sel_hi:[1,1,1]
	v_pk_fma_f32 v[84:85], v[228:229], v[252:253], v[84:85] op_sel:[0,1,0] op_sel_hi:[1,1,1]
	v_pk_fma_f32 v[86:87], v[230:231], v[252:253], v[86:87] op_sel:[0,1,0] op_sel_hi:[1,1,1]
	v_cvt_pk_f32_fp8_e32 v[224:225], v182
	v_cvt_pk_f32_fp8_sdwa v[226:227], v182 src0_sel:WORD_1
	v_cvt_pk_f32_fp8_e32 v[228:229], v183
	v_cvt_pk_f32_fp8_sdwa v[230:231], v183 src0_sel:WORD_1
	v_pk_fma_f32 v[88:89], v[224:225], v[252:253], v[88:89] op_sel:[0,1,0] op_sel_hi:[1,1,1]
	v_pk_fma_f32 v[90:91], v[226:227], v[252:253], v[90:91] op_sel:[0,1,0] op_sel_hi:[1,1,1]
	v_pk_fma_f32 v[92:93], v[228:229], v[252:253], v[92:93] op_sel:[0,1,0] op_sel_hi:[1,1,1]
	v_pk_fma_f32 v[94:95], v[230:231], v[252:253], v[94:95] op_sel:[0,1,0] op_sel_hi:[1,1,1]
	v_cvt_pk_f32_fp8_e32 v[224:225], v184
	v_cvt_pk_f32_fp8_sdwa v[226:227], v184 src0_sel:WORD_1
	v_cvt_pk_f32_fp8_e32 v[228:229], v185
	v_cvt_pk_f32_fp8_sdwa v[230:231], v185 src0_sel:WORD_1
	v_pk_fma_f32 v[80:81], v[224:225], v[254:255], v[80:81] op_sel_hi:[1,0,1]
	v_pk_fma_f32 v[82:83], v[226:227], v[254:255], v[82:83] op_sel_hi:[1,0,1]
	v_pk_fma_f32 v[84:85], v[228:229], v[254:255], v[84:85] op_sel_hi:[1,0,1]
	v_pk_fma_f32 v[86:87], v[230:231], v[254:255], v[86:87] op_sel_hi:[1,0,1]
	v_cvt_pk_f32_fp8_e32 v[224:225], v186
	v_cvt_pk_f32_fp8_sdwa v[226:227], v186 src0_sel:WORD_1
	v_cvt_pk_f32_fp8_e32 v[228:229], v187
	v_cvt_pk_f32_fp8_sdwa v[230:231], v187 src0_sel:WORD_1
	v_pk_fma_f32 v[88:89], v[224:225], v[254:255], v[88:89] op_sel_hi:[1,0,1]
	v_pk_fma_f32 v[90:91], v[226:227], v[254:255], v[90:91] op_sel_hi:[1,0,1]
	v_pk_fma_f32 v[92:93], v[228:229], v[254:255], v[92:93] op_sel_hi:[1,0,1]
	v_pk_fma_f32 v[94:95], v[230:231], v[254:255], v[94:95] op_sel_hi:[1,0,1]
	v_cvt_pk_f32_fp8_e32 v[224:225], v188
	v_cvt_pk_f32_fp8_sdwa v[226:227], v188 src0_sel:WORD_1
	v_cvt_pk_f32_fp8_e32 v[228:229], v189
	v_cvt_pk_f32_fp8_sdwa v[230:231], v189 src0_sel:WORD_1
	v_pk_fma_f32 v[80:81], v[224:225], v[254:255], v[80:81] op_sel:[0,1,0] op_sel_hi:[1,1,1]
	v_pk_fma_f32 v[82:83], v[226:227], v[254:255], v[82:83] op_sel:[0,1,0] op_sel_hi:[1,1,1]
	v_pk_fma_f32 v[84:85], v[228:229], v[254:255], v[84:85] op_sel:[0,1,0] op_sel_hi:[1,1,1]
	v_pk_fma_f32 v[86:87], v[230:231], v[254:255], v[86:87] op_sel:[0,1,0] op_sel_hi:[1,1,1]
	v_cvt_pk_f32_fp8_e32 v[224:225], v190
	v_cvt_pk_f32_fp8_sdwa v[226:227], v190 src0_sel:WORD_1
	v_cvt_pk_f32_fp8_e32 v[228:229], v191
	v_cvt_pk_f32_fp8_sdwa v[230:231], v191 src0_sel:WORD_1
	v_pk_fma_f32 v[88:89], v[224:225], v[254:255], v[88:89] op_sel:[0,1,0] op_sel_hi:[1,1,1]
	v_pk_fma_f32 v[90:91], v[226:227], v[254:255], v[90:91] op_sel:[0,1,0] op_sel_hi:[1,1,1]
	v_pk_fma_f32 v[92:93], v[228:229], v[254:255], v[92:93] op_sel:[0,1,0] op_sel_hi:[1,1,1]
	v_pk_fma_f32 v[94:95], v[230:231], v[254:255], v[94:95] op_sel:[0,1,0] op_sel_hi:[1,1,1]
	s_sub_i32 s90, s90, 1
	s_cmp_eq_u32 s90, 0
	s_cbranch_scc1 .LV_sw4
.LV_t5_s4:
	s_waitcnt lgkmcnt(0)
	buffer_load_dwordx4 v[176:179], v[232:233], s[60:63], 0 idxen offen
	buffer_load_dwordx4 v[180:183], v[234:235], s[60:63], 0 idxen offen
	buffer_load_dwordx4 v[184:187], v[236:237], s[60:63], 0 idxen offen
	buffer_load_dwordx4 v[188:191], v[238:239], s[60:63], 0 idxen offen
	ds_read_b32 v232, v213 offset:144
	ds_read_b32 v234, v213 offset:148
	ds_read_b32 v236, v213 offset:152
	ds_read_b32 v238, v213 offset:156
	ds_read_b128 v[248:251], v213 offset:5072
	s_waitcnt vmcnt(16)
	v_cvt_pk_f32_fp8_e32 v[224:225], v192
	v_cvt_pk_f32_fp8_sdwa v[226:227], v192 src0_sel:WORD_1
	v_cvt_pk_f32_fp8_e32 v[228:229], v193
	v_cvt_pk_f32_fp8_sdwa v[230:231], v193 src0_sel:WORD_1
	v_pk_fma_f32 v[80:81], v[224:225], v[208:209], v[80:81] op_sel_hi:[1,0,1]
	v_pk_fma_f32 v[82:83], v[226:227], v[208:209], v[82:83] op_sel_hi:[1,0,1]
	v_pk_fma_f32 v[84:85], v[228:229], v[208:209], v[84:85] op_sel_hi:[1,0,1]
	v_pk_fma_f32 v[86:87], v[230:231], v[208:209], v[86:87] op_sel_hi:[1,0,1]
	v_cvt_pk_f32_fp8_e32 v[224:225], v194
	v_cvt_pk_f32_fp8_sdwa v[226:227], v194 src0_sel:WORD_1
	v_cvt_pk_f32_fp8_e32 v[228:229], v195
	v_cvt_pk_f32_fp8_sdwa v[230:231], v195 src0_sel:WORD_1
	v_pk_fma_f32 v[88:89], v[224:225], v[208:209], v[88:89] op_sel_hi:[1,0,1]
	v_pk_fma_f32 v[90:91], v[226:227], v[208:209], v[90:91] op_sel_hi:[1,0,1]
	v_pk_fma_f32 v[92:93], v[228:229], v[208:209], v[92:93] op_sel_hi:[1,0,1]
	v_pk_fma_f32 v[94:95], v[230:231], v[208:209], v[94:95] op_sel_hi:[1,0,1]
	v_cvt_pk_f32_fp8_e32 v[224:225], v196
	v_cvt_pk_f32_fp8_sdwa v[226:227], v196 src0_sel:WORD_1
	v_cvt_pk_f32_fp8_e32 v[228:229], v197
	v_cvt_pk_f32_fp8_sdwa v[230:231], v197 src0_sel:WORD_1
	v_pk_fma_f32 v[80:81], v[224:225], v[208:209], v[80:81] op_sel:[0,1,0] op_sel_hi:[1,1,1]
	v_pk_fma_f32 v[82:83], v[226:227], v[208:209], v[82:83] op_sel:[0,1,0] op_sel_hi:[1,1,1]
	v_pk_fma_f32 v[84:85], v[228:229], v[208:209], v[84:85] op_sel:[0,1,0] op_sel_hi:[1,1,1]
	v_pk_fma_f32 v[86:87], v[230:231], v[208:209], v[86:87] op_sel:[0,1,0] op_sel_hi:[1,1,1]
	v_cvt_pk_f32_fp8_e32 v[224:225], v198
	v_cvt_pk_f32_fp8_sdwa v[226:227], v198 src0_sel:WORD_1
	v_cvt_pk_f32_fp8_e32 v[228:229], v199
	v_cvt_pk_f32_fp8_sdwa v[230:231], v199 src0_sel:WORD_1
	v_pk_fma_f32 v[88:89], v[224:225], v[208:209], v[88:89] op_sel:[0,1,0] op_sel_hi:[1,1,1]
	v_pk_fma_f32 v[90:91], v[226:227], v[208:209], v[90:91] op_sel:[0,1,0] op_sel_hi:[1,1,1]
	v_pk_fma_f32 v[92:93], v[228:229], v[208:209], v[92:93] op_sel:[0,1,0] op_sel_hi:[1,1,1]
	v_pk_fma_f32 v[94:95], v[230:231], v[208:209], v[94:95] op_sel:[0,1,0] op_sel_hi:[1,1,1]
	v_cvt_pk_f32_fp8_e32 v[224:225], v200
	v_cvt_pk_f32_fp8_sdwa v[226:227], v200 src0_sel:WORD_1
	v_cvt_pk_f32_fp8_e32 v[228:229], v201
	v_cvt_pk_f32_fp8_sdwa v[230:231], v201 src0_sel:WORD_1
	v_pk_fma_f32 v[80:81], v[224:225], v[210:211], v[80:81] op_sel_hi:[1,0,1]
	v_pk_fma_f32 v[82:83], v[226:227], v[210:211], v[82:83] op_sel_hi:[1,0,1]
	v_pk_fma_f32 v[84:85], v[228:229], v[210:211], v[84:85] op_sel_hi:[1,0,1]
	v_pk_fma_f32 v[86:87], v[230:231], v[210:211], v[86:87] op_sel_hi:[1,0,1]
	v_cvt_pk_f32_fp8_e32 v[224:225], v202
	v_cvt_pk_f32_fp8_sdwa v[226:227], v202 src0_sel:WORD_1
	v_cvt_pk_f32_fp8_e32 v[228:229], v203
	v_cvt_pk_f32_fp8_sdwa v[230:231], v203 src0_sel:WORD_1
	v_pk_fma_f32 v[88:89], v[224:225], v[210:211], v[88:89] op_sel_hi:[1,0,1]
	v_pk_fma_f32 v[90:91], v[226:227], v[210:211], v[90:91] op_sel_hi:[1,0,1]
	v_pk_fma_f32 v[92:93], v[228:229], v[210:211], v[92:93] op_sel_hi:[1,0,1]
	v_pk_fma_f32 v[94:95], v[230:231], v[210:211], v[94:95] op_sel_hi:[1,0,1]
	v_cvt_pk_f32_fp8_e32 v[224:225], v204
	v_cvt_pk_f32_fp8_sdwa v[226:227], v204 src0_sel:WORD_1
	v_cvt_pk_f32_fp8_e32 v[228:229], v205
	v_cvt_pk_f32_fp8_sdwa v[230:231], v205 src0_sel:WORD_1
	v_pk_fma_f32 v[80:81], v[224:225], v[210:211], v[80:81] op_sel:[0,1,0] op_sel_hi:[1,1,1]
	v_pk_fma_f32 v[82:83], v[226:227], v[210:211], v[82:83] op_sel:[0,1,0] op_sel_hi:[1,1,1]
	v_pk_fma_f32 v[84:85], v[228:229], v[210:211], v[84:85] op_sel:[0,1,0] op_sel_hi:[1,1,1]
	v_pk_fma_f32 v[86:87], v[230:231], v[210:211], v[86:87] op_sel:[0,1,0] op_sel_hi:[1,1,1]
	v_cvt_pk_f32_fp8_e32 v[224:225], v206
	v_cvt_pk_f32_fp8_sdwa v[226:227], v206 src0_sel:WORD_1
	v_cvt_pk_f32_fp8_e32 v[228:229], v207
	v_cvt_pk_f32_fp8_sdwa v[230:231], v207 src0_sel:WORD_1
	v_pk_fma_f32 v[88:89], v[224:225], v[210:211], v[88:89] op_sel:[0,1,0] op_sel_hi:[1,1,1]
	v_pk_fma_f32 v[90:91], v[226:227], v[210:211], v[90:91] op_sel:[0,1,0] op_sel_hi:[1,1,1]
	v_pk_fma_f32 v[92:93], v[228:229], v[210:211], v[92:93] op_sel:[0,1,0] op_sel_hi:[1,1,1]
	v_pk_fma_f32 v[94:95], v[230:231], v[210:211], v[94:95] op_sel:[0,1,0] op_sel_hi:[1,1,1]
	v_add_u32_e32 v213, 80, v213
	s_add_i32 s21, s21, 5
	s_sub_i32 s90, s90, 1
	s_cmp_eq_u32 s90, 0
	s_cbranch_scc1 .LV_sw0
	s_branch .LV_t5_s0
.LV_t6_s0:
	s_cmp_ge_u32 s21, s20
	s_cbranch_scc1 .LV_done
	s_waitcnt lgkmcnt(0)
	buffer_load_dwordx4 v[192:195], v[232:233], s[60:63], 0 idxen offen
	buffer_load_dwordx4 v[196:199], v[234:235], s[60:63], 0 idxen offen
	buffer_load_dwordx4 v[200:203], v[236:237], s[60:63], 0 idxen offen
	buffer_load_dwordx4 v[204:207], v[238:239], s[60:63], 0 idxen offen
	ds_read_b32 v232, v213 offset:80
	ds_read_b32 v234, v213 offset:84
	ds_read_b32 v236, v213 offset:88
	ds_read_b32 v238, v213 offset:92
	ds_read_b128 v[252:255], v213 offset:5008
	s_waitcnt vmcnt(16)
	v_cvt_pk_f32_fp8_e32 v[224:225], v128
	v_cvt_pk_f32_fp8_sdwa v[226:227], v128 src0_sel:WORD_1
	v_cvt_pk_f32_fp8_e32 v[228:229], v129
	v_cvt_pk_f32_fp8_sdwa v[230:231], v129 src0_sel:WORD_1
	v_pk_fma_f32 v[96:97], v[224:225], v[248:249], v[96:97] op_sel_hi:[1,0,1]
	v_pk_fma_f32 v[98:99], v[226:227], v[248:249], v[98:99] op_sel_hi:[1,0,1]
	v_pk_fma_f32 v[100:101], v[228:229], v[248:249], v[100:101] op_sel_hi:[1,0,1]
	v_pk_fma_f32 v[102:103], v[230:231], v[248:249], v[102:103] op_sel_hi:[1,0,1]
	v_cvt_pk_f32_fp8_e32 v[224:225], v130
	v_cvt_pk_f32_fp8_sdwa v[226:227], v130 src0_sel:WORD_1
	v_cvt_pk_f32_fp8_e32 v[228:229], v131
	v_cvt_pk_f32_fp8_sdwa v[230:231], v131 src0_sel:WORD_1
	v_pk_fma_f32 v[104:105], v[224:225], v[248:249], v[104:105] op_sel_hi:[1,0,1]
	v_pk_fma_f32 v[106:107], v[226:227], v[248:249], v[106:107] op_sel_hi:[1,0,1]
	v_pk_fma_f32 v[108:109], v[228:229], v[248:249], v[108:109] op_sel_hi:[1,0,1]
	v_pk_fma_f32 v[110:111], v[230:231], v[248:249], v[110:111] op_sel_hi:[1,0,1]
	v_cvt_pk_f32_fp8_e32 v[224:225], v132
	v_cvt_pk_f32_fp8_sdwa v[226:227], v132 src0_sel:WORD_1
	v_cvt_pk_f32_fp8_e32 v[228:229], v133
	v_cvt_pk_f32_fp8_sdwa v[230:231], v133 src0_sel:WORD_1
	v_pk_fma_f32 v[96:97], v[224:225], v[248:249], v[96:97] op_sel:[0,1,0] op_sel_hi:[1,1,1]
	v_pk_fma_f32 v[98:99], v[226:227], v[248:249], v[98:99] op_sel:[0,1,0] op_sel_hi:[1,1,1]
	v_pk_fma_f32 v[100:101], v[228:229], v[248:249], v[100:101] op_sel:[0,1,0] op_sel_hi:[1,1,1]
	v_pk_fma_f32 v[102:103], v[230:231], v[248:249], v[102:103] op_sel:[0,1,0] op_sel_hi:[1,1,1]
	v_cvt_pk_f32_fp8_e32 v[224:225], v134
	v_cvt_pk_f32_fp8_sdwa v[226:227], v134 src0_sel:WORD_1
	v_cvt_pk_f32_fp8_e32 v[228:229], v135
	v_cvt_pk_f32_fp8_sdwa v[230:231], v135 src0_sel:WORD_1
	v_pk_fma_f32 v[104:105], v[224:225], v[248:249], v[104:105] op_sel:[0,1,0] op_sel_hi:[1,1,1]
	v_pk_fma_f32 v[106:107], v[226:227], v[248:249], v[106:107] op_sel:[0,1,0] op_sel_hi:[1,1,1]
	v_pk_fma_f32 v[108:109], v[228:229], v[248:249], v[108:109] op_sel:[0,1,0] op_sel_hi:[1,1,1]
	v_pk_fma_f32 v[110:111], v[230:231], v[248:249], v[110:111] op_sel:[0,1,0] op_sel_hi:[1,1,1]
	v_cvt_pk_f32_fp8_e32 v[224:225], v136
	v_cvt_pk_f32_fp8_sdwa v[226:227], v136 src0_sel:WORD_1
	v_cvt_pk_f32_fp8_e32 v[228:229], v137
	v_cvt_pk_f32_fp8_sdwa v[230:231], v137 src0_sel:WORD_1
	v_pk_fma_f32 v[96:97], v[224:225], v[250:251], v[96:97] op_sel_hi:[1,0,1]
	v_pk_fma_f32 v[98:99], v[226:227], v[250:251], v[98:99] op_sel_hi:[1,0,1]
	v_pk_fma_f32 v[100:101], v[228:229], v[250:251], v[100:101] op_sel_hi:[1,0,1]
	v_pk_fma_f32 v[102:103], v[230:231], v[250:251], v[102:103] op_sel_hi:[1,0,1]
	v_cvt_pk_f32_fp8_e32 v[224:225], v138
	v_cvt_pk_f32_fp8_sdwa v[226:227], v138 src0_sel:WORD_1
	v_cvt_pk_f32_fp8_e32 v[228:229], v139
	v_cvt_pk_f32_fp8_sdwa v[230:231], v139 src0_sel:WORD_1
	v_pk_fma_f32 v[104:105], v[224:225], v[250:251], v[104:105] op_sel_hi:[1,0,1]
	v_pk_fma_f32 v[106:107], v[226:227], v[250:251], v[106:107] op_sel_hi:[1,0,1]
	v_pk_fma_f32 v[108:109], v[228:229], v[250:251], v[108:109] op_sel_hi:[1,0,1]
	v_pk_fma_f32 v[110:111], v[230:231], v[250:251], v[110:111] op_sel_hi:[1,0,1]
	v_cvt_pk_f32_fp8_e32 v[224:225], v140
	v_cvt_pk_f32_fp8_sdwa v[226:227], v140 src0_sel:WORD_1
	v_cvt_pk_f32_fp8_e32 v[228:229], v141
	v_cvt_pk_f32_fp8_sdwa v[230:231], v141 src0_sel:WORD_1
	v_pk_fma_f32 v[96:97], v[224:225], v[250:251], v[96:97] op_sel:[0,1,0] op_sel_hi:[1,1,1]
	v_pk_fma_f32 v[98:99], v[226:227], v[250:251], v[98:99] op_sel:[0,1,0] op_sel_hi:[1,1,1]
	v_pk_fma_f32 v[100:101], v[228:229], v[250:251], v[100:101] op_sel:[0,1,0] op_sel_hi:[1,1,1]
	v_pk_fma_f32 v[102:103], v[230:231], v[250:251], v[102:103] op_sel:[0,1,0] op_sel_hi:[1,1,1]
	v_cvt_pk_f32_fp8_e32 v[224:225], v142
	v_cvt_pk_f32_fp8_sdwa v[226:227], v142 src0_sel:WORD_1
	v_cvt_pk_f32_fp8_e32 v[228:229], v143
	v_cvt_pk_f32_fp8_sdwa v[230:231], v143 src0_sel:WORD_1
	v_pk_fma_f32 v[104:105], v[224:225], v[250:251], v[104:105] op_sel:[0,1,0] op_sel_hi:[1,1,1]
	v_pk_fma_f32 v[106:107], v[226:227], v[250:251], v[106:107] op_sel:[0,1,0] op_sel_hi:[1,1,1]
	v_pk_fma_f32 v[108:109], v[228:229], v[250:251], v[108:109] op_sel:[0,1,0] op_sel_hi:[1,1,1]
	v_pk_fma_f32 v[110:111], v[230:231], v[250:251], v[110:111] op_sel:[0,1,0] op_sel_hi:[1,1,1]
	s_sub_i32 s90, s90, 1
	s_cmp_eq_u32 s90, 0
	s_cbranch_scc1 .LV_sw1
.LV_t6_s1:
	s_waitcnt lgkmcnt(0)
	buffer_load_dwordx4 v[128:131], v[232:233], s[60:63], 0 idxen offen
	buffer_load_dwordx4 v[132:135], v[234:235], s[60:63], 0 idxen offen
	buffer_load_dwordx4 v[136:139], v[236:237], s[60:63], 0 idxen offen
	buffer_load_dwordx4 v[140:143], v[238:239], s[60:63], 0 idxen offen
	ds_read_b32 v232, v213 offset:96
	ds_read_b32 v234, v213 offset:100
	ds_read_b32 v236, v213 offset:104
	ds_read_b32 v238, v213 offset:108
	ds_read_b128 v[248:251], v213 offset:5024
	s_waitcnt vmcnt(16)
	v_cvt_pk_f32_fp8_e32 v[224:225], v144
	v_cvt_pk_f32_fp8_sdwa v[226:227], v144 src0_sel:WORD_1
	v_cvt_pk_f32_fp8_e32 v[228:229], v145
	v_cvt_pk_f32_fp8_sdwa v[230:231], v145 src0_sel:WORD_1
	v_pk_fma_f32 v[96:97], v[224:225], v[252:253], v[96:97] op_sel_hi:[1,0,1]
	v_pk_fma_f32 v[98:99], v[226:227], v[252:253], v[98:99] op_sel_hi:[1,0,1]
	v_pk_fma_f32 v[100:101], v[228:229], v[252:253], v[100:101] op_sel_hi:[1,0,1]
	v_pk_fma_f32 v[102:103], v[230:231], v[252:253], v[102:103] op_sel_hi:[1,0,1]
	v_cvt_pk_f32_fp8_e32 v[224:225], v146
	v_cvt_pk_f32_fp8_sdwa v[226:227], v146 src0_sel:WORD_1
	v_cvt_pk_f32_fp8_e32 v[228:229], v147
	v_cvt_pk_f32_fp8_sdwa v[230:231], v147 src0_sel:WORD_1
	v_pk_fma_f32 v[104:105], v[224:225], v[252:253], v[104:105] op_sel_hi:[1,0,1]
	v_pk_fma_f32 v[106:107], v[226:227], v[252:253], v[106:107] op_sel_hi:[1,0,1]
	v_pk_fma_f32 v[108:109], v[228:229], v[252:253], v[108:109] op_sel_hi:[1,0,1]
	v_pk_fma_f32 v[110:111], v[230:231], v[252:253], v[110:111] op_sel_hi:[1,0,1]
	v_cvt_pk_f32_fp8_e32 v[224:225], v148
	v_cvt_pk_f32_fp8_sdwa v[226:227], v148 src0_sel:WORD_1
	v_cvt_pk_f32_fp8_e32 v[228:229], v149
	v_cvt_pk_f32_fp8_sdwa v[230:231], v149 src0_sel:WORD_1
	v_pk_fma_f32 v[96:97], v[224:225], v[252:253], v[96:97] op_sel:[0,1,0] op_sel_hi:[1,1,1]
	v_pk_fma_f32 v[98:99], v[226:227], v[252:253], v[98:99] op_sel:[0,1,0] op_sel_hi:[1,1,1]
	v_pk_fma_f32 v[100:101], v[228:229], v[252:253], v[100:101] op_sel:[0,1,0] op_sel_hi:[1,1,1]
	v_pk_fma_f32 v[102:103], v[230:231], v[252:253], v[102:103] op_sel:[0,1,0] op_sel_hi:[1,1,1]
	v_cvt_pk_f32_fp8_e32 v[224:225], v150
	v_cvt_pk_f32_fp8_sdwa v[226:227], v150 src0_sel:WORD_1
	v_cvt_pk_f32_fp8_e32 v[228:229], v151
	v_cvt_pk_f32_fp8_sdwa v[230:231], v151 src0_sel:WORD_1
	v_pk_fma_f32 v[104:105], v[224:225], v[252:253], v[104:105] op_sel:[0,1,0] op_sel_hi:[1,1,1]
	v_pk_fma_f32 v[106:107], v[226:227], v[252:253], v[106:107] op_sel:[0,1,0] op_sel_hi:[1,1,1]
	v_pk_fma_f32 v[108:109], v[228:229], v[252:253], v[108:109] op_sel:[0,1,0] op_sel_hi:[1,1,1]
	v_pk_fma_f32 v[110:111], v[230:231], v[252:253], v[110:111] op_sel:[0,1,0] op_sel_hi:[1,1,1]
	v_cvt_pk_f32_fp8_e32 v[224:225], v152
	v_cvt_pk_f32_fp8_sdwa v[226:227], v152 src0_sel:WORD_1
	v_cvt_pk_f32_fp8_e32 v[228:229], v153
	v_cvt_pk_f32_fp8_sdwa v[230:231], v153 src0_sel:WORD_1
	v_pk_fma_f32 v[96:97], v[224:225], v[254:255], v[96:97] op_sel_hi:[1,0,1]
	v_pk_fma_f32 v[98:99], v[226:227], v[254:255], v[98:99] op_sel_hi:[1,0,1]
	v_pk_fma_f32 v[100:101], v[228:229], v[254:255], v[100:101] op_sel_hi:[1,0,1]
	v_pk_fma_f32 v[102:103], v[230:231], v[254:255], v[102:103] op_sel_hi:[1,0,1]
	v_cvt_pk_f32_fp8_e32 v[224:225], v154
	v_cvt_pk_f32_fp8_sdwa v[226:227], v154 src0_sel:WORD_1
	v_cvt_pk_f32_fp8_e32 v[228:229], v155
	v_cvt_pk_f32_fp8_sdwa v[230:231], v155 src0_sel:WORD_1
	v_pk_fma_f32 v[104:105], v[224:225], v[254:255], v[104:105] op_sel_hi:[1,0,1]
	v_pk_fma_f32 v[106:107], v[226:227], v[254:255], v[106:107] op_sel_hi:[1,0,1]
	v_pk_fma_f32 v[108:109], v[228:229], v[254:255], v[108:109] op_sel_hi:[1,0,1]
	v_pk_fma_f32 v[110:111], v[230:231], v[254:255], v[110:111] op_sel_hi:[1,0,1]
	v_cvt_pk_f32_fp8_e32 v[224:225], v156
	v_cvt_pk_f32_fp8_sdwa v[226:227], v156 src0_sel:WORD_1
	v_cvt_pk_f32_fp8_e32 v[228:229], v157
	v_cvt_pk_f32_fp8_sdwa v[230:231], v157 src0_sel:WORD_1
	v_pk_fma_f32 v[96:97], v[224:225], v[254:255], v[96:97] op_sel:[0,1,0] op_sel_hi:[1,1,1]
	v_pk_fma_f32 v[98:99], v[226:227], v[254:255], v[98:99] op_sel:[0,1,0] op_sel_hi:[1,1,1]
	v_pk_fma_f32 v[100:101], v[228:229], v[254:255], v[100:101] op_sel:[0,1,0] op_sel_hi:[1,1,1]
	v_pk_fma_f32 v[102:103], v[230:231], v[254:255], v[102:103] op_sel:[0,1,0] op_sel_hi:[1,1,1]
	v_cvt_pk_f32_fp8_e32 v[224:225], v158
	v_cvt_pk_f32_fp8_sdwa v[226:227], v158 src0_sel:WORD_1
	v_cvt_pk_f32_fp8_e32 v[228:229], v159
	v_cvt_pk_f32_fp8_sdwa v[230:231], v159 src0_sel:WORD_1
	v_pk_fma_f32 v[104:105], v[224:225], v[254:255], v[104:105] op_sel:[0,1,0] op_sel_hi:[1,1,1]
	v_pk_fma_f32 v[106:107], v[226:227], v[254:255], v[106:107] op_sel:[0,1,0] op_sel_hi:[1,1,1]
	v_pk_fma_f32 v[108:109], v[228:229], v[254:255], v[108:109] op_sel:[0,1,0] op_sel_hi:[1,1,1]
	v_pk_fma_f32 v[110:111], v[230:231], v[254:255], v[110:111] op_sel:[0,1,0] op_sel_hi:[1,1,1]
	s_sub_i32 s90, s90, 1
	s_cmp_eq_u32 s90, 0
	s_cbranch_scc1 .LV_sw2
.LV_t6_s2:
	s_waitcnt lgkmcnt(0)
	buffer_load_dwordx4 v[144:147], v[232:233], s[60:63], 0 idxen offen
	buffer_load_dwordx4 v[148:151], v[234:235], s[60:63], 0 idxen offen
	buffer_load_dwordx4 v[152:155], v[236:237], s[60:63], 0 idxen offen
	buffer_load_dwordx4 v[156:159], v[238:239], s[60:63], 0 idxen offen
	ds_read_b32 v232, v213 offset:112
	ds_read_b32 v234, v213 offset:116
	ds_read_b32 v236, v213 offset:120
	ds_read_b32 v238, v213 offset:124
	ds_read_b128 v[252:255], v213 offset:5040
	s_waitcnt vmcnt(16)
	v_cvt_pk_f32_fp8_e32 v[224:225], v160
	v_cvt_pk_f32_fp8_sdwa v[226:227], v160 src0_sel:WORD_1
	v_cvt_pk_f32_fp8_e32 v[228:229], v161
	v_cvt_pk_f32_fp8_sdwa v[230:231], v161 src0_sel:WORD_1
	v_pk_fma_f32 v[96:97], v[224:225], v[248:249], v[96:97] op_sel_hi:[1,0,1]
	v_pk_fma_f32 v[98:99], v[226:227], v[248:249], v[98:99] op_sel_hi:[1,0,1]
	v_pk_fma_f32 v[100:101], v[228:229], v[248:249], v[100:101] op_sel_hi:[1,0,1]
	v_pk_fma_f32 v[102:103], v[230:231], v[248:249], v[102:103] op_sel_hi:[1,0,1]
	v_cvt_pk_f32_fp8_e32 v[224:225], v162
	v_cvt_pk_f32_fp8_sdwa v[226:227], v162 src0_sel:WORD_1
	v_cvt_pk_f32_fp8_e32 v[228:229], v163
	v_cvt_pk_f32_fp8_sdwa v[230:231], v163 src0_sel:WORD_1
	v_pk_fma_f32 v[104:105], v[224:225], v[248:249], v[104:105] op_sel_hi:[1,0,1]
	v_pk_fma_f32 v[106:107], v[226:227], v[248:249], v[106:107] op_sel_hi:[1,0,1]
	v_pk_fma_f32 v[108:109], v[228:229], v[248:249], v[108:109] op_sel_hi:[1,0,1]
	v_pk_fma_f32 v[110:111], v[230:231], v[248:249], v[110:111] op_sel_hi:[1,0,1]
	v_cvt_pk_f32_fp8_e32 v[224:225], v164
	v_cvt_pk_f32_fp8_sdwa v[226:227], v164 src0_sel:WORD_1
	v_cvt_pk_f32_fp8_e32 v[228:229], v165
	v_cvt_pk_f32_fp8_sdwa v[230:231], v165 src0_sel:WORD_1
	v_pk_fma_f32 v[96:97], v[224:225], v[248:249], v[96:97] op_sel:[0,1,0] op_sel_hi:[1,1,1]
	v_pk_fma_f32 v[98:99], v[226:227], v[248:249], v[98:99] op_sel:[0,1,0] op_sel_hi:[1,1,1]
	v_pk_fma_f32 v[100:101], v[228:229], v[248:249], v[100:101] op_sel:[0,1,0] op_sel_hi:[1,1,1]
	v_pk_fma_f32 v[102:103], v[230:231], v[248:249], v[102:103] op_sel:[0,1,0] op_sel_hi:[1,1,1]
	v_cvt_pk_f32_fp8_e32 v[224:225], v166
	v_cvt_pk_f32_fp8_sdwa v[226:227], v166 src0_sel:WORD_1
	v_cvt_pk_f32_fp8_e32 v[228:229], v167
	v_cvt_pk_f32_fp8_sdwa v[230:231], v167 src0_sel:WORD_1
	v_pk_fma_f32 v[104:105], v[224:225], v[248:249], v[104:105] op_sel:[0,1,0] op_sel_hi:[1,1,1]
	v_pk_fma_f32 v[106:107], v[226:227], v[248:249], v[106:107] op_sel:[0,1,0] op_sel_hi:[1,1,1]
	v_pk_fma_f32 v[108:109], v[228:229], v[248:249], v[108:109] op_sel:[0,1,0] op_sel_hi:[1,1,1]
	v_pk_fma_f32 v[110:111], v[230:231], v[248:249], v[110:111] op_sel:[0,1,0] op_sel_hi:[1,1,1]
	v_cvt_pk_f32_fp8_e32 v[224:225], v168
	v_cvt_pk_f32_fp8_sdwa v[226:227], v168 src0_sel:WORD_1
	v_cvt_pk_f32_fp8_e32 v[228:229], v169
	v_cvt_pk_f32_fp8_sdwa v[230:231], v169 src0_sel:WORD_1
	v_pk_fma_f32 v[96:97], v[224:225], v[250:251], v[96:97] op_sel_hi:[1,0,1]
	v_pk_fma_f32 v[98:99], v[226:227], v[250:251], v[98:99] op_sel_hi:[1,0,1]
	v_pk_fma_f32 v[100:101], v[228:229], v[250:251], v[100:101] op_sel_hi:[1,0,1]
	v_pk_fma_f32 v[102:103], v[230:231], v[250:251], v[102:103] op_sel_hi:[1,0,1]
	v_cvt_pk_f32_fp8_e32 v[224:225], v170
	v_cvt_pk_f32_fp8_sdwa v[226:227], v170 src0_sel:WORD_1
	v_cvt_pk_f32_fp8_e32 v[228:229], v171
	v_cvt_pk_f32_fp8_sdwa v[230:231], v171 src0_sel:WORD_1
	v_pk_fma_f32 v[104:105], v[224:225], v[250:251], v[104:105] op_sel_hi:[1,0,1]
	v_pk_fma_f32 v[106:107], v[226:227], v[250:251], v[106:107] op_sel_hi:[1,0,1]
	v_pk_fma_f32 v[108:109], v[228:229], v[250:251], v[108:109] op_sel_hi:[1,0,1]
	v_pk_fma_f32 v[110:111], v[230:231], v[250:251], v[110:111] op_sel_hi:[1,0,1]
	v_cvt_pk_f32_fp8_e32 v[224:225], v172
	v_cvt_pk_f32_fp8_sdwa v[226:227], v172 src0_sel:WORD_1
	v_cvt_pk_f32_fp8_e32 v[228:229], v173
	v_cvt_pk_f32_fp8_sdwa v[230:231], v173 src0_sel:WORD_1
	v_pk_fma_f32 v[96:97], v[224:225], v[250:251], v[96:97] op_sel:[0,1,0] op_sel_hi:[1,1,1]
	v_pk_fma_f32 v[98:99], v[226:227], v[250:251], v[98:99] op_sel:[0,1,0] op_sel_hi:[1,1,1]
	v_pk_fma_f32 v[100:101], v[228:229], v[250:251], v[100:101] op_sel:[0,1,0] op_sel_hi:[1,1,1]
	v_pk_fma_f32 v[102:103], v[230:231], v[250:251], v[102:103] op_sel:[0,1,0] op_sel_hi:[1,1,1]
	v_cvt_pk_f32_fp8_e32 v[224:225], v174
	v_cvt_pk_f32_fp8_sdwa v[226:227], v174 src0_sel:WORD_1
	v_cvt_pk_f32_fp8_e32 v[228:229], v175
	v_cvt_pk_f32_fp8_sdwa v[230:231], v175 src0_sel:WORD_1
	v_pk_fma_f32 v[104:105], v[224:225], v[250:251], v[104:105] op_sel:[0,1,0] op_sel_hi:[1,1,1]
	v_pk_fma_f32 v[106:107], v[226:227], v[250:251], v[106:107] op_sel:[0,1,0] op_sel_hi:[1,1,1]
	v_pk_fma_f32 v[108:109], v[228:229], v[250:251], v[108:109] op_sel:[0,1,0] op_sel_hi:[1,1,1]
	v_pk_fma_f32 v[110:111], v[230:231], v[250:251], v[110:111] op_sel:[0,1,0] op_sel_hi:[1,1,1]
	s_sub_i32 s90, s90, 1
	s_cmp_eq_u32 s90, 0
	s_cbranch_scc1 .LV_sw3
.LV_t6_s3:
	s_waitcnt lgkmcnt(0)
	buffer_load_dwordx4 v[160:163], v[232:233], s[60:63], 0 idxen offen
	buffer_load_dwordx4 v[164:167], v[234:235], s[60:63], 0 idxen offen
	buffer_load_dwordx4 v[168:171], v[236:237], s[60:63], 0 idxen offen
	buffer_load_dwordx4 v[172:175], v[238:239], s[60:63], 0 idxen offen
	ds_read_b32 v232, v213 offset:128
	ds_read_b32 v234, v213 offset:132
	ds_read_b32 v236, v213 offset:136
	ds_read_b32 v238, v213 offset:140
	ds_read_b128 v[208:211], v213 offset:5056
	s_waitcnt vmcnt(16)
	v_cvt_pk_f32_fp8_e32 v[224:225], v176
	v_cvt_pk_f32_fp8_sdwa v[226:227], v176 src0_sel:WORD_1
	v_cvt_pk_f32_fp8_e32 v[228:229], v177
	v_cvt_pk_f32_fp8_sdwa v[230:231], v177 src0_sel:WORD_1
	v_pk_fma_f32 v[96:97], v[224:225], v[252:253], v[96:97] op_sel_hi:[1,0,1]
	v_pk_fma_f32 v[98:99], v[226:227], v[252:253], v[98:99] op_sel_hi:[1,0,1]
	v_pk_fma_f32 v[100:101], v[228:229], v[252:253], v[100:101] op_sel_hi:[1,0,1]
	v_pk_fma_f32 v[102:103], v[230:231], v[252:253], v[102:103] op_sel_hi:[1,0,1]
	v_cvt_pk_f32_fp8_e32 v[224:225], v178
	v_cvt_pk_f32_fp8_sdwa v[226:227], v178 src0_sel:WORD_1
	v_cvt_pk_f32_fp8_e32 v[228:229], v179
	v_cvt_pk_f32_fp8_sdwa v[230:231], v179 src0_sel:WORD_1
	v_pk_fma_f32 v[104:105], v[224:225], v[252:253], v[104:105] op_sel_hi:[1,0,1]
	v_pk_fma_f32 v[106:107], v[226:227], v[252:253], v[106:107] op_sel_hi:[1,0,1]
	v_pk_fma_f32 v[108:109], v[228:229], v[252:253], v[108:109] op_sel_hi:[1,0,1]
	v_pk_fma_f32 v[110:111], v[230:231], v[252:253], v[110:111] op_sel_hi:[1,0,1]
	v_cvt_pk_f32_fp8_e32 v[224:225], v180
	v_cvt_pk_f32_fp8_sdwa v[226:227], v180 src0_sel:WORD_1
	v_cvt_pk_f32_fp8_e32 v[228:229], v181
	v_cvt_pk_f32_fp8_sdwa v[230:231], v181 src0_sel:WORD_1
	v_pk_fma_f32 v[96:97], v[224:225], v[252:253], v[96:97] op_sel:[0,1,0] op_sel_hi:[1,1,1]
	v_pk_fma_f32 v[98:99], v[226:227], v[252:253], v[98:99] op_sel:[0,1,0] op_sel_hi:[1,1,1]
	v_pk_fma_f32 v[100:101], v[228:229], v[252:253], v[100:101] op_sel:[0,1,0] op_sel_hi:[1,1,1]
	v_pk_fma_f32 v[102:103], v[230:231], v[252:253], v[102:103] op_sel:[0,1,0] op_sel_hi:[1,1,1]
	v_cvt_pk_f32_fp8_e32 v[224:225], v182
	v_cvt_pk_f32_fp8_sdwa v[226:227], v182 src0_sel:WORD_1
	v_cvt_pk_f32_fp8_e32 v[228:229], v183
	v_cvt_pk_f32_fp8_sdwa v[230:231], v183 src0_sel:WORD_1
	v_pk_fma_f32 v[104:105], v[224:225], v[252:253], v[104:105] op_sel:[0,1,0] op_sel_hi:[1,1,1]
	v_pk_fma_f32 v[106:107], v[226:227], v[252:253], v[106:107] op_sel:[0,1,0] op_sel_hi:[1,1,1]
	v_pk_fma_f32 v[108:109], v[228:229], v[252:253], v[108:109] op_sel:[0,1,0] op_sel_hi:[1,1,1]
	v_pk_fma_f32 v[110:111], v[230:231], v[252:253], v[110:111] op_sel:[0,1,0] op_sel_hi:[1,1,1]
	v_cvt_pk_f32_fp8_e32 v[224:225], v184
	v_cvt_pk_f32_fp8_sdwa v[226:227], v184 src0_sel:WORD_1
	v_cvt_pk_f32_fp8_e32 v[228:229], v185
	v_cvt_pk_f32_fp8_sdwa v[230:231], v185 src0_sel:WORD_1
	v_pk_fma_f32 v[96:97], v[224:225], v[254:255], v[96:97] op_sel_hi:[1,0,1]
	v_pk_fma_f32 v[98:99], v[226:227], v[254:255], v[98:99] op_sel_hi:[1,0,1]
	v_pk_fma_f32 v[100:101], v[228:229], v[254:255], v[100:101] op_sel_hi:[1,0,1]
	v_pk_fma_f32 v[102:103], v[230:231], v[254:255], v[102:103] op_sel_hi:[1,0,1]
	v_cvt_pk_f32_fp8_e32 v[224:225], v186
	v_cvt_pk_f32_fp8_sdwa v[226:227], v186 src0_sel:WORD_1
	v_cvt_pk_f32_fp8_e32 v[228:229], v187
	v_cvt_pk_f32_fp8_sdwa v[230:231], v187 src0_sel:WORD_1
	v_pk_fma_f32 v[104:105], v[224:225], v[254:255], v[104:105] op_sel_hi:[1,0,1]
	v_pk_fma_f32 v[106:107], v[226:227], v[254:255], v[106:107] op_sel_hi:[1,0,1]
	v_pk_fma_f32 v[108:109], v[228:229], v[254:255], v[108:109] op_sel_hi:[1,0,1]
	v_pk_fma_f32 v[110:111], v[230:231], v[254:255], v[110:111] op_sel_hi:[1,0,1]
	v_cvt_pk_f32_fp8_e32 v[224:225], v188
	v_cvt_pk_f32_fp8_sdwa v[226:227], v188 src0_sel:WORD_1
	v_cvt_pk_f32_fp8_e32 v[228:229], v189
	v_cvt_pk_f32_fp8_sdwa v[230:231], v189 src0_sel:WORD_1
	v_pk_fma_f32 v[96:97], v[224:225], v[254:255], v[96:97] op_sel:[0,1,0] op_sel_hi:[1,1,1]
	v_pk_fma_f32 v[98:99], v[226:227], v[254:255], v[98:99] op_sel:[0,1,0] op_sel_hi:[1,1,1]
	v_pk_fma_f32 v[100:101], v[228:229], v[254:255], v[100:101] op_sel:[0,1,0] op_sel_hi:[1,1,1]
	v_pk_fma_f32 v[102:103], v[230:231], v[254:255], v[102:103] op_sel:[0,1,0] op_sel_hi:[1,1,1]
	v_cvt_pk_f32_fp8_e32 v[224:225], v190
	v_cvt_pk_f32_fp8_sdwa v[226:227], v190 src0_sel:WORD_1
	v_cvt_pk_f32_fp8_e32 v[228:229], v191
	v_cvt_pk_f32_fp8_sdwa v[230:231], v191 src0_sel:WORD_1
	v_pk_fma_f32 v[104:105], v[224:225], v[254:255], v[104:105] op_sel:[0,1,0] op_sel_hi:[1,1,1]
	v_pk_fma_f32 v[106:107], v[226:227], v[254:255], v[106:107] op_sel:[0,1,0] op_sel_hi:[1,1,1]
	v_pk_fma_f32 v[108:109], v[228:229], v[254:255], v[108:109] op_sel:[0,1,0] op_sel_hi:[1,1,1]
	v_pk_fma_f32 v[110:111], v[230:231], v[254:255], v[110:111] op_sel:[0,1,0] op_sel_hi:[1,1,1]
	s_sub_i32 s90, s90, 1
	s_cmp_eq_u32 s90, 0
	s_cbranch_scc1 .LV_sw4
.LV_t6_s4:
	s_waitcnt lgkmcnt(0)
	buffer_load_dwordx4 v[176:179], v[232:233], s[60:63], 0 idxen offen
	buffer_load_dwordx4 v[180:183], v[234:235], s[60:63], 0 idxen offen
	buffer_load_dwordx4 v[184:187], v[236:237], s[60:63], 0 idxen offen
	buffer_load_dwordx4 v[188:191], v[238:239], s[60:63], 0 idxen offen
	ds_read_b32 v232, v213 offset:144
	ds_read_b32 v234, v213 offset:148
	ds_read_b32 v236, v213 offset:152
	ds_read_b32 v238, v213 offset:156
	ds_read_b128 v[248:251], v213 offset:5072
	s_waitcnt vmcnt(16)
	v_cvt_pk_f32_fp8_e32 v[224:225], v192
	v_cvt_pk_f32_fp8_sdwa v[226:227], v192 src0_sel:WORD_1
	v_cvt_pk_f32_fp8_e32 v[228:229], v193
	v_cvt_pk_f32_fp8_sdwa v[230:231], v193 src0_sel:WORD_1
	v_pk_fma_f32 v[96:97], v[224:225], v[208:209], v[96:97] op_sel_hi:[1,0,1]
	v_pk_fma_f32 v[98:99], v[226:227], v[208:209], v[98:99] op_sel_hi:[1,0,1]
	v_pk_fma_f32 v[100:101], v[228:229], v[208:209], v[100:101] op_sel_hi:[1,0,1]
	v_pk_fma_f32 v[102:103], v[230:231], v[208:209], v[102:103] op_sel_hi:[1,0,1]
	v_cvt_pk_f32_fp8_e32 v[224:225], v194
	v_cvt_pk_f32_fp8_sdwa v[226:227], v194 src0_sel:WORD_1
	v_cvt_pk_f32_fp8_e32 v[228:229], v195
	v_cvt_pk_f32_fp8_sdwa v[230:231], v195 src0_sel:WORD_1
	v_pk_fma_f32 v[104:105], v[224:225], v[208:209], v[104:105] op_sel_hi:[1,0,1]
	v_pk_fma_f32 v[106:107], v[226:227], v[208:209], v[106:107] op_sel_hi:[1,0,1]
	v_pk_fma_f32 v[108:109], v[228:229], v[208:209], v[108:109] op_sel_hi:[1,0,1]
	v_pk_fma_f32 v[110:111], v[230:231], v[208:209], v[110:111] op_sel_hi:[1,0,1]
	v_cvt_pk_f32_fp8_e32 v[224:225], v196
	v_cvt_pk_f32_fp8_sdwa v[226:227], v196 src0_sel:WORD_1
	v_cvt_pk_f32_fp8_e32 v[228:229], v197
	v_cvt_pk_f32_fp8_sdwa v[230:231], v197 src0_sel:WORD_1
	v_pk_fma_f32 v[96:97], v[224:225], v[208:209], v[96:97] op_sel:[0,1,0] op_sel_hi:[1,1,1]
	v_pk_fma_f32 v[98:99], v[226:227], v[208:209], v[98:99] op_sel:[0,1,0] op_sel_hi:[1,1,1]
	v_pk_fma_f32 v[100:101], v[228:229], v[208:209], v[100:101] op_sel:[0,1,0] op_sel_hi:[1,1,1]
	v_pk_fma_f32 v[102:103], v[230:231], v[208:209], v[102:103] op_sel:[0,1,0] op_sel_hi:[1,1,1]
	v_cvt_pk_f32_fp8_e32 v[224:225], v198
	v_cvt_pk_f32_fp8_sdwa v[226:227], v198 src0_sel:WORD_1
	v_cvt_pk_f32_fp8_e32 v[228:229], v199
	v_cvt_pk_f32_fp8_sdwa v[230:231], v199 src0_sel:WORD_1
	v_pk_fma_f32 v[104:105], v[224:225], v[208:209], v[104:105] op_sel:[0,1,0] op_sel_hi:[1,1,1]
	v_pk_fma_f32 v[106:107], v[226:227], v[208:209], v[106:107] op_sel:[0,1,0] op_sel_hi:[1,1,1]
	v_pk_fma_f32 v[108:109], v[228:229], v[208:209], v[108:109] op_sel:[0,1,0] op_sel_hi:[1,1,1]
	v_pk_fma_f32 v[110:111], v[230:231], v[208:209], v[110:111] op_sel:[0,1,0] op_sel_hi:[1,1,1]
	v_cvt_pk_f32_fp8_e32 v[224:225], v200
	v_cvt_pk_f32_fp8_sdwa v[226:227], v200 src0_sel:WORD_1
	v_cvt_pk_f32_fp8_e32 v[228:229], v201
	v_cvt_pk_f32_fp8_sdwa v[230:231], v201 src0_sel:WORD_1
	v_pk_fma_f32 v[96:97], v[224:225], v[210:211], v[96:97] op_sel_hi:[1,0,1]
	v_pk_fma_f32 v[98:99], v[226:227], v[210:211], v[98:99] op_sel_hi:[1,0,1]
	v_pk_fma_f32 v[100:101], v[228:229], v[210:211], v[100:101] op_sel_hi:[1,0,1]
	v_pk_fma_f32 v[102:103], v[230:231], v[210:211], v[102:103] op_sel_hi:[1,0,1]
	v_cvt_pk_f32_fp8_e32 v[224:225], v202
	v_cvt_pk_f32_fp8_sdwa v[226:227], v202 src0_sel:WORD_1
	v_cvt_pk_f32_fp8_e32 v[228:229], v203
	v_cvt_pk_f32_fp8_sdwa v[230:231], v203 src0_sel:WORD_1
	v_pk_fma_f32 v[104:105], v[224:225], v[210:211], v[104:105] op_sel_hi:[1,0,1]
	v_pk_fma_f32 v[106:107], v[226:227], v[210:211], v[106:107] op_sel_hi:[1,0,1]
	v_pk_fma_f32 v[108:109], v[228:229], v[210:211], v[108:109] op_sel_hi:[1,0,1]
	v_pk_fma_f32 v[110:111], v[230:231], v[210:211], v[110:111] op_sel_hi:[1,0,1]
	v_cvt_pk_f32_fp8_e32 v[224:225], v204
	v_cvt_pk_f32_fp8_sdwa v[226:227], v204 src0_sel:WORD_1
	v_cvt_pk_f32_fp8_e32 v[228:229], v205
	v_cvt_pk_f32_fp8_sdwa v[230:231], v205 src0_sel:WORD_1
	v_pk_fma_f32 v[96:97], v[224:225], v[210:211], v[96:97] op_sel:[0,1,0] op_sel_hi:[1,1,1]
	v_pk_fma_f32 v[98:99], v[226:227], v[210:211], v[98:99] op_sel:[0,1,0] op_sel_hi:[1,1,1]
	v_pk_fma_f32 v[100:101], v[228:229], v[210:211], v[100:101] op_sel:[0,1,0] op_sel_hi:[1,1,1]
	v_pk_fma_f32 v[102:103], v[230:231], v[210:211], v[102:103] op_sel:[0,1,0] op_sel_hi:[1,1,1]
	v_cvt_pk_f32_fp8_e32 v[224:225], v206
	v_cvt_pk_f32_fp8_sdwa v[226:227], v206 src0_sel:WORD_1
	v_cvt_pk_f32_fp8_e32 v[228:229], v207
	v_cvt_pk_f32_fp8_sdwa v[230:231], v207 src0_sel:WORD_1
	v_pk_fma_f32 v[104:105], v[224:225], v[210:211], v[104:105] op_sel:[0,1,0] op_sel_hi:[1,1,1]
	v_pk_fma_f32 v[106:107], v[226:227], v[210:211], v[106:107] op_sel:[0,1,0] op_sel_hi:[1,1,1]
	v_pk_fma_f32 v[108:109], v[228:229], v[210:211], v[108:109] op_sel:[0,1,0] op_sel_hi:[1,1,1]
	v_pk_fma_f32 v[110:111], v[230:231], v[210:211], v[110:111] op_sel:[0,1,0] op_sel_hi:[1,1,1]
	v_add_u32_e32 v213, 80, v213
	s_add_i32 s21, s21, 5
	s_sub_i32 s90, s90, 1
	s_cmp_eq_u32 s90, 0
	s_cbranch_scc1 .LV_sw0
	s_branch .LV_t6_s0
.LV_t7_s0:
	s_cmp_ge_u32 s21, s20
	s_cbranch_scc1 .LV_done
	s_waitcnt lgkmcnt(0)
	buffer_load_dwordx4 v[192:195], v[232:233], s[60:63], 0 idxen offen
	buffer_load_dwordx4 v[196:199], v[234:235], s[60:63], 0 idxen offen
	buffer_load_dwordx4 v[200:203], v[236:237], s[60:63], 0 idxen offen
	buffer_load_dwordx4 v[204:207], v[238:239], s[60:63], 0 idxen offen
	ds_read_b32 v232, v213 offset:80
	ds_read_b32 v234, v213 offset:84
	ds_read_b32 v236, v213 offset:88
	ds_read_b32 v238, v213 offset:92
	ds_read_b128 v[252:255], v213 offset:5008
	s_waitcnt vmcnt(16)
	v_cvt_pk_f32_fp8_e32 v[224:225], v128
	v_cvt_pk_f32_fp8_sdwa v[226:227], v128 src0_sel:WORD_1
	v_cvt_pk_f32_fp8_e32 v[228:229], v129
	v_cvt_pk_f32_fp8_sdwa v[230:231], v129 src0_sel:WORD_1
	v_pk_fma_f32 v[112:113], v[224:225], v[248:249], v[112:113] op_sel_hi:[1,0,1]
	v_pk_fma_f32 v[114:115], v[226:227], v[248:249], v[114:115] op_sel_hi:[1,0,1]
	v_pk_fma_f32 v[116:117], v[228:229], v[248:249], v[116:117] op_sel_hi:[1,0,1]
	v_pk_fma_f32 v[118:119], v[230:231], v[248:249], v[118:119] op_sel_hi:[1,0,1]
	v_cvt_pk_f32_fp8_e32 v[224:225], v130
	v_cvt_pk_f32_fp8_sdwa v[226:227], v130 src0_sel:WORD_1
	v_cvt_pk_f32_fp8_e32 v[228:229], v131
	v_cvt_pk_f32_fp8_sdwa v[230:231], v131 src0_sel:WORD_1
	v_pk_fma_f32 v[120:121], v[224:225], v[248:249], v[120:121] op_sel_hi:[1,0,1]
	v_pk_fma_f32 v[122:123], v[226:227], v[248:249], v[122:123] op_sel_hi:[1,0,1]
	v_pk_fma_f32 v[124:125], v[228:229], v[248:249], v[124:125] op_sel_hi:[1,0,1]
	v_pk_fma_f32 v[126:127], v[230:231], v[248:249], v[126:127] op_sel_hi:[1,0,1]
	v_cvt_pk_f32_fp8_e32 v[224:225], v132
	v_cvt_pk_f32_fp8_sdwa v[226:227], v132 src0_sel:WORD_1
	v_cvt_pk_f32_fp8_e32 v[228:229], v133
	v_cvt_pk_f32_fp8_sdwa v[230:231], v133 src0_sel:WORD_1
	v_pk_fma_f32 v[112:113], v[224:225], v[248:249], v[112:113] op_sel:[0,1,0] op_sel_hi:[1,1,1]
	v_pk_fma_f32 v[114:115], v[226:227], v[248:249], v[114:115] op_sel:[0,1,0] op_sel_hi:[1,1,1]
	v_pk_fma_f32 v[116:117], v[228:229], v[248:249], v[116:117] op_sel:[0,1,0] op_sel_hi:[1,1,1]
	v_pk_fma_f32 v[118:119], v[230:231], v[248:249], v[118:119] op_sel:[0,1,0] op_sel_hi:[1,1,1]
	v_cvt_pk_f32_fp8_e32 v[224:225], v134
	v_cvt_pk_f32_fp8_sdwa v[226:227], v134 src0_sel:WORD_1
	v_cvt_pk_f32_fp8_e32 v[228:229], v135
	v_cvt_pk_f32_fp8_sdwa v[230:231], v135 src0_sel:WORD_1
	v_pk_fma_f32 v[120:121], v[224:225], v[248:249], v[120:121] op_sel:[0,1,0] op_sel_hi:[1,1,1]
	v_pk_fma_f32 v[122:123], v[226:227], v[248:249], v[122:123] op_sel:[0,1,0] op_sel_hi:[1,1,1]
	v_pk_fma_f32 v[124:125], v[228:229], v[248:249], v[124:125] op_sel:[0,1,0] op_sel_hi:[1,1,1]
	v_pk_fma_f32 v[126:127], v[230:231], v[248:249], v[126:127] op_sel:[0,1,0] op_sel_hi:[1,1,1]
	v_cvt_pk_f32_fp8_e32 v[224:225], v136
	v_cvt_pk_f32_fp8_sdwa v[226:227], v136 src0_sel:WORD_1
	v_cvt_pk_f32_fp8_e32 v[228:229], v137
	v_cvt_pk_f32_fp8_sdwa v[230:231], v137 src0_sel:WORD_1
	v_pk_fma_f32 v[112:113], v[224:225], v[250:251], v[112:113] op_sel_hi:[1,0,1]
	v_pk_fma_f32 v[114:115], v[226:227], v[250:251], v[114:115] op_sel_hi:[1,0,1]
	v_pk_fma_f32 v[116:117], v[228:229], v[250:251], v[116:117] op_sel_hi:[1,0,1]
	v_pk_fma_f32 v[118:119], v[230:231], v[250:251], v[118:119] op_sel_hi:[1,0,1]
	v_cvt_pk_f32_fp8_e32 v[224:225], v138
	v_cvt_pk_f32_fp8_sdwa v[226:227], v138 src0_sel:WORD_1
	v_cvt_pk_f32_fp8_e32 v[228:229], v139
	v_cvt_pk_f32_fp8_sdwa v[230:231], v139 src0_sel:WORD_1
	v_pk_fma_f32 v[120:121], v[224:225], v[250:251], v[120:121] op_sel_hi:[1,0,1]
	v_pk_fma_f32 v[122:123], v[226:227], v[250:251], v[122:123] op_sel_hi:[1,0,1]
	v_pk_fma_f32 v[124:125], v[228:229], v[250:251], v[124:125] op_sel_hi:[1,0,1]
	v_pk_fma_f32 v[126:127], v[230:231], v[250:251], v[126:127] op_sel_hi:[1,0,1]
	v_cvt_pk_f32_fp8_e32 v[224:225], v140
	v_cvt_pk_f32_fp8_sdwa v[226:227], v140 src0_sel:WORD_1
	v_cvt_pk_f32_fp8_e32 v[228:229], v141
	v_cvt_pk_f32_fp8_sdwa v[230:231], v141 src0_sel:WORD_1
	v_pk_fma_f32 v[112:113], v[224:225], v[250:251], v[112:113] op_sel:[0,1,0] op_sel_hi:[1,1,1]
	v_pk_fma_f32 v[114:115], v[226:227], v[250:251], v[114:115] op_sel:[0,1,0] op_sel_hi:[1,1,1]
	v_pk_fma_f32 v[116:117], v[228:229], v[250:251], v[116:117] op_sel:[0,1,0] op_sel_hi:[1,1,1]
	v_pk_fma_f32 v[118:119], v[230:231], v[250:251], v[118:119] op_sel:[0,1,0] op_sel_hi:[1,1,1]
	v_cvt_pk_f32_fp8_e32 v[224:225], v142
	v_cvt_pk_f32_fp8_sdwa v[226:227], v142 src0_sel:WORD_1
	v_cvt_pk_f32_fp8_e32 v[228:229], v143
	v_cvt_pk_f32_fp8_sdwa v[230:231], v143 src0_sel:WORD_1
	v_pk_fma_f32 v[120:121], v[224:225], v[250:251], v[120:121] op_sel:[0,1,0] op_sel_hi:[1,1,1]
	v_pk_fma_f32 v[122:123], v[226:227], v[250:251], v[122:123] op_sel:[0,1,0] op_sel_hi:[1,1,1]
	v_pk_fma_f32 v[124:125], v[228:229], v[250:251], v[124:125] op_sel:[0,1,0] op_sel_hi:[1,1,1]
	v_pk_fma_f32 v[126:127], v[230:231], v[250:251], v[126:127] op_sel:[0,1,0] op_sel_hi:[1,1,1]
	s_sub_i32 s90, s90, 1
	s_cmp_eq_u32 s90, 0
	s_cbranch_scc1 .LV_sw1
.LV_t7_s1:
	s_waitcnt lgkmcnt(0)
	buffer_load_dwordx4 v[128:131], v[232:233], s[60:63], 0 idxen offen
	buffer_load_dwordx4 v[132:135], v[234:235], s[60:63], 0 idxen offen
	buffer_load_dwordx4 v[136:139], v[236:237], s[60:63], 0 idxen offen
	buffer_load_dwordx4 v[140:143], v[238:239], s[60:63], 0 idxen offen
	ds_read_b32 v232, v213 offset:96
	ds_read_b32 v234, v213 offset:100
	ds_read_b32 v236, v213 offset:104
	ds_read_b32 v238, v213 offset:108
	ds_read_b128 v[248:251], v213 offset:5024
	s_waitcnt vmcnt(16)
	v_cvt_pk_f32_fp8_e32 v[224:225], v144
	v_cvt_pk_f32_fp8_sdwa v[226:227], v144 src0_sel:WORD_1
	v_cvt_pk_f32_fp8_e32 v[228:229], v145
	v_cvt_pk_f32_fp8_sdwa v[230:231], v145 src0_sel:WORD_1
	v_pk_fma_f32 v[112:113], v[224:225], v[252:253], v[112:113] op_sel_hi:[1,0,1]
	v_pk_fma_f32 v[114:115], v[226:227], v[252:253], v[114:115] op_sel_hi:[1,0,1]
	v_pk_fma_f32 v[116:117], v[228:229], v[252:253], v[116:117] op_sel_hi:[1,0,1]
	v_pk_fma_f32 v[118:119], v[230:231], v[252:253], v[118:119] op_sel_hi:[1,0,1]
	v_cvt_pk_f32_fp8_e32 v[224:225], v146
	v_cvt_pk_f32_fp8_sdwa v[226:227], v146 src0_sel:WORD_1
	v_cvt_pk_f32_fp8_e32 v[228:229], v147
	v_cvt_pk_f32_fp8_sdwa v[230:231], v147 src0_sel:WORD_1
	v_pk_fma_f32 v[120:121], v[224:225], v[252:253], v[120:121] op_sel_hi:[1,0,1]
	v_pk_fma_f32 v[122:123], v[226:227], v[252:253], v[122:123] op_sel_hi:[1,0,1]
	v_pk_fma_f32 v[124:125], v[228:229], v[252:253], v[124:125] op_sel_hi:[1,0,1]
	v_pk_fma_f32 v[126:127], v[230:231], v[252:253], v[126:127] op_sel_hi:[1,0,1]
	v_cvt_pk_f32_fp8_e32 v[224:225], v148
	v_cvt_pk_f32_fp8_sdwa v[226:227], v148 src0_sel:WORD_1
	v_cvt_pk_f32_fp8_e32 v[228:229], v149
	v_cvt_pk_f32_fp8_sdwa v[230:231], v149 src0_sel:WORD_1
	v_pk_fma_f32 v[112:113], v[224:225], v[252:253], v[112:113] op_sel:[0,1,0] op_sel_hi:[1,1,1]
	v_pk_fma_f32 v[114:115], v[226:227], v[252:253], v[114:115] op_sel:[0,1,0] op_sel_hi:[1,1,1]
	v_pk_fma_f32 v[116:117], v[228:229], v[252:253], v[116:117] op_sel:[0,1,0] op_sel_hi:[1,1,1]
	v_pk_fma_f32 v[118:119], v[230:231], v[252:253], v[118:119] op_sel:[0,1,0] op_sel_hi:[1,1,1]
	v_cvt_pk_f32_fp8_e32 v[224:225], v150
	v_cvt_pk_f32_fp8_sdwa v[226:227], v150 src0_sel:WORD_1
	v_cvt_pk_f32_fp8_e32 v[228:229], v151
	v_cvt_pk_f32_fp8_sdwa v[230:231], v151 src0_sel:WORD_1
	v_pk_fma_f32 v[120:121], v[224:225], v[252:253], v[120:121] op_sel:[0,1,0] op_sel_hi:[1,1,1]
	v_pk_fma_f32 v[122:123], v[226:227], v[252:253], v[122:123] op_sel:[0,1,0] op_sel_hi:[1,1,1]
	v_pk_fma_f32 v[124:125], v[228:229], v[252:253], v[124:125] op_sel:[0,1,0] op_sel_hi:[1,1,1]
	v_pk_fma_f32 v[126:127], v[230:231], v[252:253], v[126:127] op_sel:[0,1,0] op_sel_hi:[1,1,1]
	v_cvt_pk_f32_fp8_e32 v[224:225], v152
	v_cvt_pk_f32_fp8_sdwa v[226:227], v152 src0_sel:WORD_1
	v_cvt_pk_f32_fp8_e32 v[228:229], v153
	v_cvt_pk_f32_fp8_sdwa v[230:231], v153 src0_sel:WORD_1
	v_pk_fma_f32 v[112:113], v[224:225], v[254:255], v[112:113] op_sel_hi:[1,0,1]
	v_pk_fma_f32 v[114:115], v[226:227], v[254:255], v[114:115] op_sel_hi:[1,0,1]
	v_pk_fma_f32 v[116:117], v[228:229], v[254:255], v[116:117] op_sel_hi:[1,0,1]
	v_pk_fma_f32 v[118:119], v[230:231], v[254:255], v[118:119] op_sel_hi:[1,0,1]
	v_cvt_pk_f32_fp8_e32 v[224:225], v154
	v_cvt_pk_f32_fp8_sdwa v[226:227], v154 src0_sel:WORD_1
	v_cvt_pk_f32_fp8_e32 v[228:229], v155
	v_cvt_pk_f32_fp8_sdwa v[230:231], v155 src0_sel:WORD_1
	v_pk_fma_f32 v[120:121], v[224:225], v[254:255], v[120:121] op_sel_hi:[1,0,1]
	v_pk_fma_f32 v[122:123], v[226:227], v[254:255], v[122:123] op_sel_hi:[1,0,1]
	v_pk_fma_f32 v[124:125], v[228:229], v[254:255], v[124:125] op_sel_hi:[1,0,1]
	v_pk_fma_f32 v[126:127], v[230:231], v[254:255], v[126:127] op_sel_hi:[1,0,1]
	v_cvt_pk_f32_fp8_e32 v[224:225], v156
	v_cvt_pk_f32_fp8_sdwa v[226:227], v156 src0_sel:WORD_1
	v_cvt_pk_f32_fp8_e32 v[228:229], v157
	v_cvt_pk_f32_fp8_sdwa v[230:231], v157 src0_sel:WORD_1
	v_pk_fma_f32 v[112:113], v[224:225], v[254:255], v[112:113] op_sel:[0,1,0] op_sel_hi:[1,1,1]
	v_pk_fma_f32 v[114:115], v[226:227], v[254:255], v[114:115] op_sel:[0,1,0] op_sel_hi:[1,1,1]
	v_pk_fma_f32 v[116:117], v[228:229], v[254:255], v[116:117] op_sel:[0,1,0] op_sel_hi:[1,1,1]
	v_pk_fma_f32 v[118:119], v[230:231], v[254:255], v[118:119] op_sel:[0,1,0] op_sel_hi:[1,1,1]
	v_cvt_pk_f32_fp8_e32 v[224:225], v158
	v_cvt_pk_f32_fp8_sdwa v[226:227], v158 src0_sel:WORD_1
	v_cvt_pk_f32_fp8_e32 v[228:229], v159
	v_cvt_pk_f32_fp8_sdwa v[230:231], v159 src0_sel:WORD_1
	v_pk_fma_f32 v[120:121], v[224:225], v[254:255], v[120:121] op_sel:[0,1,0] op_sel_hi:[1,1,1]
	v_pk_fma_f32 v[122:123], v[226:227], v[254:255], v[122:123] op_sel:[0,1,0] op_sel_hi:[1,1,1]
	v_pk_fma_f32 v[124:125], v[228:229], v[254:255], v[124:125] op_sel:[0,1,0] op_sel_hi:[1,1,1]
	v_pk_fma_f32 v[126:127], v[230:231], v[254:255], v[126:127] op_sel:[0,1,0] op_sel_hi:[1,1,1]
	s_sub_i32 s90, s90, 1
	s_cmp_eq_u32 s90, 0
	s_cbranch_scc1 .LV_sw2
.LV_t7_s2:
	s_waitcnt lgkmcnt(0)
	buffer_load_dwordx4 v[144:147], v[232:233], s[60:63], 0 idxen offen
	buffer_load_dwordx4 v[148:151], v[234:235], s[60:63], 0 idxen offen
	buffer_load_dwordx4 v[152:155], v[236:237], s[60:63], 0 idxen offen
	buffer_load_dwordx4 v[156:159], v[238:239], s[60:63], 0 idxen offen
	ds_read_b32 v232, v213 offset:112
	ds_read_b32 v234, v213 offset:116
	ds_read_b32 v236, v213 offset:120
	ds_read_b32 v238, v213 offset:124
	ds_read_b128 v[252:255], v213 offset:5040
	s_waitcnt vmcnt(16)
	v_cvt_pk_f32_fp8_e32 v[224:225], v160
	v_cvt_pk_f32_fp8_sdwa v[226:227], v160 src0_sel:WORD_1
	v_cvt_pk_f32_fp8_e32 v[228:229], v161
	v_cvt_pk_f32_fp8_sdwa v[230:231], v161 src0_sel:WORD_1
	v_pk_fma_f32 v[112:113], v[224:225], v[248:249], v[112:113] op_sel_hi:[1,0,1]
	v_pk_fma_f32 v[114:115], v[226:227], v[248:249], v[114:115] op_sel_hi:[1,0,1]
	v_pk_fma_f32 v[116:117], v[228:229], v[248:249], v[116:117] op_sel_hi:[1,0,1]
	v_pk_fma_f32 v[118:119], v[230:231], v[248:249], v[118:119] op_sel_hi:[1,0,1]
	v_cvt_pk_f32_fp8_e32 v[224:225], v162
	v_cvt_pk_f32_fp8_sdwa v[226:227], v162 src0_sel:WORD_1
	v_cvt_pk_f32_fp8_e32 v[228:229], v163
	v_cvt_pk_f32_fp8_sdwa v[230:231], v163 src0_sel:WORD_1
	v_pk_fma_f32 v[120:121], v[224:225], v[248:249], v[120:121] op_sel_hi:[1,0,1]
	v_pk_fma_f32 v[122:123], v[226:227], v[248:249], v[122:123] op_sel_hi:[1,0,1]
	v_pk_fma_f32 v[124:125], v[228:229], v[248:249], v[124:125] op_sel_hi:[1,0,1]
	v_pk_fma_f32 v[126:127], v[230:231], v[248:249], v[126:127] op_sel_hi:[1,0,1]
	v_cvt_pk_f32_fp8_e32 v[224:225], v164
	v_cvt_pk_f32_fp8_sdwa v[226:227], v164 src0_sel:WORD_1
	v_cvt_pk_f32_fp8_e32 v[228:229], v165
	v_cvt_pk_f32_fp8_sdwa v[230:231], v165 src0_sel:WORD_1
	v_pk_fma_f32 v[112:113], v[224:225], v[248:249], v[112:113] op_sel:[0,1,0] op_sel_hi:[1,1,1]
	v_pk_fma_f32 v[114:115], v[226:227], v[248:249], v[114:115] op_sel:[0,1,0] op_sel_hi:[1,1,1]
	v_pk_fma_f32 v[116:117], v[228:229], v[248:249], v[116:117] op_sel:[0,1,0] op_sel_hi:[1,1,1]
	v_pk_fma_f32 v[118:119], v[230:231], v[248:249], v[118:119] op_sel:[0,1,0] op_sel_hi:[1,1,1]
	v_cvt_pk_f32_fp8_e32 v[224:225], v166
	v_cvt_pk_f32_fp8_sdwa v[226:227], v166 src0_sel:WORD_1
	v_cvt_pk_f32_fp8_e32 v[228:229], v167
	v_cvt_pk_f32_fp8_sdwa v[230:231], v167 src0_sel:WORD_1
	v_pk_fma_f32 v[120:121], v[224:225], v[248:249], v[120:121] op_sel:[0,1,0] op_sel_hi:[1,1,1]
	v_pk_fma_f32 v[122:123], v[226:227], v[248:249], v[122:123] op_sel:[0,1,0] op_sel_hi:[1,1,1]
	v_pk_fma_f32 v[124:125], v[228:229], v[248:249], v[124:125] op_sel:[0,1,0] op_sel_hi:[1,1,1]
	v_pk_fma_f32 v[126:127], v[230:231], v[248:249], v[126:127] op_sel:[0,1,0] op_sel_hi:[1,1,1]
	v_cvt_pk_f32_fp8_e32 v[224:225], v168
	v_cvt_pk_f32_fp8_sdwa v[226:227], v168 src0_sel:WORD_1
	v_cvt_pk_f32_fp8_e32 v[228:229], v169
	v_cvt_pk_f32_fp8_sdwa v[230:231], v169 src0_sel:WORD_1
	v_pk_fma_f32 v[112:113], v[224:225], v[250:251], v[112:113] op_sel_hi:[1,0,1]
	v_pk_fma_f32 v[114:115], v[226:227], v[250:251], v[114:115] op_sel_hi:[1,0,1]
	v_pk_fma_f32 v[116:117], v[228:229], v[250:251], v[116:117] op_sel_hi:[1,0,1]
	v_pk_fma_f32 v[118:119], v[230:231], v[250:251], v[118:119] op_sel_hi:[1,0,1]
	v_cvt_pk_f32_fp8_e32 v[224:225], v170
	v_cvt_pk_f32_fp8_sdwa v[226:227], v170 src0_sel:WORD_1
	v_cvt_pk_f32_fp8_e32 v[228:229], v171
	v_cvt_pk_f32_fp8_sdwa v[230:231], v171 src0_sel:WORD_1
	v_pk_fma_f32 v[120:121], v[224:225], v[250:251], v[120:121] op_sel_hi:[1,0,1]
	v_pk_fma_f32 v[122:123], v[226:227], v[250:251], v[122:123] op_sel_hi:[1,0,1]
	v_pk_fma_f32 v[124:125], v[228:229], v[250:251], v[124:125] op_sel_hi:[1,0,1]
	v_pk_fma_f32 v[126:127], v[230:231], v[250:251], v[126:127] op_sel_hi:[1,0,1]
	v_cvt_pk_f32_fp8_e32 v[224:225], v172
	v_cvt_pk_f32_fp8_sdwa v[226:227], v172 src0_sel:WORD_1
	v_cvt_pk_f32_fp8_e32 v[228:229], v173
	v_cvt_pk_f32_fp8_sdwa v[230:231], v173 src0_sel:WORD_1
	v_pk_fma_f32 v[112:113], v[224:225], v[250:251], v[112:113] op_sel:[0,1,0] op_sel_hi:[1,1,1]
	v_pk_fma_f32 v[114:115], v[226:227], v[250:251], v[114:115] op_sel:[0,1,0] op_sel_hi:[1,1,1]
	v_pk_fma_f32 v[116:117], v[228:229], v[250:251], v[116:117] op_sel:[0,1,0] op_sel_hi:[1,1,1]
	v_pk_fma_f32 v[118:119], v[230:231], v[250:251], v[118:119] op_sel:[0,1,0] op_sel_hi:[1,1,1]
	v_cvt_pk_f32_fp8_e32 v[224:225], v174
	v_cvt_pk_f32_fp8_sdwa v[226:227], v174 src0_sel:WORD_1
	v_cvt_pk_f32_fp8_e32 v[228:229], v175
	v_cvt_pk_f32_fp8_sdwa v[230:231], v175 src0_sel:WORD_1
	v_pk_fma_f32 v[120:121], v[224:225], v[250:251], v[120:121] op_sel:[0,1,0] op_sel_hi:[1,1,1]
	v_pk_fma_f32 v[122:123], v[226:227], v[250:251], v[122:123] op_sel:[0,1,0] op_sel_hi:[1,1,1]
	v_pk_fma_f32 v[124:125], v[228:229], v[250:251], v[124:125] op_sel:[0,1,0] op_sel_hi:[1,1,1]
	v_pk_fma_f32 v[126:127], v[230:231], v[250:251], v[126:127] op_sel:[0,1,0] op_sel_hi:[1,1,1]
	s_sub_i32 s90, s90, 1
	s_cmp_eq_u32 s90, 0
	s_cbranch_scc1 .LV_sw3
.LV_t7_s3:
	s_waitcnt lgkmcnt(0)
	buffer_load_dwordx4 v[160:163], v[232:233], s[60:63], 0 idxen offen
	buffer_load_dwordx4 v[164:167], v[234:235], s[60:63], 0 idxen offen
	buffer_load_dwordx4 v[168:171], v[236:237], s[60:63], 0 idxen offen
	buffer_load_dwordx4 v[172:175], v[238:239], s[60:63], 0 idxen offen
	ds_read_b32 v232, v213 offset:128
	ds_read_b32 v234, v213 offset:132
	ds_read_b32 v236, v213 offset:136
	ds_read_b32 v238, v213 offset:140
	ds_read_b128 v[208:211], v213 offset:5056
	s_waitcnt vmcnt(16)
	v_cvt_pk_f32_fp8_e32 v[224:225], v176
	v_cvt_pk_f32_fp8_sdwa v[226:227], v176 src0_sel:WORD_1
	v_cvt_pk_f32_fp8_e32 v[228:229], v177
	v_cvt_pk_f32_fp8_sdwa v[230:231], v177 src0_sel:WORD_1
	v_pk_fma_f32 v[112:113], v[224:225], v[252:253], v[112:113] op_sel_hi:[1,0,1]
	v_pk_fma_f32 v[114:115], v[226:227], v[252:253], v[114:115] op_sel_hi:[1,0,1]
	v_pk_fma_f32 v[116:117], v[228:229], v[252:253], v[116:117] op_sel_hi:[1,0,1]
	v_pk_fma_f32 v[118:119], v[230:231], v[252:253], v[118:119] op_sel_hi:[1,0,1]
	v_cvt_pk_f32_fp8_e32 v[224:225], v178
	v_cvt_pk_f32_fp8_sdwa v[226:227], v178 src0_sel:WORD_1
	v_cvt_pk_f32_fp8_e32 v[228:229], v179
	v_cvt_pk_f32_fp8_sdwa v[230:231], v179 src0_sel:WORD_1
	v_pk_fma_f32 v[120:121], v[224:225], v[252:253], v[120:121] op_sel_hi:[1,0,1]
	v_pk_fma_f32 v[122:123], v[226:227], v[252:253], v[122:123] op_sel_hi:[1,0,1]
	v_pk_fma_f32 v[124:125], v[228:229], v[252:253], v[124:125] op_sel_hi:[1,0,1]
	v_pk_fma_f32 v[126:127], v[230:231], v[252:253], v[126:127] op_sel_hi:[1,0,1]
	v_cvt_pk_f32_fp8_e32 v[224:225], v180
	v_cvt_pk_f32_fp8_sdwa v[226:227], v180 src0_sel:WORD_1
	v_cvt_pk_f32_fp8_e32 v[228:229], v181
	v_cvt_pk_f32_fp8_sdwa v[230:231], v181 src0_sel:WORD_1
	v_pk_fma_f32 v[112:113], v[224:225], v[252:253], v[112:113] op_sel:[0,1,0] op_sel_hi:[1,1,1]
	v_pk_fma_f32 v[114:115], v[226:227], v[252:253], v[114:115] op_sel:[0,1,0] op_sel_hi:[1,1,1]
	v_pk_fma_f32 v[116:117], v[228:229], v[252:253], v[116:117] op_sel:[0,1,0] op_sel_hi:[1,1,1]
	v_pk_fma_f32 v[118:119], v[230:231], v[252:253], v[118:119] op_sel:[0,1,0] op_sel_hi:[1,1,1]
	v_cvt_pk_f32_fp8_e32 v[224:225], v182
	v_cvt_pk_f32_fp8_sdwa v[226:227], v182 src0_sel:WORD_1
	v_cvt_pk_f32_fp8_e32 v[228:229], v183
	v_cvt_pk_f32_fp8_sdwa v[230:231], v183 src0_sel:WORD_1
	v_pk_fma_f32 v[120:121], v[224:225], v[252:253], v[120:121] op_sel:[0,1,0] op_sel_hi:[1,1,1]
	v_pk_fma_f32 v[122:123], v[226:227], v[252:253], v[122:123] op_sel:[0,1,0] op_sel_hi:[1,1,1]
	v_pk_fma_f32 v[124:125], v[228:229], v[252:253], v[124:125] op_sel:[0,1,0] op_sel_hi:[1,1,1]
	v_pk_fma_f32 v[126:127], v[230:231], v[252:253], v[126:127] op_sel:[0,1,0] op_sel_hi:[1,1,1]
	v_cvt_pk_f32_fp8_e32 v[224:225], v184
	v_cvt_pk_f32_fp8_sdwa v[226:227], v184 src0_sel:WORD_1
	v_cvt_pk_f32_fp8_e32 v[228:229], v185
	v_cvt_pk_f32_fp8_sdwa v[230:231], v185 src0_sel:WORD_1
	v_pk_fma_f32 v[112:113], v[224:225], v[254:255], v[112:113] op_sel_hi:[1,0,1]
	v_pk_fma_f32 v[114:115], v[226:227], v[254:255], v[114:115] op_sel_hi:[1,0,1]
	v_pk_fma_f32 v[116:117], v[228:229], v[254:255], v[116:117] op_sel_hi:[1,0,1]
	v_pk_fma_f32 v[118:119], v[230:231], v[254:255], v[118:119] op_sel_hi:[1,0,1]
	v_cvt_pk_f32_fp8_e32 v[224:225], v186
	v_cvt_pk_f32_fp8_sdwa v[226:227], v186 src0_sel:WORD_1
	v_cvt_pk_f32_fp8_e32 v[228:229], v187
	v_cvt_pk_f32_fp8_sdwa v[230:231], v187 src0_sel:WORD_1
	v_pk_fma_f32 v[120:121], v[224:225], v[254:255], v[120:121] op_sel_hi:[1,0,1]
	v_pk_fma_f32 v[122:123], v[226:227], v[254:255], v[122:123] op_sel_hi:[1,0,1]
	v_pk_fma_f32 v[124:125], v[228:229], v[254:255], v[124:125] op_sel_hi:[1,0,1]
	v_pk_fma_f32 v[126:127], v[230:231], v[254:255], v[126:127] op_sel_hi:[1,0,1]
	v_cvt_pk_f32_fp8_e32 v[224:225], v188
	v_cvt_pk_f32_fp8_sdwa v[226:227], v188 src0_sel:WORD_1
	v_cvt_pk_f32_fp8_e32 v[228:229], v189
	v_cvt_pk_f32_fp8_sdwa v[230:231], v189 src0_sel:WORD_1
	v_pk_fma_f32 v[112:113], v[224:225], v[254:255], v[112:113] op_sel:[0,1,0] op_sel_hi:[1,1,1]
	v_pk_fma_f32 v[114:115], v[226:227], v[254:255], v[114:115] op_sel:[0,1,0] op_sel_hi:[1,1,1]
	v_pk_fma_f32 v[116:117], v[228:229], v[254:255], v[116:117] op_sel:[0,1,0] op_sel_hi:[1,1,1]
	v_pk_fma_f32 v[118:119], v[230:231], v[254:255], v[118:119] op_sel:[0,1,0] op_sel_hi:[1,1,1]
	v_cvt_pk_f32_fp8_e32 v[224:225], v190
	v_cvt_pk_f32_fp8_sdwa v[226:227], v190 src0_sel:WORD_1
	v_cvt_pk_f32_fp8_e32 v[228:229], v191
	v_cvt_pk_f32_fp8_sdwa v[230:231], v191 src0_sel:WORD_1
	v_pk_fma_f32 v[120:121], v[224:225], v[254:255], v[120:121] op_sel:[0,1,0] op_sel_hi:[1,1,1]
	v_pk_fma_f32 v[122:123], v[226:227], v[254:255], v[122:123] op_sel:[0,1,0] op_sel_hi:[1,1,1]
	v_pk_fma_f32 v[124:125], v[228:229], v[254:255], v[124:125] op_sel:[0,1,0] op_sel_hi:[1,1,1]
	v_pk_fma_f32 v[126:127], v[230:231], v[254:255], v[126:127] op_sel:[0,1,0] op_sel_hi:[1,1,1]
	s_sub_i32 s90, s90, 1
	s_cmp_eq_u32 s90, 0
	s_cbranch_scc1 .LV_sw4
.LV_t7_s4:
	s_waitcnt lgkmcnt(0)
	buffer_load_dwordx4 v[176:179], v[232:233], s[60:63], 0 idxen offen
	buffer_load_dwordx4 v[180:183], v[234:235], s[60:63], 0 idxen offen
	buffer_load_dwordx4 v[184:187], v[236:237], s[60:63], 0 idxen offen
	buffer_load_dwordx4 v[188:191], v[238:239], s[60:63], 0 idxen offen
	ds_read_b32 v232, v213 offset:144
	ds_read_b32 v234, v213 offset:148
	ds_read_b32 v236, v213 offset:152
	ds_read_b32 v238, v213 offset:156
	ds_read_b128 v[248:251], v213 offset:5072
	s_waitcnt vmcnt(16)
	v_cvt_pk_f32_fp8_e32 v[224:225], v192
	v_cvt_pk_f32_fp8_sdwa v[226:227], v192 src0_sel:WORD_1
	v_cvt_pk_f32_fp8_e32 v[228:229], v193
	v_cvt_pk_f32_fp8_sdwa v[230:231], v193 src0_sel:WORD_1
	v_pk_fma_f32 v[112:113], v[224:225], v[208:209], v[112:113] op_sel_hi:[1,0,1]
	v_pk_fma_f32 v[114:115], v[226:227], v[208:209], v[114:115] op_sel_hi:[1,0,1]
	v_pk_fma_f32 v[116:117], v[228:229], v[208:209], v[116:117] op_sel_hi:[1,0,1]
	v_pk_fma_f32 v[118:119], v[230:231], v[208:209], v[118:119] op_sel_hi:[1,0,1]
	v_cvt_pk_f32_fp8_e32 v[224:225], v194
	v_cvt_pk_f32_fp8_sdwa v[226:227], v194 src0_sel:WORD_1
	v_cvt_pk_f32_fp8_e32 v[228:229], v195
	v_cvt_pk_f32_fp8_sdwa v[230:231], v195 src0_sel:WORD_1
	v_pk_fma_f32 v[120:121], v[224:225], v[208:209], v[120:121] op_sel_hi:[1,0,1]
	v_pk_fma_f32 v[122:123], v[226:227], v[208:209], v[122:123] op_sel_hi:[1,0,1]
	v_pk_fma_f32 v[124:125], v[228:229], v[208:209], v[124:125] op_sel_hi:[1,0,1]
	v_pk_fma_f32 v[126:127], v[230:231], v[208:209], v[126:127] op_sel_hi:[1,0,1]
	v_cvt_pk_f32_fp8_e32 v[224:225], v196
	v_cvt_pk_f32_fp8_sdwa v[226:227], v196 src0_sel:WORD_1
	v_cvt_pk_f32_fp8_e32 v[228:229], v197
	v_cvt_pk_f32_fp8_sdwa v[230:231], v197 src0_sel:WORD_1
	v_pk_fma_f32 v[112:113], v[224:225], v[208:209], v[112:113] op_sel:[0,1,0] op_sel_hi:[1,1,1]
	v_pk_fma_f32 v[114:115], v[226:227], v[208:209], v[114:115] op_sel:[0,1,0] op_sel_hi:[1,1,1]
	v_pk_fma_f32 v[116:117], v[228:229], v[208:209], v[116:117] op_sel:[0,1,0] op_sel_hi:[1,1,1]
	v_pk_fma_f32 v[118:119], v[230:231], v[208:209], v[118:119] op_sel:[0,1,0] op_sel_hi:[1,1,1]
	v_cvt_pk_f32_fp8_e32 v[224:225], v198
	v_cvt_pk_f32_fp8_sdwa v[226:227], v198 src0_sel:WORD_1
	v_cvt_pk_f32_fp8_e32 v[228:229], v199
	v_cvt_pk_f32_fp8_sdwa v[230:231], v199 src0_sel:WORD_1
	v_pk_fma_f32 v[120:121], v[224:225], v[208:209], v[120:121] op_sel:[0,1,0] op_sel_hi:[1,1,1]
	v_pk_fma_f32 v[122:123], v[226:227], v[208:209], v[122:123] op_sel:[0,1,0] op_sel_hi:[1,1,1]
	v_pk_fma_f32 v[124:125], v[228:229], v[208:209], v[124:125] op_sel:[0,1,0] op_sel_hi:[1,1,1]
	v_pk_fma_f32 v[126:127], v[230:231], v[208:209], v[126:127] op_sel:[0,1,0] op_sel_hi:[1,1,1]
	v_cvt_pk_f32_fp8_e32 v[224:225], v200
	v_cvt_pk_f32_fp8_sdwa v[226:227], v200 src0_sel:WORD_1
	v_cvt_pk_f32_fp8_e32 v[228:229], v201
	v_cvt_pk_f32_fp8_sdwa v[230:231], v201 src0_sel:WORD_1
	v_pk_fma_f32 v[112:113], v[224:225], v[210:211], v[112:113] op_sel_hi:[1,0,1]
	v_pk_fma_f32 v[114:115], v[226:227], v[210:211], v[114:115] op_sel_hi:[1,0,1]
	v_pk_fma_f32 v[116:117], v[228:229], v[210:211], v[116:117] op_sel_hi:[1,0,1]
	v_pk_fma_f32 v[118:119], v[230:231], v[210:211], v[118:119] op_sel_hi:[1,0,1]
	v_cvt_pk_f32_fp8_e32 v[224:225], v202
	v_cvt_pk_f32_fp8_sdwa v[226:227], v202 src0_sel:WORD_1
	v_cvt_pk_f32_fp8_e32 v[228:229], v203
	v_cvt_pk_f32_fp8_sdwa v[230:231], v203 src0_sel:WORD_1
	v_pk_fma_f32 v[120:121], v[224:225], v[210:211], v[120:121] op_sel_hi:[1,0,1]
	v_pk_fma_f32 v[122:123], v[226:227], v[210:211], v[122:123] op_sel_hi:[1,0,1]
	v_pk_fma_f32 v[124:125], v[228:229], v[210:211], v[124:125] op_sel_hi:[1,0,1]
	v_pk_fma_f32 v[126:127], v[230:231], v[210:211], v[126:127] op_sel_hi:[1,0,1]
	v_cvt_pk_f32_fp8_e32 v[224:225], v204
	v_cvt_pk_f32_fp8_sdwa v[226:227], v204 src0_sel:WORD_1
	v_cvt_pk_f32_fp8_e32 v[228:229], v205
	v_cvt_pk_f32_fp8_sdwa v[230:231], v205 src0_sel:WORD_1
	v_pk_fma_f32 v[112:113], v[224:225], v[210:211], v[112:113] op_sel:[0,1,0] op_sel_hi:[1,1,1]
	v_pk_fma_f32 v[114:115], v[226:227], v[210:211], v[114:115] op_sel:[0,1,0] op_sel_hi:[1,1,1]
	v_pk_fma_f32 v[116:117], v[228:229], v[210:211], v[116:117] op_sel:[0,1,0] op_sel_hi:[1,1,1]
	v_pk_fma_f32 v[118:119], v[230:231], v[210:211], v[118:119] op_sel:[0,1,0] op_sel_hi:[1,1,1]
	v_cvt_pk_f32_fp8_e32 v[224:225], v206
	v_cvt_pk_f32_fp8_sdwa v[226:227], v206 src0_sel:WORD_1
	v_cvt_pk_f32_fp8_e32 v[228:229], v207
	v_cvt_pk_f32_fp8_sdwa v[230:231], v207 src0_sel:WORD_1
	v_pk_fma_f32 v[120:121], v[224:225], v[210:211], v[120:121] op_sel:[0,1,0] op_sel_hi:[1,1,1]
	v_pk_fma_f32 v[122:123], v[226:227], v[210:211], v[122:123] op_sel:[0,1,0] op_sel_hi:[1,1,1]
	v_pk_fma_f32 v[124:125], v[228:229], v[210:211], v[124:125] op_sel:[0,1,0] op_sel_hi:[1,1,1]
	v_pk_fma_f32 v[126:127], v[230:231], v[210:211], v[126:127] op_sel:[0,1,0] op_sel_hi:[1,1,1]
	v_add_u32_e32 v213, 80, v213
	s_add_i32 s21, s21, 5
	s_sub_i32 s90, s90, 1
	s_cmp_eq_u32 s90, 0
	s_cbranch_scc1 .LV_sw0
	s_branch .LV_t7_s0
